# fused epilogue: row sum-of-squares reductions via v_permlane16/32_swap instead of ds_bpermute round trips (bit-identical adds)
# baseline (speedup 1.0000x reference)
.LBB0_150:
	s_mov_b32 s11, s63
	v_mov_b32_e32 v206, v219
	s_mov_b32 s13, s60
	v_mov_b32_e32 v231, v218
	s_mov_b64 s[8:9], s[0:1]
	v_and_b32_e32 v107, 64, v224
	v_mov_b64_e32 v[104:105], s[8:9]
	flat_load_dwordx2 v[202:203], v[104:105] offset:216
	s_nop 0
	flat_load_dwordx2 v[104:105], v[104:105] offset:32
	v_xor_b32_e32 v106, 16, v224
	v_add_u32_e32 v107, 64, v107
	v_cmp_lt_i32_e32 vcc, v106, v107
	v_mul_f32_e32 v108, v143, v143
	v_fmac_f32_e32 v108, v142, v142
	v_cndmask_b32_e32 v106, v224, v106, vcc
	v_lshlrev_b32_e32 v228, 2, v106
	v_mul_f32_e32 v106, v141, v141
	v_fmac_f32_e32 v106, v140, v140
	v_add_f32_e32 v106, v106, v108
	v_mul_f32_e32 v108, v137, v137
	v_mul_f32_e32 v109, v139, v139
	v_fmac_f32_e32 v108, v136, v136
	v_fmac_f32_e32 v109, v138, v138
	v_add_f32_e32 v108, v108, v109
	v_add_f32_e32 v106, v106, v108
	v_mul_f32_e32 v108, v133, v133
	v_mul_f32_e32 v109, v135, v135
	v_fmac_f32_e32 v108, v132, v132
	v_fmac_f32_e32 v109, v134, v134
	v_add_f32_e32 v108, v108, v109
	v_add_f32_e32 v106, v106, v108
	v_mul_f32_e32 v108, v129, v129
	v_mul_f32_e32 v109, v131, v131
	v_fmac_f32_e32 v108, v128, v128
	v_fmac_f32_e32 v109, v130, v130
	v_add_f32_e32 v108, v108, v109
	v_add_f32_e32 v106, v106, v108
	v_mov_b32_e32 v108, v106
	s_nop 1
	v_permlane16_swap_b32 v108, v106
	v_xor_b32_e32 v109, 32, v224
	v_cmp_lt_i32_e32 vcc, v109, v107
	s_lshl_b32 s75, s11, 2
	s_add_i32 s75, s75, 0x20400
	v_cndmask_b32_e32 v107, v224, v109, vcc
	v_lshlrev_b32_e32 v229, 2, v107
	s_waitcnt lgkmcnt(0)
	v_add_f32_e32 v106, v106, v108
	v_mov_b32_e32 v107, v106
	s_nop 1
	v_permlane32_swap_b32 v107, v106
	v_cmp_eq_u32_e32 vcc, 0, v206
	s_and_saveexec_b64 s[8:9], vcc
	s_cbranch_execz .LBB0_152
	s_lshl_b32 s36, s13, 10
	s_add_i32 s36, s75, s36
	v_lshl_add_u32 v108, v231, 4, s36
	s_waitcnt lgkmcnt(0)
	v_add_f32_e32 v106, v106, v107
	ds_write_b32 v108, v106
.LBB0_152:
	s_or_b64 exec, exec, s[8:9]
	v_mul_f32_e32 v106, v117, v117
	s_waitcnt lgkmcnt(0)
	v_mul_f32_e32 v107, v119, v119
	v_fmac_f32_e32 v106, v116, v116
	v_fmac_f32_e32 v107, v118, v118
	v_add_f32_e32 v106, v106, v107
	v_mul_f32_e32 v107, v113, v113
	v_mul_f32_e32 v108, v115, v115
	v_fmac_f32_e32 v107, v112, v112
	v_fmac_f32_e32 v108, v114, v114
	v_add_f32_e32 v107, v107, v108
	v_add_f32_e32 v106, v106, v107
	v_mul_f32_e32 v107, v101, v101
	v_mul_f32_e32 v108, v103, v103
	v_fmac_f32_e32 v107, v100, v100
	v_fmac_f32_e32 v108, v102, v102
	v_add_f32_e32 v107, v107, v108
	v_add_f32_e32 v106, v106, v107
	v_mul_f32_e32 v107, v97, v97
	v_mul_f32_e32 v108, v99, v99
	v_fmac_f32_e32 v107, v96, v96
	v_fmac_f32_e32 v108, v98, v98
	v_add_f32_e32 v107, v107, v108
	v_add_f32_e32 v106, v106, v107
	v_mov_b32_e32 v107, v106
	s_nop 1
	v_permlane16_swap_b32 v107, v106
	s_waitcnt lgkmcnt(0)
	v_add_f32_e32 v106, v106, v107
	v_mov_b32_e32 v107, v106
	s_nop 1
	v_permlane32_swap_b32 v107, v106
	s_and_saveexec_b64 s[8:9], vcc
	s_cbranch_execz .LBB0_154
	s_lshl_b32 s36, s13, 10
	s_add_i32 s36, s75, s36
	v_lshl_add_u32 v108, v231, 4, s36
	s_waitcnt lgkmcnt(0)
	v_add_f32_e32 v106, v106, v107
	ds_write_b32 v108, v106 offset:256
.LBB0_154:
	s_or_b64 exec, exec, s[8:9]
	v_mul_f32_e32 v106, v93, v93
	s_waitcnt lgkmcnt(0)
	v_mul_f32_e32 v107, v95, v95
	v_fmac_f32_e32 v106, v92, v92
	v_fmac_f32_e32 v107, v94, v94
	v_add_f32_e32 v106, v106, v107
	v_mul_f32_e32 v107, v89, v89
	v_mul_f32_e32 v108, v91, v91
	v_fmac_f32_e32 v107, v88, v88
	v_fmac_f32_e32 v108, v90, v90
	v_add_f32_e32 v107, v107, v108
	v_add_f32_e32 v106, v106, v107
	v_mul_f32_e32 v107, v85, v85
	v_mul_f32_e32 v108, v87, v87
	v_fmac_f32_e32 v107, v84, v84
	v_fmac_f32_e32 v108, v86, v86
	v_add_f32_e32 v107, v107, v108
	v_add_f32_e32 v106, v106, v107
	v_mul_f32_e32 v107, v81, v81
	v_mul_f32_e32 v108, v83, v83
	v_fmac_f32_e32 v107, v80, v80
	v_fmac_f32_e32 v108, v82, v82
	v_add_f32_e32 v107, v107, v108
	v_add_f32_e32 v106, v106, v107
	v_mov_b32_e32 v107, v106
	s_nop 1
	v_permlane16_swap_b32 v107, v106
	s_waitcnt lgkmcnt(0)
	v_add_f32_e32 v106, v106, v107
	v_mov_b32_e32 v107, v106
	s_nop 1
	v_permlane32_swap_b32 v107, v106
	s_and_saveexec_b64 s[8:9], vcc
	s_cbranch_execz .LBB0_156
	s_lshl_b32 s36, s13, 10
	s_add_i32 s36, s75, s36
	v_lshl_add_u32 v108, v231, 4, s36
	s_waitcnt lgkmcnt(0)
	v_add_f32_e32 v106, v106, v107
	ds_write_b32 v108, v106 offset:512
.LBB0_156:
	s_or_b64 exec, exec, s[8:9]
	v_mul_f32_e32 v106, v77, v77
	s_waitcnt lgkmcnt(0)
	v_mul_f32_e32 v107, v79, v79
	v_fmac_f32_e32 v106, v76, v76
	v_fmac_f32_e32 v107, v78, v78
	v_add_f32_e32 v106, v106, v107
	v_mul_f32_e32 v107, v73, v73
	v_mul_f32_e32 v108, v75, v75
	v_fmac_f32_e32 v107, v72, v72
	v_fmac_f32_e32 v108, v74, v74
	v_add_f32_e32 v107, v107, v108
	v_add_f32_e32 v106, v106, v107
	v_mul_f32_e32 v107, v69, v69
	v_mul_f32_e32 v108, v71, v71
	v_fmac_f32_e32 v107, v68, v68
	v_fmac_f32_e32 v108, v70, v70
	v_add_f32_e32 v107, v107, v108
	v_add_f32_e32 v106, v106, v107
	v_mul_f32_e32 v107, v65, v65
	v_mul_f32_e32 v108, v67, v67
	v_fmac_f32_e32 v107, v64, v64
	v_fmac_f32_e32 v108, v66, v66
	v_add_f32_e32 v107, v107, v108
	v_add_f32_e32 v106, v106, v107
	v_mov_b32_e32 v107, v106
	s_nop 1
	v_permlane16_swap_b32 v107, v106
	s_waitcnt lgkmcnt(0)
	v_add_f32_e32 v106, v106, v107
	v_mov_b32_e32 v107, v106
	s_nop 1
	v_permlane32_swap_b32 v107, v106
	s_and_saveexec_b64 s[8:9], vcc
	s_cbranch_execz .LBB0_158
	s_lshl_b32 s36, s13, 10
	s_add_i32 s36, s75, s36
	v_lshl_add_u32 v108, v231, 4, s36
	s_waitcnt lgkmcnt(0)
	v_add_f32_e32 v106, v106, v107
	ds_write_b32 v108, v106 offset:768
.LBB0_158:
	s_or_b64 exec, exec, s[8:9]
	v_mul_f32_e32 v106, v61, v61
	s_waitcnt lgkmcnt(0)
	v_mul_f32_e32 v107, v63, v63
	v_fmac_f32_e32 v106, v60, v60
	v_fmac_f32_e32 v107, v62, v62
	v_add_f32_e32 v106, v106, v107
	v_mul_f32_e32 v107, v57, v57
	v_mul_f32_e32 v108, v59, v59
	v_fmac_f32_e32 v107, v56, v56
	v_fmac_f32_e32 v108, v58, v58
	v_add_f32_e32 v107, v107, v108
	v_add_f32_e32 v106, v106, v107
	v_mul_f32_e32 v107, v53, v53
	v_mul_f32_e32 v108, v55, v55
	v_fmac_f32_e32 v107, v52, v52
	v_fmac_f32_e32 v108, v54, v54
	v_add_f32_e32 v107, v107, v108
	v_add_f32_e32 v106, v106, v107
	v_mul_f32_e32 v107, v49, v49
	v_mul_f32_e32 v108, v51, v51
	v_fmac_f32_e32 v107, v48, v48
	v_fmac_f32_e32 v108, v50, v50
	v_add_f32_e32 v107, v107, v108
	v_add_f32_e32 v106, v106, v107
	v_mov_b32_e32 v107, v106
	s_nop 1
	v_permlane16_swap_b32 v107, v106
	s_waitcnt lgkmcnt(0)
	v_add_f32_e32 v106, v106, v107
	v_mov_b32_e32 v107, v106
	s_nop 1
	v_permlane32_swap_b32 v107, v106
	s_and_saveexec_b64 s[8:9], vcc
	s_cbranch_execz .LBB0_160
	s_lshl_b32 s36, s13, 10
	s_add_i32 s36, s75, s36
	v_lshl_add_u32 v108, v231, 4, s36
	s_waitcnt lgkmcnt(0)
	v_add_f32_e32 v106, v106, v107
	ds_write_b32 v108, v106 offset:2048
.LBB0_160:
	s_or_b64 exec, exec, s[8:9]
	v_mul_f32_e32 v106, v45, v45
	s_waitcnt lgkmcnt(0)
	v_mul_f32_e32 v107, v47, v47
	v_fmac_f32_e32 v106, v44, v44
	v_fmac_f32_e32 v107, v46, v46
	v_add_f32_e32 v106, v106, v107
	v_mul_f32_e32 v107, v41, v41
	v_mul_f32_e32 v108, v43, v43
	v_fmac_f32_e32 v107, v40, v40
	v_fmac_f32_e32 v108, v42, v42
	v_add_f32_e32 v107, v107, v108
	v_add_f32_e32 v106, v106, v107
	v_mul_f32_e32 v107, v37, v37
	v_mul_f32_e32 v108, v39, v39
	v_fmac_f32_e32 v107, v36, v36
	v_fmac_f32_e32 v108, v38, v38
	v_add_f32_e32 v107, v107, v108
	v_add_f32_e32 v106, v106, v107
	v_mul_f32_e32 v107, v33, v33
	v_mul_f32_e32 v108, v35, v35
	v_fmac_f32_e32 v107, v32, v32
	v_fmac_f32_e32 v108, v34, v34
	v_add_f32_e32 v107, v107, v108
	v_add_f32_e32 v106, v106, v107
	v_mov_b32_e32 v107, v106
	s_nop 1
	v_permlane16_swap_b32 v107, v106
	s_waitcnt lgkmcnt(0)
	v_add_f32_e32 v106, v106, v107
	v_mov_b32_e32 v107, v106
	s_nop 1
	v_permlane32_swap_b32 v107, v106
	s_and_saveexec_b64 s[8:9], vcc
	s_cbranch_execz .LBB0_162
	s_lshl_b32 s36, s13, 10
	s_add_i32 s36, s75, s36
	v_lshl_add_u32 v108, v231, 4, s36
	s_waitcnt lgkmcnt(0)
	v_add_f32_e32 v106, v106, v107
	ds_write_b32 v108, v106 offset:2304
.LBB0_162:
	s_or_b64 exec, exec, s[8:9]
	v_mul_f32_e32 v106, v29, v29
	s_waitcnt lgkmcnt(0)
	v_mul_f32_e32 v107, v31, v31
	v_fmac_f32_e32 v106, v28, v28
	v_fmac_f32_e32 v107, v30, v30
	v_add_f32_e32 v106, v106, v107
	v_mul_f32_e32 v107, v25, v25
	v_mul_f32_e32 v108, v27, v27
	v_fmac_f32_e32 v107, v24, v24
	v_fmac_f32_e32 v108, v26, v26
	v_add_f32_e32 v107, v107, v108
	v_add_f32_e32 v106, v106, v107
	v_mul_f32_e32 v107, v21, v21
	v_mul_f32_e32 v108, v23, v23
	v_fmac_f32_e32 v107, v20, v20
	v_fmac_f32_e32 v108, v22, v22
	v_add_f32_e32 v107, v107, v108
	v_add_f32_e32 v106, v106, v107
	v_mul_f32_e32 v107, v17, v17
	v_mul_f32_e32 v108, v19, v19
	v_fmac_f32_e32 v107, v16, v16
	v_fmac_f32_e32 v108, v18, v18
	v_add_f32_e32 v107, v107, v108
	v_add_f32_e32 v106, v106, v107
	v_mov_b32_e32 v107, v106
	s_nop 1
	v_permlane16_swap_b32 v107, v106
	s_waitcnt lgkmcnt(0)
	v_add_f32_e32 v106, v106, v107
	v_mov_b32_e32 v107, v106
	s_nop 1
	v_permlane32_swap_b32 v107, v106
	s_and_saveexec_b64 s[8:9], vcc
	s_cbranch_execz .LBB0_164
	s_lshl_b32 s36, s13, 10
	s_add_i32 s36, s75, s36
	v_lshl_add_u32 v108, v231, 4, s36
	s_waitcnt lgkmcnt(0)
	v_add_f32_e32 v106, v106, v107
	ds_write_b32 v108, v106 offset:2560
.LBB0_164:
	s_or_b64 exec, exec, s[8:9]
	v_mul_f32_e32 v106, v13, v13
	s_waitcnt lgkmcnt(0)
	v_mul_f32_e32 v107, v15, v15
	v_fmac_f32_e32 v106, v12, v12
	v_fmac_f32_e32 v107, v14, v14
	v_add_f32_e32 v106, v106, v107
	v_mul_f32_e32 v107, v9, v9
	v_mul_f32_e32 v108, v11, v11
	v_fmac_f32_e32 v107, v8, v8
	v_fmac_f32_e32 v108, v10, v10
	v_add_f32_e32 v107, v107, v108
	v_add_f32_e32 v106, v106, v107
	v_mul_f32_e32 v107, v5, v5
	v_mul_f32_e32 v108, v7, v7
	v_fmac_f32_e32 v107, v4, v4
	v_fmac_f32_e32 v108, v6, v6
	v_add_f32_e32 v107, v107, v108
	v_add_f32_e32 v106, v106, v107
	v_mul_f32_e32 v107, v1, v1
	v_mul_f32_e32 v108, v3, v3
	v_fmac_f32_e32 v107, v0, v0
	v_fmac_f32_e32 v108, v2, v2
	v_add_f32_e32 v107, v107, v108
	v_add_f32_e32 v106, v106, v107
	v_mov_b32_e32 v107, v106
	s_nop 1
	v_permlane16_swap_b32 v107, v106
	s_waitcnt lgkmcnt(0)
	v_add_f32_e32 v106, v106, v107
	v_mov_b32_e32 v107, v106
	s_nop 1
	v_permlane32_swap_b32 v107, v106
	s_and_saveexec_b64 s[8:9], vcc
	s_cbranch_execz .LBB0_166
	s_lshl_b32 s36, s13, 10
	s_add_i32 s36, s75, s36
	v_lshl_add_u32 v108, v231, 4, s36
	s_waitcnt lgkmcnt(0)
	v_add_f32_e32 v106, v106, v107
	ds_write_b32 v108, v106 offset:2816

.LBB0_181:
	s_or_b64 exec, exec, s[36:37]
	v_add_u32_e32 v207, s77, v231
	s_waitcnt vmcnt(0) lgkmcnt(0)
	s_barrier
	v_lshl_add_u32 v206, v207, 2, v227
	ds_read_b32 v210, v206
	v_lshlrev_b32_e32 v212, 16, v172
	v_and_b32_e32 v213, 0xffff0000, v172
	v_lshlrev_b32_e32 v172, 16, v173
	v_and_b32_e32 v173, 0xffff0000, v173
	s_waitcnt lgkmcnt(0)
	v_pk_mul_f32 v[142:143], v[142:143], v[210:211] op_sel_hi:[1,0]
	v_pk_mul_f32 v[140:141], v[140:141], v[210:211] op_sel_hi:[1,0]
	v_lshlrev_b32_e32 v214, 16, v174
	v_and_b32_e32 v215, 0xffff0000, v174
	v_lshlrev_b32_e32 v174, 16, v175
	v_and_b32_e32 v175, 0xffff0000, v175
	v_pk_fma_f32 v[142:143], v[126:127], v[142:143], v[172:173]
	v_pk_fma_f32 v[140:141], v[124:125], v[140:141], v[212:213]
	v_pk_mul_f32 v[138:139], v[138:139], v[210:211] op_sel_hi:[1,0]
	v_pk_mul_f32 v[136:137], v[136:137], v[210:211] op_sel_hi:[1,0]
	v_pk_fma_f32 v[172:173], v[122:123], v[138:139], v[174:175]
	v_pk_fma_f32 v[138:139], v[120:121], v[136:137], v[214:215]
	v_mul_f32_e32 v136, v141, v141
	v_mul_f32_e32 v137, v143, v143
	v_fmac_f32_e32 v136, v140, v140
	v_fmac_f32_e32 v137, v142, v142
	v_add_f32_e32 v136, v136, v137
	v_mul_f32_e32 v137, v139, v139
	v_mul_f32_e32 v174, v173, v173
	v_fmac_f32_e32 v137, v138, v138
	v_fmac_f32_e32 v174, v172, v172
	v_add_f32_e32 v137, v137, v174
	v_add_f32_e32 v174, v136, v137
	v_cvt_pk_bf16_f32 v136, v140, v141
	v_cvt_pk_bf16_f32 v137, v142, v143
	v_lshlrev_b32_e32 v140, 16, v168
	v_and_b32_e32 v141, 0xffff0000, v168
	v_lshlrev_b32_e32 v142, 16, v169
	v_and_b32_e32 v143, 0xffff0000, v169
	v_pk_mul_f32 v[134:135], v[134:135], v[210:211] op_sel_hi:[1,0]
	v_pk_mul_f32 v[132:133], v[132:133], v[210:211] op_sel_hi:[1,0]
	v_lshlrev_b32_e32 v168, 16, v170
	v_and_b32_e32 v169, 0xffff0000, v170
	v_pk_fma_f32 v[134:135], v[110:111], v[134:135], v[142:143]
	v_pk_fma_f32 v[132:133], v[108:109], v[132:133], v[140:141]
	v_pk_mul_f32 v[128:129], v[128:129], v[210:211] op_sel_hi:[1,0]
	v_lshlrev_b32_e32 v170, 16, v171
	v_and_b32_e32 v171, 0xffff0000, v171
	v_pk_mul_f32 v[130:131], v[130:131], v[210:211] op_sel_hi:[1,0]
	v_pk_fma_f32 v[142:143], v[104:105], v[128:129], v[168:169]
	v_mul_f32_e32 v128, v133, v133
	v_mul_f32_e32 v129, v135, v135
	v_pk_fma_f32 v[140:141], v[106:107], v[130:131], v[170:171]
	v_fmac_f32_e32 v128, v132, v132
	v_fmac_f32_e32 v129, v134, v134
	v_add_f32_e32 v128, v128, v129
	v_mul_f32_e32 v129, v143, v143
	v_mul_f32_e32 v130, v141, v141
	v_fmac_f32_e32 v129, v142, v142
	v_fmac_f32_e32 v130, v140, v140
	v_add_f32_e32 v129, v129, v130
	v_add_f32_e32 v128, v128, v129
	v_add_f32_e32 v128, v174, v128
	v_mov_b32_e32 v129, v128
	s_nop 1
	v_permlane16_swap_b32 v129, v128
	v_add_u32_e32 v208, s76, v207
	v_ashrrev_i32_e32 v209, 31, v208
	v_lshlrev_b64 v[208:209], 11, v[208:209]
	v_lshl_add_u64 v[208:209], v[204:205], 0, v[208:209]
	s_waitcnt lgkmcnt(0)
	v_add_f32_e32 v128, v128, v129
	v_mov_b32_e32 v129, v128
	s_nop 1
	v_permlane32_swap_b32 v129, v128
	v_cvt_pk_bf16_f32 v138, v138, v139
	v_cvt_pk_bf16_f32 v139, v172, v173
	global_store_dwordx4 v[208:209], v[136:139], off
	v_cvt_pk_bf16_f32 v130, v132, v133
	v_cvt_pk_bf16_f32 v131, v134, v135
	v_cvt_pk_bf16_f32 v132, v142, v143
	v_cvt_pk_bf16_f32 v133, v140, v141
	global_store_dwordx4 v[208:209], v[130:133], off offset:256
	s_and_saveexec_b64 s[10:11], vcc
	s_cbranch_execz .LBB0_183
	s_waitcnt lgkmcnt(0)
	v_add_f32_e32 v128, v128, v129
	v_lshl_add_u32 v129, v207, 4, s75
	ds_write_b32 v129, v128
.LBB0_183:
	s_or_b64 exec, exec, s[10:11]
	v_add_u32_e32 v252, 0xa0, v207
	v_add_u32_e32 v252, s76, v252
	v_ashrrev_i32_e32 v253, 31, v252
	v_lshlrev_b64 v[252:253], 11, v[252:253]
	v_lshl_add_u64 v[252:253], v[204:205], 0, v[252:253]
	global_load_dwordx4 v[168:171], v[252:253], off
	global_load_dwordx4 v[172:175], v[252:253], off offset:256
	v_add_u32_e32 v252, 0xb0, v207
	v_add_u32_e32 v252, s76, v252
	v_ashrrev_i32_e32 v253, 31, v252
	v_lshlrev_b64 v[252:253], 11, v[252:253]
	v_lshl_add_u64 v[252:253], v[204:205], 0, v[252:253]
	global_load_dwordx4 v[208:211], v[252:253], off
	global_load_dwordx4 v[212:215], v[252:253], off offset:256
	ds_read_b32 v132, v206 offset:64
	v_lshlrev_b32_e32 v134, 16, v164
	v_and_b32_e32 v135, 0xffff0000, v164
	v_lshlrev_b32_e32 v136, 16, v165
	v_and_b32_e32 v137, 0xffff0000, v165
	s_waitcnt lgkmcnt(0)
	v_pk_mul_f32 v[118:119], v[118:119], v[132:133] op_sel_hi:[1,0]
	v_pk_mul_f32 v[116:117], v[116:117], v[132:133] op_sel_hi:[1,0]
	v_lshlrev_b32_e32 v138, 16, v166
	v_and_b32_e32 v139, 0xffff0000, v166
	v_lshlrev_b32_e32 v140, 16, v167
	v_and_b32_e32 v141, 0xffff0000, v167
	v_pk_fma_f32 v[118:119], v[126:127], v[118:119], v[136:137]
	v_pk_fma_f32 v[116:117], v[124:125], v[116:117], v[134:135]
	v_pk_mul_f32 v[114:115], v[114:115], v[132:133] op_sel_hi:[1,0]
	v_pk_mul_f32 v[112:113], v[112:113], v[132:133] op_sel_hi:[1,0]
	v_pk_fma_f32 v[134:135], v[122:123], v[114:115], v[140:141]
	v_pk_fma_f32 v[114:115], v[120:121], v[112:113], v[138:139]
	v_mul_f32_e32 v112, v117, v117
	v_mul_f32_e32 v113, v119, v119
	v_fmac_f32_e32 v112, v116, v116
	v_fmac_f32_e32 v113, v118, v118
	v_add_f32_e32 v112, v112, v113
	v_mul_f32_e32 v113, v115, v115
	v_mul_f32_e32 v129, v135, v135
	v_fmac_f32_e32 v113, v114, v114
	v_fmac_f32_e32 v129, v134, v134
	v_add_f32_e32 v113, v113, v129
	v_add_f32_e32 v129, v112, v113
	v_cvt_pk_bf16_f32 v112, v116, v117
	v_cvt_pk_bf16_f32 v113, v118, v119
	v_lshlrev_b32_e32 v116, 16, v160
	v_and_b32_e32 v117, 0xffff0000, v160
	v_lshlrev_b32_e32 v118, 16, v161
	v_and_b32_e32 v119, 0xffff0000, v161
	v_pk_mul_f32 v[102:103], v[102:103], v[132:133] op_sel_hi:[1,0]
	v_pk_mul_f32 v[100:101], v[100:101], v[132:133] op_sel_hi:[1,0]
	v_lshlrev_b32_e32 v136, 16, v162
	v_and_b32_e32 v137, 0xffff0000, v162
	v_pk_fma_f32 v[102:103], v[110:111], v[102:103], v[118:119]
	v_pk_fma_f32 v[100:101], v[108:109], v[100:101], v[116:117]
	v_pk_mul_f32 v[96:97], v[96:97], v[132:133] op_sel_hi:[1,0]
	v_lshlrev_b32_e32 v138, 16, v163
	v_and_b32_e32 v139, 0xffff0000, v163
	v_pk_mul_f32 v[98:99], v[98:99], v[132:133] op_sel_hi:[1,0]
	v_pk_fma_f32 v[118:119], v[104:105], v[96:97], v[136:137]
	v_mul_f32_e32 v96, v101, v101
	v_mul_f32_e32 v97, v103, v103
	v_pk_fma_f32 v[116:117], v[106:107], v[98:99], v[138:139]
	v_fmac_f32_e32 v96, v100, v100
	v_fmac_f32_e32 v97, v102, v102
	v_add_f32_e32 v96, v96, v97
	v_mul_f32_e32 v97, v119, v119
	v_mul_f32_e32 v98, v117, v117
	v_fmac_f32_e32 v97, v118, v118
	v_fmac_f32_e32 v98, v116, v116
	v_add_f32_e32 v97, v97, v98
	v_add_f32_e32 v96, v96, v97
	v_add_f32_e32 v96, v129, v96
	v_mov_b32_e32 v97, v96
	s_nop 1
	v_permlane16_swap_b32 v97, v96
	v_add_u32_e32 v128, 16, v207
	v_add_u32_e32 v130, s76, v128
	v_ashrrev_i32_e32 v131, 31, v130
	v_lshlrev_b64 v[130:131], 11, v[130:131]
	s_waitcnt lgkmcnt(0)
	v_add_f32_e32 v96, v96, v97
	v_mov_b32_e32 v97, v96
	s_nop 1
	v_permlane32_swap_b32 v97, v96
	v_lshl_add_u64 v[130:131], v[204:205], 0, v[130:131]
	v_cvt_pk_bf16_f32 v114, v114, v115
	v_cvt_pk_bf16_f32 v115, v134, v135
	global_store_dwordx4 v[130:131], v[112:115], off
	v_cvt_pk_bf16_f32 v98, v100, v101
	v_cvt_pk_bf16_f32 v99, v102, v103
	v_cvt_pk_bf16_f32 v100, v118, v119
	v_cvt_pk_bf16_f32 v101, v116, v117
	global_store_dwordx4 v[130:131], v[98:101], off offset:256
	s_and_saveexec_b64 s[10:11], vcc
	s_cbranch_execz .LBB0_185
	s_waitcnt lgkmcnt(0)
	v_add_f32_e32 v96, v96, v97
	v_lshl_add_u32 v97, v128, 4, s75
	ds_write_b32 v97, v96
.LBB0_185:
	s_or_b64 exec, exec, s[10:11]
	ds_read_b32 v100, v206 offset:128
	v_lshlrev_b32_e32 v102, 16, v156
	v_and_b32_e32 v103, 0xffff0000, v156
	v_lshlrev_b32_e32 v112, 16, v157
	v_and_b32_e32 v113, 0xffff0000, v157
	s_waitcnt lgkmcnt(0)
	v_pk_mul_f32 v[94:95], v[94:95], v[100:101] op_sel_hi:[1,0]
	v_pk_mul_f32 v[92:93], v[92:93], v[100:101] op_sel_hi:[1,0]
	v_lshlrev_b32_e32 v114, 16, v158
	v_and_b32_e32 v115, 0xffff0000, v158
	v_lshlrev_b32_e32 v116, 16, v159
	v_and_b32_e32 v117, 0xffff0000, v159
	v_pk_fma_f32 v[94:95], v[126:127], v[94:95], v[112:113]
	v_pk_fma_f32 v[92:93], v[124:125], v[92:93], v[102:103]
	v_pk_mul_f32 v[90:91], v[90:91], v[100:101] op_sel_hi:[1,0]
	v_pk_mul_f32 v[88:89], v[88:89], v[100:101] op_sel_hi:[1,0]
	v_pk_fma_f32 v[102:103], v[122:123], v[90:91], v[116:117]
	v_pk_fma_f32 v[90:91], v[120:121], v[88:89], v[114:115]
	v_mul_f32_e32 v88, v93, v93
	v_mul_f32_e32 v89, v95, v95
	v_fmac_f32_e32 v88, v92, v92
	v_fmac_f32_e32 v89, v94, v94
	v_add_f32_e32 v88, v88, v89
	v_mul_f32_e32 v89, v91, v91
	v_mul_f32_e32 v97, v103, v103
	v_fmac_f32_e32 v89, v90, v90
	v_fmac_f32_e32 v97, v102, v102
	v_add_f32_e32 v89, v89, v97
	v_add_f32_e32 v97, v88, v89
	v_cvt_pk_bf16_f32 v88, v92, v93
	v_cvt_pk_bf16_f32 v89, v94, v95
	v_lshlrev_b32_e32 v92, 16, v152
	v_and_b32_e32 v93, 0xffff0000, v152
	v_lshlrev_b32_e32 v94, 16, v153
	v_and_b32_e32 v95, 0xffff0000, v153
	v_pk_mul_f32 v[86:87], v[86:87], v[100:101] op_sel_hi:[1,0]
	v_pk_mul_f32 v[84:85], v[84:85], v[100:101] op_sel_hi:[1,0]
	v_lshlrev_b32_e32 v112, 16, v154
	v_and_b32_e32 v113, 0xffff0000, v154
	v_pk_fma_f32 v[86:87], v[110:111], v[86:87], v[94:95]
	v_pk_fma_f32 v[84:85], v[108:109], v[84:85], v[92:93]
	v_pk_mul_f32 v[80:81], v[80:81], v[100:101] op_sel_hi:[1,0]
	v_lshlrev_b32_e32 v114, 16, v155
	v_and_b32_e32 v115, 0xffff0000, v155
	v_pk_mul_f32 v[82:83], v[82:83], v[100:101] op_sel_hi:[1,0]
	v_pk_fma_f32 v[94:95], v[104:105], v[80:81], v[112:113]
	v_mul_f32_e32 v80, v85, v85
	v_mul_f32_e32 v81, v87, v87
	v_pk_fma_f32 v[92:93], v[106:107], v[82:83], v[114:115]
	v_fmac_f32_e32 v80, v84, v84
	v_fmac_f32_e32 v81, v86, v86
	v_add_f32_e32 v80, v80, v81
	v_mul_f32_e32 v81, v95, v95
	v_mul_f32_e32 v82, v93, v93
	v_fmac_f32_e32 v81, v94, v94
	v_fmac_f32_e32 v82, v92, v92
	v_add_f32_e32 v81, v81, v82
	v_add_f32_e32 v80, v80, v81
	v_add_f32_e32 v80, v97, v80
	v_mov_b32_e32 v81, v80
	s_nop 1
	v_permlane16_swap_b32 v81, v80
	v_add_u32_e32 v96, 32, v207
	v_add_u32_e32 v98, s76, v96
	v_ashrrev_i32_e32 v99, 31, v98
	v_lshlrev_b64 v[98:99], 11, v[98:99]
	s_waitcnt lgkmcnt(0)
	v_add_f32_e32 v80, v80, v81
	v_mov_b32_e32 v81, v80
	s_nop 1
	v_permlane32_swap_b32 v81, v80
	v_lshl_add_u64 v[98:99], v[204:205], 0, v[98:99]
	v_cvt_pk_bf16_f32 v90, v90, v91
	v_cvt_pk_bf16_f32 v91, v102, v103
	global_store_dwordx4 v[98:99], v[88:91], off
	v_cvt_pk_bf16_f32 v82, v84, v85
	v_cvt_pk_bf16_f32 v83, v86, v87
	v_cvt_pk_bf16_f32 v84, v94, v95
	v_cvt_pk_bf16_f32 v85, v92, v93
	global_store_dwordx4 v[98:99], v[82:85], off offset:256
	s_and_saveexec_b64 s[10:11], vcc
	s_cbranch_execz .LBB0_187
	s_waitcnt lgkmcnt(0)
	v_add_f32_e32 v80, v80, v81
	v_lshl_add_u32 v81, v96, 4, s75
	ds_write_b32 v81, v80
.LBB0_187:
	s_or_b64 exec, exec, s[10:11]
	ds_read_b32 v84, v206 offset:192
	v_lshlrev_b32_e32 v86, 16, v148
	v_and_b32_e32 v87, 0xffff0000, v148
	v_lshlrev_b32_e32 v88, 16, v149
	v_and_b32_e32 v89, 0xffff0000, v149
	s_waitcnt lgkmcnt(0)
	v_pk_mul_f32 v[78:79], v[78:79], v[84:85] op_sel_hi:[1,0]
	v_pk_mul_f32 v[76:77], v[76:77], v[84:85] op_sel_hi:[1,0]
	v_lshlrev_b32_e32 v90, 16, v150
	v_and_b32_e32 v91, 0xffff0000, v150
	v_lshlrev_b32_e32 v92, 16, v151
	v_and_b32_e32 v93, 0xffff0000, v151
	v_pk_fma_f32 v[78:79], v[126:127], v[78:79], v[88:89]
	v_pk_fma_f32 v[76:77], v[124:125], v[76:77], v[86:87]
	v_pk_mul_f32 v[74:75], v[74:75], v[84:85] op_sel_hi:[1,0]
	v_pk_mul_f32 v[72:73], v[72:73], v[84:85] op_sel_hi:[1,0]
	v_pk_fma_f32 v[86:87], v[122:123], v[74:75], v[92:93]
	v_pk_fma_f32 v[74:75], v[120:121], v[72:73], v[90:91]
	v_mul_f32_e32 v72, v77, v77
	v_mul_f32_e32 v73, v79, v79
	v_fmac_f32_e32 v72, v76, v76
	v_fmac_f32_e32 v73, v78, v78
	v_add_f32_e32 v72, v72, v73
	v_mul_f32_e32 v73, v75, v75
	v_mul_f32_e32 v81, v87, v87
	v_fmac_f32_e32 v73, v74, v74
	v_fmac_f32_e32 v81, v86, v86
	v_add_f32_e32 v73, v73, v81
	v_add_f32_e32 v81, v72, v73
	v_cvt_pk_bf16_f32 v72, v76, v77
	v_cvt_pk_bf16_f32 v73, v78, v79
	v_lshlrev_b32_e32 v76, 16, v144
	v_and_b32_e32 v77, 0xffff0000, v144
	v_lshlrev_b32_e32 v78, 16, v145
	v_and_b32_e32 v79, 0xffff0000, v145
	v_pk_mul_f32 v[70:71], v[70:71], v[84:85] op_sel_hi:[1,0]
	v_pk_mul_f32 v[68:69], v[68:69], v[84:85] op_sel_hi:[1,0]
	v_lshlrev_b32_e32 v88, 16, v146
	v_and_b32_e32 v89, 0xffff0000, v146
	v_pk_fma_f32 v[70:71], v[110:111], v[70:71], v[78:79]
	v_pk_fma_f32 v[68:69], v[108:109], v[68:69], v[76:77]
	v_pk_mul_f32 v[64:65], v[64:65], v[84:85] op_sel_hi:[1,0]
	v_lshlrev_b32_e32 v90, 16, v147
	v_and_b32_e32 v91, 0xffff0000, v147
	v_pk_mul_f32 v[66:67], v[66:67], v[84:85] op_sel_hi:[1,0]
	v_pk_fma_f32 v[78:79], v[104:105], v[64:65], v[88:89]
	v_mul_f32_e32 v64, v69, v69
	v_mul_f32_e32 v65, v71, v71
	v_pk_fma_f32 v[76:77], v[106:107], v[66:67], v[90:91]
	v_fmac_f32_e32 v64, v68, v68
	v_fmac_f32_e32 v65, v70, v70
	v_add_f32_e32 v64, v64, v65
	v_mul_f32_e32 v65, v79, v79
	v_mul_f32_e32 v66, v77, v77
	v_fmac_f32_e32 v65, v78, v78
	v_fmac_f32_e32 v66, v76, v76
	v_add_f32_e32 v65, v65, v66
	v_add_f32_e32 v64, v64, v65
	v_add_f32_e32 v64, v81, v64
	v_mov_b32_e32 v65, v64
	s_nop 1
	v_permlane16_swap_b32 v65, v64
	v_add_u32_e32 v80, 48, v207
	v_add_u32_e32 v82, s76, v80
	v_ashrrev_i32_e32 v83, 31, v82
	v_lshlrev_b64 v[82:83], 11, v[82:83]
	s_waitcnt lgkmcnt(0)
	v_add_f32_e32 v64, v64, v65
	v_mov_b32_e32 v65, v64
	s_nop 1
	v_permlane32_swap_b32 v65, v64
	v_lshl_add_u64 v[82:83], v[204:205], 0, v[82:83]
	v_cvt_pk_bf16_f32 v74, v74, v75
	v_cvt_pk_bf16_f32 v75, v86, v87
	global_store_dwordx4 v[82:83], v[72:75], off
	v_cvt_pk_bf16_f32 v66, v68, v69
	v_cvt_pk_bf16_f32 v67, v70, v71
	v_cvt_pk_bf16_f32 v68, v78, v79
	v_cvt_pk_bf16_f32 v69, v76, v77
	global_store_dwordx4 v[82:83], v[66:69], off offset:256
	s_and_saveexec_b64 s[10:11], vcc
	s_cbranch_execz .LBB0_189
	s_waitcnt lgkmcnt(0)
	v_add_f32_e32 v64, v64, v65
	v_lshl_add_u32 v65, v80, 4, s75
	ds_write_b32 v65, v64
.LBB0_189:
	s_or_b64 exec, exec, s[10:11]
	v_add_u32_e32 v64, 0x80, v207
	v_add_u32_e32 v66, s76, v64
	v_ashrrev_i32_e32 v67, 31, v66
	v_lshlrev_b64 v[66:67], 11, v[66:67]
	v_lshl_add_u64 v[70:71], v[204:205], 0, v[66:67]
	ds_read_b32 v72, v206 offset:512
	s_waitcnt lgkmcnt(0)
	v_pk_mul_f32 v[62:63], v[62:63], v[72:73] op_sel_hi:[1,0]
	v_pk_mul_f32 v[60:61], v[60:61], v[72:73] op_sel_hi:[1,0]
	v_pk_mul_f32 v[58:59], v[58:59], v[72:73] op_sel_hi:[1,0]
	v_pk_mul_f32 v[56:57], v[56:57], v[72:73] op_sel_hi:[1,0]
	v_pk_mul_f32 v[54:55], v[54:55], v[72:73] op_sel_hi:[1,0]
	v_pk_mul_f32 v[52:53], v[52:53], v[72:73] op_sel_hi:[1,0]
	v_pk_mul_f32 v[50:51], v[50:51], v[72:73] op_sel_hi:[1,0]
	v_pk_mul_f32 v[48:49], v[48:49], v[72:73] op_sel_hi:[1,0]
	v_lshlrev_b32_e32 v74, 16, v236
	v_and_b32_e32 v75, 0xffff0000, v236
	v_lshlrev_b32_e32 v66, 16, v237
	v_and_b32_e32 v67, 0xffff0000, v237
	v_lshlrev_b32_e32 v76, 16, v238
	v_and_b32_e32 v77, 0xffff0000, v238
	v_lshlrev_b32_e32 v68, 16, v239
	v_and_b32_e32 v69, 0xffff0000, v239
	v_pk_fma_f32 v[66:67], v[126:127], v[62:63], v[66:67]
	v_pk_fma_f32 v[74:75], v[124:125], v[60:61], v[74:75]
	v_pk_fma_f32 v[68:69], v[122:123], v[58:59], v[68:69]
	v_pk_fma_f32 v[76:77], v[120:121], v[56:57], v[76:77]
	v_cvt_pk_bf16_f32 v56, v74, v75
	v_cvt_pk_bf16_f32 v57, v66, v67
	v_mul_f32_e32 v65, v75, v75
	v_cvt_pk_bf16_f32 v58, v76, v77
	v_cvt_pk_bf16_f32 v59, v68, v69
	v_mul_f32_e32 v67, v67, v67
	v_mul_f32_e32 v72, v77, v77
	v_mul_f32_e32 v69, v69, v69
	v_fmac_f32_e32 v65, v74, v74
	v_fmac_f32_e32 v67, v66, v66
	v_fmac_f32_e32 v72, v76, v76
	v_fmac_f32_e32 v69, v68, v68
	v_add_f32_e32 v65, v65, v67
	v_add_f32_e32 v66, v72, v69
	v_add_f32_e32 v65, v65, v66
	global_store_dwordx4 v[70:71], v[56:59], off
	v_lshlrev_b32_e32 v66, 16, v240
	v_and_b32_e32 v67, 0xffff0000, v240
	v_lshlrev_b32_e32 v60, 16, v241
	v_and_b32_e32 v61, 0xffff0000, v241
	v_lshlrev_b32_e32 v68, 16, v242
	v_and_b32_e32 v69, 0xffff0000, v242
	v_lshlrev_b32_e32 v62, 16, v243
	v_and_b32_e32 v63, 0xffff0000, v243
	v_pk_fma_f32 v[54:55], v[110:111], v[54:55], v[60:61]
	v_pk_fma_f32 v[52:53], v[108:109], v[52:53], v[66:67]
	v_pk_fma_f32 v[60:61], v[106:107], v[50:51], v[62:63]
	v_pk_fma_f32 v[62:63], v[104:105], v[48:49], v[68:69]
	v_mul_f32_e32 v48, v53, v53
	v_mul_f32_e32 v49, v55, v55
	v_mul_f32_e32 v50, v63, v63
	v_mul_f32_e32 v51, v61, v61
	v_fmac_f32_e32 v48, v52, v52
	v_fmac_f32_e32 v49, v54, v54
	v_fmac_f32_e32 v50, v62, v62
	v_fmac_f32_e32 v51, v60, v60
	v_add_f32_e32 v48, v48, v49
	v_add_f32_e32 v49, v50, v51
	v_add_f32_e32 v48, v48, v49
	v_add_f32_e32 v48, v65, v48
	v_mov_b32_e32 v49, v48
	s_nop 1
	v_permlane16_swap_b32 v49, v48
	v_cvt_pk_bf16_f32 v50, v52, v53
	v_cvt_pk_bf16_f32 v51, v54, v55
	v_cvt_pk_bf16_f32 v52, v62, v63
	v_cvt_pk_bf16_f32 v53, v60, v61
	s_waitcnt lgkmcnt(0)
	v_add_f32_e32 v48, v48, v49
	v_mov_b32_e32 v49, v48
	s_nop 1
	v_permlane32_swap_b32 v49, v48
	global_store_dwordx4 v[70:71], v[50:53], off offset:256
	s_and_saveexec_b64 s[10:11], vcc
	s_cbranch_execz .LBB0_191
	s_waitcnt lgkmcnt(0)
	v_add_f32_e32 v48, v48, v49
	v_lshl_add_u32 v49, v64, 4, s75
	ds_write_b32 v49, v48
.LBB0_191:
	s_or_b64 exec, exec, s[10:11]
	v_add_u32_e32 v48, 0x90, v207
	v_add_u32_e32 v50, s76, v48
	v_ashrrev_i32_e32 v51, 31, v50
	v_lshlrev_b64 v[50:51], 11, v[50:51]
	v_lshl_add_u64 v[54:55], v[204:205], 0, v[50:51]
	ds_read_b32 v56, v206 offset:576
	s_waitcnt lgkmcnt(0)
	v_pk_mul_f32 v[46:47], v[46:47], v[56:57] op_sel_hi:[1,0]
	v_pk_mul_f32 v[44:45], v[44:45], v[56:57] op_sel_hi:[1,0]
	v_pk_mul_f32 v[42:43], v[42:43], v[56:57] op_sel_hi:[1,0]
	v_pk_mul_f32 v[40:41], v[40:41], v[56:57] op_sel_hi:[1,0]
	v_pk_mul_f32 v[38:39], v[38:39], v[56:57] op_sel_hi:[1,0]
	v_pk_mul_f32 v[36:37], v[36:37], v[56:57] op_sel_hi:[1,0]
	v_pk_mul_f32 v[34:35], v[34:35], v[56:57] op_sel_hi:[1,0]
	v_pk_mul_f32 v[32:33], v[32:33], v[56:57] op_sel_hi:[1,0]
	v_lshlrev_b32_e32 v58, 16, v244
	v_and_b32_e32 v59, 0xffff0000, v244
	v_lshlrev_b32_e32 v50, 16, v245
	v_and_b32_e32 v51, 0xffff0000, v245
	v_lshlrev_b32_e32 v60, 16, v246
	v_and_b32_e32 v61, 0xffff0000, v246
	v_lshlrev_b32_e32 v52, 16, v247
	v_and_b32_e32 v53, 0xffff0000, v247
	v_pk_fma_f32 v[50:51], v[126:127], v[46:47], v[50:51]
	v_pk_fma_f32 v[58:59], v[124:125], v[44:45], v[58:59]
	v_pk_fma_f32 v[52:53], v[122:123], v[42:43], v[52:53]
	v_pk_fma_f32 v[60:61], v[120:121], v[40:41], v[60:61]
	v_cvt_pk_bf16_f32 v40, v58, v59
	v_cvt_pk_bf16_f32 v41, v50, v51
	v_mul_f32_e32 v49, v59, v59
	v_cvt_pk_bf16_f32 v42, v60, v61
	v_cvt_pk_bf16_f32 v43, v52, v53
	v_mul_f32_e32 v51, v51, v51
	v_mul_f32_e32 v56, v61, v61
	v_mul_f32_e32 v53, v53, v53
	v_fmac_f32_e32 v49, v58, v58
	v_fmac_f32_e32 v51, v50, v50
	v_fmac_f32_e32 v56, v60, v60
	v_fmac_f32_e32 v53, v52, v52
	v_add_f32_e32 v49, v49, v51
	v_add_f32_e32 v50, v56, v53
	v_add_f32_e32 v49, v49, v50
	global_store_dwordx4 v[54:55], v[40:43], off
	v_lshlrev_b32_e32 v50, 16, v248
	v_and_b32_e32 v51, 0xffff0000, v248
	v_lshlrev_b32_e32 v44, 16, v249
	v_and_b32_e32 v45, 0xffff0000, v249
	v_lshlrev_b32_e32 v52, 16, v250
	v_and_b32_e32 v53, 0xffff0000, v250
	v_lshlrev_b32_e32 v46, 16, v251
	v_and_b32_e32 v47, 0xffff0000, v251
	v_pk_fma_f32 v[38:39], v[110:111], v[38:39], v[44:45]
	v_pk_fma_f32 v[36:37], v[108:109], v[36:37], v[50:51]
	v_pk_fma_f32 v[44:45], v[106:107], v[34:35], v[46:47]
	v_pk_fma_f32 v[46:47], v[104:105], v[32:33], v[52:53]
	v_mul_f32_e32 v32, v37, v37
	v_mul_f32_e32 v33, v39, v39
	v_mul_f32_e32 v34, v47, v47
	v_mul_f32_e32 v35, v45, v45
	v_fmac_f32_e32 v32, v36, v36
	v_fmac_f32_e32 v33, v38, v38
	v_fmac_f32_e32 v34, v46, v46
	v_fmac_f32_e32 v35, v44, v44
	v_add_f32_e32 v32, v32, v33
	v_add_f32_e32 v33, v34, v35
	v_add_f32_e32 v32, v32, v33
	v_add_f32_e32 v32, v49, v32
	v_mov_b32_e32 v33, v32
	s_nop 1
	v_permlane16_swap_b32 v33, v32
	v_cvt_pk_bf16_f32 v34, v36, v37
	v_cvt_pk_bf16_f32 v35, v38, v39
	v_cvt_pk_bf16_f32 v36, v46, v47
	v_cvt_pk_bf16_f32 v37, v44, v45
	s_waitcnt lgkmcnt(0)
	v_add_f32_e32 v32, v32, v33
	v_mov_b32_e32 v33, v32
	s_nop 1
	v_permlane32_swap_b32 v33, v32
	global_store_dwordx4 v[54:55], v[34:37], off offset:256
	s_and_saveexec_b64 s[10:11], vcc
	s_cbranch_execz .LBB0_193
	s_waitcnt lgkmcnt(0)
	v_add_f32_e32 v32, v32, v33
	v_lshl_add_u32 v33, v48, 4, s75
	ds_write_b32 v33, v32
.LBB0_193:
	s_or_b64 exec, exec, s[10:11]
	v_add_u32_e32 v32, 0xa0, v207
	v_add_u32_e32 v34, s76, v32
	v_ashrrev_i32_e32 v35, 31, v34
	v_lshlrev_b64 v[34:35], 11, v[34:35]
	v_lshl_add_u64 v[38:39], v[204:205], 0, v[34:35]
	ds_read_b32 v40, v206 offset:640
	s_waitcnt lgkmcnt(0)
	v_pk_mul_f32 v[30:31], v[30:31], v[40:41] op_sel_hi:[1,0]
	v_pk_mul_f32 v[28:29], v[28:29], v[40:41] op_sel_hi:[1,0]
	v_pk_mul_f32 v[26:27], v[26:27], v[40:41] op_sel_hi:[1,0]
	v_pk_mul_f32 v[24:25], v[24:25], v[40:41] op_sel_hi:[1,0]
	v_pk_mul_f32 v[22:23], v[22:23], v[40:41] op_sel_hi:[1,0]
	v_pk_mul_f32 v[20:21], v[20:21], v[40:41] op_sel_hi:[1,0]
	v_pk_mul_f32 v[18:19], v[18:19], v[40:41] op_sel_hi:[1,0]
	v_pk_mul_f32 v[16:17], v[16:17], v[40:41] op_sel_hi:[1,0]
	s_waitcnt vmcnt(13)
	v_lshlrev_b32_e32 v42, 16, v168
	v_and_b32_e32 v43, 0xffff0000, v168
	v_lshlrev_b32_e32 v34, 16, v169
	v_and_b32_e32 v35, 0xffff0000, v169
	v_lshlrev_b32_e32 v44, 16, v170
	v_and_b32_e32 v45, 0xffff0000, v170
	v_lshlrev_b32_e32 v36, 16, v171
	v_and_b32_e32 v37, 0xffff0000, v171
	v_pk_fma_f32 v[34:35], v[126:127], v[30:31], v[34:35]
	v_pk_fma_f32 v[42:43], v[124:125], v[28:29], v[42:43]
	v_pk_fma_f32 v[36:37], v[122:123], v[26:27], v[36:37]
	v_pk_fma_f32 v[44:45], v[120:121], v[24:25], v[44:45]
	v_cvt_pk_bf16_f32 v24, v42, v43
	v_cvt_pk_bf16_f32 v25, v34, v35
	v_mul_f32_e32 v33, v43, v43
	v_cvt_pk_bf16_f32 v26, v44, v45
	v_cvt_pk_bf16_f32 v27, v36, v37
	v_mul_f32_e32 v35, v35, v35
	v_mul_f32_e32 v40, v45, v45
	v_mul_f32_e32 v37, v37, v37
	v_fmac_f32_e32 v33, v42, v42
	v_fmac_f32_e32 v35, v34, v34
	v_fmac_f32_e32 v40, v44, v44
	v_fmac_f32_e32 v37, v36, v36
	v_add_f32_e32 v33, v33, v35
	v_add_f32_e32 v34, v40, v37
	v_add_f32_e32 v33, v33, v34
	global_store_dwordx4 v[38:39], v[24:27], off
	s_waitcnt vmcnt(13)
	v_lshlrev_b32_e32 v34, 16, v172
	v_and_b32_e32 v35, 0xffff0000, v172
	v_lshlrev_b32_e32 v28, 16, v173
	v_and_b32_e32 v29, 0xffff0000, v173
	v_lshlrev_b32_e32 v36, 16, v174
	v_and_b32_e32 v37, 0xffff0000, v174
	v_lshlrev_b32_e32 v30, 16, v175
	v_and_b32_e32 v31, 0xffff0000, v175
	v_pk_fma_f32 v[22:23], v[110:111], v[22:23], v[28:29]
	v_pk_fma_f32 v[20:21], v[108:109], v[20:21], v[34:35]
	v_pk_fma_f32 v[28:29], v[106:107], v[18:19], v[30:31]
	v_pk_fma_f32 v[30:31], v[104:105], v[16:17], v[36:37]
	v_mul_f32_e32 v16, v21, v21
	v_mul_f32_e32 v17, v23, v23
	v_mul_f32_e32 v18, v31, v31
	v_mul_f32_e32 v19, v29, v29
	v_fmac_f32_e32 v16, v20, v20
	v_fmac_f32_e32 v17, v22, v22
	v_fmac_f32_e32 v18, v30, v30
	v_fmac_f32_e32 v19, v28, v28
	v_add_f32_e32 v16, v16, v17
	v_add_f32_e32 v17, v18, v19
	v_add_f32_e32 v16, v16, v17
	v_add_f32_e32 v16, v33, v16
	v_mov_b32_e32 v17, v16
	s_nop 1
	v_permlane16_swap_b32 v17, v16
	v_cvt_pk_bf16_f32 v18, v20, v21
	v_cvt_pk_bf16_f32 v19, v22, v23
	v_cvt_pk_bf16_f32 v20, v30, v31
	v_cvt_pk_bf16_f32 v21, v28, v29
	s_waitcnt lgkmcnt(0)
	v_add_f32_e32 v16, v16, v17
	v_mov_b32_e32 v17, v16
	s_nop 1
	v_permlane32_swap_b32 v17, v16
	global_store_dwordx4 v[38:39], v[18:21], off offset:256
	s_and_saveexec_b64 s[10:11], vcc
	s_cbranch_execz .LBB0_195
	s_waitcnt lgkmcnt(0)
	v_add_f32_e32 v16, v16, v17
	v_lshl_add_u32 v17, v32, 4, s75
	ds_write_b32 v17, v16
.LBB0_195:
	s_or_b64 exec, exec, s[10:11]
	v_add_u32_e32 v16, 0xb0, v207
	v_add_u32_e32 v18, s76, v16
	v_ashrrev_i32_e32 v19, 31, v18
	v_lshlrev_b64 v[18:19], 11, v[18:19]
	v_lshl_add_u64 v[22:23], v[204:205], 0, v[18:19]
	ds_read_b32 v24, v206 offset:704
	s_waitcnt lgkmcnt(0)
	v_pk_mul_f32 v[14:15], v[14:15], v[24:25] op_sel_hi:[1,0]
	v_pk_mul_f32 v[12:13], v[12:13], v[24:25] op_sel_hi:[1,0]
	v_pk_mul_f32 v[10:11], v[10:11], v[24:25] op_sel_hi:[1,0]
	v_pk_mul_f32 v[8:9], v[8:9], v[24:25] op_sel_hi:[1,0]
	v_pk_mul_f32 v[6:7], v[6:7], v[24:25] op_sel_hi:[1,0]
	v_pk_mul_f32 v[4:5], v[4:5], v[24:25] op_sel_hi:[1,0]
	v_pk_mul_f32 v[2:3], v[2:3], v[24:25] op_sel_hi:[1,0]
	v_pk_mul_f32 v[0:1], v[0:1], v[24:25] op_sel_hi:[1,0]
	s_waitcnt vmcnt(13)
	v_lshlrev_b32_e32 v26, 16, v208
	v_and_b32_e32 v27, 0xffff0000, v208
	v_lshlrev_b32_e32 v18, 16, v209
	v_and_b32_e32 v19, 0xffff0000, v209
	v_lshlrev_b32_e32 v28, 16, v210
	v_and_b32_e32 v29, 0xffff0000, v210
	v_lshlrev_b32_e32 v20, 16, v211
	v_and_b32_e32 v21, 0xffff0000, v211
	v_pk_fma_f32 v[18:19], v[126:127], v[14:15], v[18:19]
	v_pk_fma_f32 v[26:27], v[124:125], v[12:13], v[26:27]
	v_pk_fma_f32 v[20:21], v[122:123], v[10:11], v[20:21]
	v_pk_fma_f32 v[28:29], v[120:121], v[8:9], v[28:29]
	v_cvt_pk_bf16_f32 v8, v26, v27
	v_cvt_pk_bf16_f32 v9, v18, v19
	v_mul_f32_e32 v17, v27, v27
	v_cvt_pk_bf16_f32 v10, v28, v29
	v_cvt_pk_bf16_f32 v11, v20, v21
	v_mul_f32_e32 v19, v19, v19
	v_mul_f32_e32 v24, v29, v29
	v_mul_f32_e32 v21, v21, v21
	v_fmac_f32_e32 v17, v26, v26
	v_fmac_f32_e32 v19, v18, v18
	v_fmac_f32_e32 v24, v28, v28
	v_fmac_f32_e32 v21, v20, v20
	v_add_f32_e32 v17, v17, v19
	v_add_f32_e32 v18, v24, v21
	v_add_f32_e32 v17, v17, v18
	global_store_dwordx4 v[22:23], v[8:11], off
	s_waitcnt vmcnt(13)
	v_lshlrev_b32_e32 v18, 16, v212
	v_and_b32_e32 v19, 0xffff0000, v212
	v_lshlrev_b32_e32 v12, 16, v213
	v_and_b32_e32 v13, 0xffff0000, v213
	v_lshlrev_b32_e32 v20, 16, v214
	v_and_b32_e32 v21, 0xffff0000, v214
	v_lshlrev_b32_e32 v14, 16, v215
	v_and_b32_e32 v15, 0xffff0000, v215
	v_pk_fma_f32 v[6:7], v[110:111], v[6:7], v[12:13]
	v_pk_fma_f32 v[4:5], v[108:109], v[4:5], v[18:19]
	v_pk_fma_f32 v[12:13], v[106:107], v[2:3], v[14:15]
	v_pk_fma_f32 v[14:15], v[104:105], v[0:1], v[20:21]
	v_mul_f32_e32 v0, v5, v5
	v_mul_f32_e32 v1, v7, v7
	v_mul_f32_e32 v2, v15, v15
	v_mul_f32_e32 v3, v13, v13
	v_fmac_f32_e32 v0, v4, v4
	v_fmac_f32_e32 v1, v6, v6
	v_fmac_f32_e32 v2, v14, v14
	v_fmac_f32_e32 v3, v12, v12
	v_add_f32_e32 v0, v0, v1
	v_add_f32_e32 v1, v2, v3
	v_add_f32_e32 v0, v0, v1
	v_add_f32_e32 v0, v17, v0
	v_mov_b32_e32 v1, v0
	s_nop 1
	v_permlane16_swap_b32 v1, v0
	v_cvt_pk_bf16_f32 v2, v4, v5
	v_cvt_pk_bf16_f32 v3, v6, v7
	v_cvt_pk_bf16_f32 v4, v14, v15
	v_cvt_pk_bf16_f32 v5, v12, v13
	s_waitcnt lgkmcnt(0)
	v_add_f32_e32 v0, v0, v1
	v_mov_b32_e32 v1, v0
	s_nop 1
	v_permlane32_swap_b32 v1, v0
	global_store_dwordx4 v[22:23], v[2:5], off offset:256
	s_and_saveexec_b64 s[10:11], vcc
	s_cbranch_execz .LBB0_197
	s_waitcnt lgkmcnt(0)
	v_add_f32_e32 v0, v0, v1
	v_lshl_add_u32 v1, v16, 4, s75
	ds_write_b32 v1, v0

.LBB0_511:
	s_mov_b32 s9, s73
	v_mov_b32_e32 v206, v219
	s_mov_b32 s13, s70
	v_mov_b32_e32 v232, v218
	s_mov_b64 s[10:11], s[0:1]
	v_and_b32_e32 v107, 64, v225
	v_mov_b64_e32 v[104:105], s[10:11]
	flat_load_dwordx2 v[202:203], v[104:105] offset:216
	s_nop 0
	flat_load_dwordx2 v[104:105], v[104:105] offset:168
	v_xor_b32_e32 v106, 16, v225
	v_add_u32_e32 v107, 64, v107
	v_cmp_lt_i32_e32 vcc, v106, v107
	v_mul_f32_e32 v108, v143, v143
	v_fmac_f32_e32 v108, v142, v142
	v_cndmask_b32_e32 v106, v225, v106, vcc
	v_lshlrev_b32_e32 v229, 2, v106
	v_mul_f32_e32 v106, v141, v141
	v_fmac_f32_e32 v106, v140, v140
	v_add_f32_e32 v106, v106, v108
	v_mul_f32_e32 v108, v137, v137
	v_mul_f32_e32 v109, v139, v139
	v_fmac_f32_e32 v108, v136, v136
	v_fmac_f32_e32 v109, v138, v138
	v_add_f32_e32 v108, v108, v109
	v_add_f32_e32 v106, v106, v108
	v_mul_f32_e32 v108, v133, v133
	v_mul_f32_e32 v109, v135, v135
	v_fmac_f32_e32 v108, v132, v132
	v_fmac_f32_e32 v109, v134, v134
	v_add_f32_e32 v108, v108, v109
	v_add_f32_e32 v106, v106, v108
	v_mul_f32_e32 v108, v129, v129
	v_mul_f32_e32 v109, v131, v131
	v_fmac_f32_e32 v108, v128, v128
	v_fmac_f32_e32 v109, v130, v130
	v_add_f32_e32 v108, v108, v109
	v_add_f32_e32 v106, v106, v108
	v_mov_b32_e32 v108, v106
	s_nop 1
	v_permlane16_swap_b32 v108, v106
	v_xor_b32_e32 v109, 32, v225
	v_cmp_lt_i32_e32 vcc, v109, v107
	s_lshl_b32 s39, s9, 2
	s_add_i32 s39, s39, 0x20400
	v_cndmask_b32_e32 v107, v225, v109, vcc
	v_lshlrev_b32_e32 v230, 2, v107
	s_waitcnt lgkmcnt(0)
	v_add_f32_e32 v106, v106, v108
	v_mov_b32_e32 v107, v106
	s_nop 1
	v_permlane32_swap_b32 v107, v106
	v_cmp_eq_u32_e32 vcc, 0, v206
	s_and_saveexec_b64 s[10:11], vcc
	s_cbranch_execz .LBB0_513
	s_lshl_b32 s51, s13, 10
	s_add_i32 s51, s39, s51
	v_lshl_add_u32 v108, v232, 4, s51
	s_waitcnt lgkmcnt(0)
	v_add_f32_e32 v106, v106, v107
	ds_write_b32 v108, v106
.LBB0_513:
	s_or_b64 exec, exec, s[10:11]
	v_mul_f32_e32 v106, v117, v117
	s_waitcnt lgkmcnt(0)
	v_mul_f32_e32 v107, v119, v119
	v_fmac_f32_e32 v106, v116, v116
	v_fmac_f32_e32 v107, v118, v118
	v_add_f32_e32 v106, v106, v107
	v_mul_f32_e32 v107, v113, v113
	v_mul_f32_e32 v108, v115, v115
	v_fmac_f32_e32 v107, v112, v112
	v_fmac_f32_e32 v108, v114, v114
	v_add_f32_e32 v107, v107, v108
	v_add_f32_e32 v106, v106, v107
	v_mul_f32_e32 v107, v101, v101
	v_mul_f32_e32 v108, v103, v103
	v_fmac_f32_e32 v107, v100, v100
	v_fmac_f32_e32 v108, v102, v102
	v_add_f32_e32 v107, v107, v108
	v_add_f32_e32 v106, v106, v107
	v_mul_f32_e32 v107, v97, v97
	v_mul_f32_e32 v108, v99, v99
	v_fmac_f32_e32 v107, v96, v96
	v_fmac_f32_e32 v108, v98, v98
	v_add_f32_e32 v107, v107, v108
	v_add_f32_e32 v106, v106, v107
	v_mov_b32_e32 v107, v106
	s_nop 1
	v_permlane16_swap_b32 v107, v106
	s_waitcnt lgkmcnt(0)
	v_add_f32_e32 v106, v106, v107
	v_mov_b32_e32 v107, v106
	s_nop 1
	v_permlane32_swap_b32 v107, v106
	s_and_saveexec_b64 s[10:11], vcc
	s_cbranch_execz .LBB0_515
	s_lshl_b32 s51, s13, 10
	s_add_i32 s51, s39, s51
	v_lshl_add_u32 v108, v232, 4, s51
	s_waitcnt lgkmcnt(0)
	v_add_f32_e32 v106, v106, v107
	ds_write_b32 v108, v106 offset:256
.LBB0_515:
	s_or_b64 exec, exec, s[10:11]
	v_mul_f32_e32 v106, v93, v93
	s_waitcnt lgkmcnt(0)
	v_mul_f32_e32 v107, v95, v95
	v_fmac_f32_e32 v106, v92, v92
	v_fmac_f32_e32 v107, v94, v94
	v_add_f32_e32 v106, v106, v107
	v_mul_f32_e32 v107, v89, v89
	v_mul_f32_e32 v108, v91, v91
	v_fmac_f32_e32 v107, v88, v88
	v_fmac_f32_e32 v108, v90, v90
	v_add_f32_e32 v107, v107, v108
	v_add_f32_e32 v106, v106, v107
	v_mul_f32_e32 v107, v85, v85
	v_mul_f32_e32 v108, v87, v87
	v_fmac_f32_e32 v107, v84, v84
	v_fmac_f32_e32 v108, v86, v86
	v_add_f32_e32 v107, v107, v108
	v_add_f32_e32 v106, v106, v107
	v_mul_f32_e32 v107, v81, v81
	v_mul_f32_e32 v108, v83, v83
	v_fmac_f32_e32 v107, v80, v80
	v_fmac_f32_e32 v108, v82, v82
	v_add_f32_e32 v107, v107, v108
	v_add_f32_e32 v106, v106, v107
	v_mov_b32_e32 v107, v106
	s_nop 1
	v_permlane16_swap_b32 v107, v106
	s_waitcnt lgkmcnt(0)
	v_add_f32_e32 v106, v106, v107
	v_mov_b32_e32 v107, v106
	s_nop 1
	v_permlane32_swap_b32 v107, v106
	s_and_saveexec_b64 s[10:11], vcc
	s_cbranch_execz .LBB0_517
	s_lshl_b32 s51, s13, 10
	s_add_i32 s51, s39, s51
	v_lshl_add_u32 v108, v232, 4, s51
	s_waitcnt lgkmcnt(0)
	v_add_f32_e32 v106, v106, v107
	ds_write_b32 v108, v106 offset:512
.LBB0_517:
	s_or_b64 exec, exec, s[10:11]
	v_mul_f32_e32 v106, v77, v77
	s_waitcnt lgkmcnt(0)
	v_mul_f32_e32 v107, v79, v79
	v_fmac_f32_e32 v106, v76, v76
	v_fmac_f32_e32 v107, v78, v78
	v_add_f32_e32 v106, v106, v107
	v_mul_f32_e32 v107, v73, v73
	v_mul_f32_e32 v108, v75, v75
	v_fmac_f32_e32 v107, v72, v72
	v_fmac_f32_e32 v108, v74, v74
	v_add_f32_e32 v107, v107, v108
	v_add_f32_e32 v106, v106, v107
	v_mul_f32_e32 v107, v69, v69
	v_mul_f32_e32 v108, v71, v71
	v_fmac_f32_e32 v107, v68, v68
	v_fmac_f32_e32 v108, v70, v70
	v_add_f32_e32 v107, v107, v108
	v_add_f32_e32 v106, v106, v107
	v_mul_f32_e32 v107, v65, v65
	v_mul_f32_e32 v108, v67, v67
	v_fmac_f32_e32 v107, v64, v64
	v_fmac_f32_e32 v108, v66, v66
	v_add_f32_e32 v107, v107, v108
	v_add_f32_e32 v106, v106, v107
	v_mov_b32_e32 v107, v106
	s_nop 1
	v_permlane16_swap_b32 v107, v106
	s_waitcnt lgkmcnt(0)
	v_add_f32_e32 v106, v106, v107
	v_mov_b32_e32 v107, v106
	s_nop 1
	v_permlane32_swap_b32 v107, v106
	s_and_saveexec_b64 s[10:11], vcc
	s_cbranch_execz .LBB0_519
	s_lshl_b32 s51, s13, 10
	s_add_i32 s51, s39, s51
	v_lshl_add_u32 v108, v232, 4, s51
	s_waitcnt lgkmcnt(0)
	v_add_f32_e32 v106, v106, v107
	ds_write_b32 v108, v106 offset:768
.LBB0_519:
	s_or_b64 exec, exec, s[10:11]
	v_mul_f32_e32 v106, v61, v61
	s_waitcnt lgkmcnt(0)
	v_mul_f32_e32 v107, v63, v63
	v_fmac_f32_e32 v106, v60, v60
	v_fmac_f32_e32 v107, v62, v62
	v_add_f32_e32 v106, v106, v107
	v_mul_f32_e32 v107, v57, v57
	v_mul_f32_e32 v108, v59, v59
	v_fmac_f32_e32 v107, v56, v56
	v_fmac_f32_e32 v108, v58, v58
	v_add_f32_e32 v107, v107, v108
	v_add_f32_e32 v106, v106, v107
	v_mul_f32_e32 v107, v53, v53
	v_mul_f32_e32 v108, v55, v55
	v_fmac_f32_e32 v107, v52, v52
	v_fmac_f32_e32 v108, v54, v54
	v_add_f32_e32 v107, v107, v108
	v_add_f32_e32 v106, v106, v107
	v_mul_f32_e32 v107, v49, v49
	v_mul_f32_e32 v108, v51, v51
	v_fmac_f32_e32 v107, v48, v48
	v_fmac_f32_e32 v108, v50, v50
	v_add_f32_e32 v107, v107, v108
	v_add_f32_e32 v106, v106, v107
	v_mov_b32_e32 v107, v106
	s_nop 1
	v_permlane16_swap_b32 v107, v106
	s_waitcnt lgkmcnt(0)
	v_add_f32_e32 v106, v106, v107
	v_mov_b32_e32 v107, v106
	s_nop 1
	v_permlane32_swap_b32 v107, v106
	s_and_saveexec_b64 s[10:11], vcc
	s_cbranch_execz .LBB0_521
	s_lshl_b32 s51, s13, 10
	s_add_i32 s51, s39, s51
	v_lshl_add_u32 v108, v232, 4, s51
	s_waitcnt lgkmcnt(0)
	v_add_f32_e32 v106, v106, v107
	ds_write_b32 v108, v106 offset:2048
.LBB0_521:
	s_or_b64 exec, exec, s[10:11]
	v_mul_f32_e32 v106, v45, v45
	s_waitcnt lgkmcnt(0)
	v_mul_f32_e32 v107, v47, v47
	v_fmac_f32_e32 v106, v44, v44
	v_fmac_f32_e32 v107, v46, v46
	v_add_f32_e32 v106, v106, v107
	v_mul_f32_e32 v107, v41, v41
	v_mul_f32_e32 v108, v43, v43
	v_fmac_f32_e32 v107, v40, v40
	v_fmac_f32_e32 v108, v42, v42
	v_add_f32_e32 v107, v107, v108
	v_add_f32_e32 v106, v106, v107
	v_mul_f32_e32 v107, v37, v37
	v_mul_f32_e32 v108, v39, v39
	v_fmac_f32_e32 v107, v36, v36
	v_fmac_f32_e32 v108, v38, v38
	v_add_f32_e32 v107, v107, v108
	v_add_f32_e32 v106, v106, v107
	v_mul_f32_e32 v107, v33, v33
	v_mul_f32_e32 v108, v35, v35
	v_fmac_f32_e32 v107, v32, v32
	v_fmac_f32_e32 v108, v34, v34
	v_add_f32_e32 v107, v107, v108
	v_add_f32_e32 v106, v106, v107
	v_mov_b32_e32 v107, v106
	s_nop 1
	v_permlane16_swap_b32 v107, v106
	s_waitcnt lgkmcnt(0)
	v_add_f32_e32 v106, v106, v107
	v_mov_b32_e32 v107, v106
	s_nop 1
	v_permlane32_swap_b32 v107, v106
	s_and_saveexec_b64 s[10:11], vcc
	s_cbranch_execz .LBB0_523
	s_lshl_b32 s51, s13, 10
	s_add_i32 s51, s39, s51
	v_lshl_add_u32 v108, v232, 4, s51
	s_waitcnt lgkmcnt(0)
	v_add_f32_e32 v106, v106, v107
	ds_write_b32 v108, v106 offset:2304
.LBB0_523:
	s_or_b64 exec, exec, s[10:11]
	v_mul_f32_e32 v106, v29, v29
	s_waitcnt lgkmcnt(0)
	v_mul_f32_e32 v107, v31, v31
	v_fmac_f32_e32 v106, v28, v28
	v_fmac_f32_e32 v107, v30, v30
	v_add_f32_e32 v106, v106, v107
	v_mul_f32_e32 v107, v25, v25
	v_mul_f32_e32 v108, v27, v27
	v_fmac_f32_e32 v107, v24, v24
	v_fmac_f32_e32 v108, v26, v26
	v_add_f32_e32 v107, v107, v108
	v_add_f32_e32 v106, v106, v107
	v_mul_f32_e32 v107, v21, v21
	v_mul_f32_e32 v108, v23, v23
	v_fmac_f32_e32 v107, v20, v20
	v_fmac_f32_e32 v108, v22, v22
	v_add_f32_e32 v107, v107, v108
	v_add_f32_e32 v106, v106, v107
	v_mul_f32_e32 v107, v17, v17
	v_mul_f32_e32 v108, v19, v19
	v_fmac_f32_e32 v107, v16, v16
	v_fmac_f32_e32 v108, v18, v18
	v_add_f32_e32 v107, v107, v108
	v_add_f32_e32 v106, v106, v107
	v_mov_b32_e32 v107, v106
	s_nop 1
	v_permlane16_swap_b32 v107, v106
	s_waitcnt lgkmcnt(0)
	v_add_f32_e32 v106, v106, v107
	v_mov_b32_e32 v107, v106
	s_nop 1
	v_permlane32_swap_b32 v107, v106
	s_and_saveexec_b64 s[10:11], vcc
	s_cbranch_execz .LBB0_525
	s_lshl_b32 s51, s13, 10
	s_add_i32 s51, s39, s51
	v_lshl_add_u32 v108, v232, 4, s51
	s_waitcnt lgkmcnt(0)
	v_add_f32_e32 v106, v106, v107
	ds_write_b32 v108, v106 offset:2560
.LBB0_525:
	s_or_b64 exec, exec, s[10:11]
	v_mul_f32_e32 v106, v13, v13
	s_waitcnt lgkmcnt(0)
	v_mul_f32_e32 v107, v15, v15
	v_fmac_f32_e32 v106, v12, v12
	v_fmac_f32_e32 v107, v14, v14
	v_add_f32_e32 v106, v106, v107
	v_mul_f32_e32 v107, v9, v9
	v_mul_f32_e32 v108, v11, v11
	v_fmac_f32_e32 v107, v8, v8
	v_fmac_f32_e32 v108, v10, v10
	v_add_f32_e32 v107, v107, v108
	v_add_f32_e32 v106, v106, v107
	v_mul_f32_e32 v107, v5, v5
	v_mul_f32_e32 v108, v7, v7
	v_fmac_f32_e32 v107, v4, v4
	v_fmac_f32_e32 v108, v6, v6
	v_add_f32_e32 v107, v107, v108
	v_add_f32_e32 v106, v106, v107
	v_mul_f32_e32 v107, v1, v1
	v_mul_f32_e32 v108, v3, v3
	v_fmac_f32_e32 v107, v0, v0
	v_fmac_f32_e32 v108, v2, v2
	v_add_f32_e32 v107, v107, v108
	v_add_f32_e32 v106, v106, v107
	v_mov_b32_e32 v107, v106
	s_nop 1
	v_permlane16_swap_b32 v107, v106
	s_waitcnt lgkmcnt(0)
	v_add_f32_e32 v106, v106, v107
	v_mov_b32_e32 v107, v106
	s_nop 1
	v_permlane32_swap_b32 v107, v106
	s_and_saveexec_b64 s[10:11], vcc
	s_cbranch_execz .LBB0_527
	s_lshl_b32 s51, s13, 10
	s_add_i32 s51, s39, s51
	v_lshl_add_u32 v108, v232, 4, s51
	s_waitcnt lgkmcnt(0)
	v_add_f32_e32 v106, v106, v107
	ds_write_b32 v108, v106 offset:2816

.LBB0_542:
	s_or_b64 exec, exec, s[52:53]
	v_add_u32_e32 v207, s85, v232
	s_waitcnt vmcnt(0) lgkmcnt(0)
	s_barrier
	v_lshl_add_u32 v206, v207, 2, v228
	ds_read_b32 v210, v206
	v_lshlrev_b32_e32 v212, 16, v172
	v_and_b32_e32 v213, 0xffff0000, v172
	v_lshlrev_b32_e32 v172, 16, v173
	v_and_b32_e32 v173, 0xffff0000, v173
	s_waitcnt lgkmcnt(0)
	v_pk_mul_f32 v[142:143], v[142:143], v[210:211] op_sel_hi:[1,0]
	v_pk_mul_f32 v[140:141], v[140:141], v[210:211] op_sel_hi:[1,0]
	v_lshlrev_b32_e32 v214, 16, v174
	v_and_b32_e32 v215, 0xffff0000, v174
	v_lshlrev_b32_e32 v174, 16, v175
	v_and_b32_e32 v175, 0xffff0000, v175
	v_pk_fma_f32 v[142:143], v[126:127], v[142:143], v[172:173]
	v_pk_fma_f32 v[140:141], v[124:125], v[140:141], v[212:213]
	v_pk_mul_f32 v[138:139], v[138:139], v[210:211] op_sel_hi:[1,0]
	v_pk_mul_f32 v[136:137], v[136:137], v[210:211] op_sel_hi:[1,0]
	v_pk_fma_f32 v[172:173], v[122:123], v[138:139], v[174:175]
	v_pk_fma_f32 v[138:139], v[120:121], v[136:137], v[214:215]
	v_mul_f32_e32 v136, v141, v141
	v_mul_f32_e32 v137, v143, v143
	v_fmac_f32_e32 v136, v140, v140
	v_fmac_f32_e32 v137, v142, v142
	v_add_f32_e32 v136, v136, v137
	v_mul_f32_e32 v137, v139, v139
	v_mul_f32_e32 v174, v173, v173
	v_fmac_f32_e32 v137, v138, v138
	v_fmac_f32_e32 v174, v172, v172
	v_add_f32_e32 v137, v137, v174
	v_add_f32_e32 v174, v136, v137
	v_cvt_pk_bf16_f32 v136, v140, v141
	v_cvt_pk_bf16_f32 v137, v142, v143
	v_lshlrev_b32_e32 v140, 16, v168
	v_and_b32_e32 v141, 0xffff0000, v168
	v_lshlrev_b32_e32 v142, 16, v169
	v_and_b32_e32 v143, 0xffff0000, v169
	v_pk_mul_f32 v[134:135], v[134:135], v[210:211] op_sel_hi:[1,0]
	v_pk_mul_f32 v[132:133], v[132:133], v[210:211] op_sel_hi:[1,0]
	v_lshlrev_b32_e32 v168, 16, v170
	v_and_b32_e32 v169, 0xffff0000, v170
	v_pk_fma_f32 v[134:135], v[110:111], v[134:135], v[142:143]
	v_pk_fma_f32 v[132:133], v[108:109], v[132:133], v[140:141]
	v_pk_mul_f32 v[128:129], v[128:129], v[210:211] op_sel_hi:[1,0]
	v_lshlrev_b32_e32 v170, 16, v171
	v_and_b32_e32 v171, 0xffff0000, v171
	v_pk_mul_f32 v[130:131], v[130:131], v[210:211] op_sel_hi:[1,0]
	v_pk_fma_f32 v[142:143], v[104:105], v[128:129], v[168:169]
	v_mul_f32_e32 v128, v133, v133
	v_mul_f32_e32 v129, v135, v135
	v_pk_fma_f32 v[140:141], v[106:107], v[130:131], v[170:171]
	v_fmac_f32_e32 v128, v132, v132
	v_fmac_f32_e32 v129, v134, v134
	v_add_f32_e32 v128, v128, v129
	v_mul_f32_e32 v129, v143, v143
	v_mul_f32_e32 v130, v141, v141
	v_fmac_f32_e32 v129, v142, v142
	v_fmac_f32_e32 v130, v140, v140
	v_add_f32_e32 v129, v129, v130
	v_add_f32_e32 v128, v128, v129
	v_add_f32_e32 v128, v174, v128
	v_mov_b32_e32 v129, v128
	s_nop 1
	v_permlane16_swap_b32 v129, v128
	v_add_u32_e32 v208, s51, v207
	v_ashrrev_i32_e32 v209, 31, v208
	v_lshlrev_b64 v[208:209], 11, v[208:209]
	v_lshl_add_u64 v[208:209], v[204:205], 0, v[208:209]
	s_waitcnt lgkmcnt(0)
	v_add_f32_e32 v128, v128, v129
	v_mov_b32_e32 v129, v128
	s_nop 1
	v_permlane32_swap_b32 v129, v128
	v_cvt_pk_bf16_f32 v138, v138, v139
	v_cvt_pk_bf16_f32 v139, v172, v173
	global_store_dwordx4 v[208:209], v[136:139], off
	v_cvt_pk_bf16_f32 v130, v132, v133
	v_cvt_pk_bf16_f32 v131, v134, v135
	v_cvt_pk_bf16_f32 v132, v142, v143
	v_cvt_pk_bf16_f32 v133, v140, v141
	global_store_dwordx4 v[208:209], v[130:133], off offset:256
	s_and_saveexec_b64 s[10:11], vcc
	s_cbranch_execz .LBB0_544
	s_waitcnt lgkmcnt(0)
	v_add_f32_e32 v128, v128, v129
	v_lshl_add_u32 v129, v207, 4, s39
	ds_write_b32 v129, v128
.LBB0_544:
	s_or_b64 exec, exec, s[10:11]
	v_add_u32_e32 v252, 0xa0, v207
	v_add_u32_e32 v252, s51, v252
	v_ashrrev_i32_e32 v253, 31, v252
	v_lshlrev_b64 v[252:253], 11, v[252:253]
	v_lshl_add_u64 v[252:253], v[204:205], 0, v[252:253]
	global_load_dwordx4 v[168:171], v[252:253], off
	global_load_dwordx4 v[172:175], v[252:253], off offset:256
	v_add_u32_e32 v252, 0xb0, v207
	v_add_u32_e32 v252, s51, v252
	v_ashrrev_i32_e32 v253, 31, v252
	v_lshlrev_b64 v[252:253], 11, v[252:253]
	v_lshl_add_u64 v[252:253], v[204:205], 0, v[252:253]
	global_load_dwordx4 v[208:211], v[252:253], off
	global_load_dwordx4 v[212:215], v[252:253], off offset:256
	ds_read_b32 v132, v206 offset:64
	v_lshlrev_b32_e32 v134, 16, v164
	v_and_b32_e32 v135, 0xffff0000, v164
	v_lshlrev_b32_e32 v136, 16, v165
	v_and_b32_e32 v137, 0xffff0000, v165
	s_waitcnt lgkmcnt(0)
	v_pk_mul_f32 v[118:119], v[118:119], v[132:133] op_sel_hi:[1,0]
	v_pk_mul_f32 v[116:117], v[116:117], v[132:133] op_sel_hi:[1,0]
	v_lshlrev_b32_e32 v138, 16, v166
	v_and_b32_e32 v139, 0xffff0000, v166
	v_lshlrev_b32_e32 v140, 16, v167
	v_and_b32_e32 v141, 0xffff0000, v167
	v_pk_fma_f32 v[118:119], v[126:127], v[118:119], v[136:137]
	v_pk_fma_f32 v[116:117], v[124:125], v[116:117], v[134:135]
	v_pk_mul_f32 v[114:115], v[114:115], v[132:133] op_sel_hi:[1,0]
	v_pk_mul_f32 v[112:113], v[112:113], v[132:133] op_sel_hi:[1,0]
	v_pk_fma_f32 v[134:135], v[122:123], v[114:115], v[140:141]
	v_pk_fma_f32 v[114:115], v[120:121], v[112:113], v[138:139]
	v_mul_f32_e32 v112, v117, v117
	v_mul_f32_e32 v113, v119, v119
	v_fmac_f32_e32 v112, v116, v116
	v_fmac_f32_e32 v113, v118, v118
	v_add_f32_e32 v112, v112, v113
	v_mul_f32_e32 v113, v115, v115
	v_mul_f32_e32 v129, v135, v135
	v_fmac_f32_e32 v113, v114, v114
	v_fmac_f32_e32 v129, v134, v134
	v_add_f32_e32 v113, v113, v129
	v_add_f32_e32 v129, v112, v113
	v_cvt_pk_bf16_f32 v112, v116, v117
	v_cvt_pk_bf16_f32 v113, v118, v119
	v_lshlrev_b32_e32 v116, 16, v160
	v_and_b32_e32 v117, 0xffff0000, v160
	v_lshlrev_b32_e32 v118, 16, v161
	v_and_b32_e32 v119, 0xffff0000, v161
	v_pk_mul_f32 v[102:103], v[102:103], v[132:133] op_sel_hi:[1,0]
	v_pk_mul_f32 v[100:101], v[100:101], v[132:133] op_sel_hi:[1,0]
	v_lshlrev_b32_e32 v136, 16, v162
	v_and_b32_e32 v137, 0xffff0000, v162
	v_pk_fma_f32 v[102:103], v[110:111], v[102:103], v[118:119]
	v_pk_fma_f32 v[100:101], v[108:109], v[100:101], v[116:117]
	v_pk_mul_f32 v[96:97], v[96:97], v[132:133] op_sel_hi:[1,0]
	v_lshlrev_b32_e32 v138, 16, v163
	v_and_b32_e32 v139, 0xffff0000, v163
	v_pk_mul_f32 v[98:99], v[98:99], v[132:133] op_sel_hi:[1,0]
	v_pk_fma_f32 v[118:119], v[104:105], v[96:97], v[136:137]
	v_mul_f32_e32 v96, v101, v101
	v_mul_f32_e32 v97, v103, v103
	v_pk_fma_f32 v[116:117], v[106:107], v[98:99], v[138:139]
	v_fmac_f32_e32 v96, v100, v100
	v_fmac_f32_e32 v97, v102, v102
	v_add_f32_e32 v96, v96, v97
	v_mul_f32_e32 v97, v119, v119
	v_mul_f32_e32 v98, v117, v117
	v_fmac_f32_e32 v97, v118, v118
	v_fmac_f32_e32 v98, v116, v116
	v_add_f32_e32 v97, v97, v98
	v_add_f32_e32 v96, v96, v97
	v_add_f32_e32 v96, v129, v96
	v_mov_b32_e32 v97, v96
	s_nop 1
	v_permlane16_swap_b32 v97, v96
	v_add_u32_e32 v128, 16, v207
	v_add_u32_e32 v130, s51, v128
	v_ashrrev_i32_e32 v131, 31, v130
	v_lshlrev_b64 v[130:131], 11, v[130:131]
	s_waitcnt lgkmcnt(0)
	v_add_f32_e32 v96, v96, v97
	v_mov_b32_e32 v97, v96
	s_nop 1
	v_permlane32_swap_b32 v97, v96
	v_lshl_add_u64 v[130:131], v[204:205], 0, v[130:131]
	v_cvt_pk_bf16_f32 v114, v114, v115
	v_cvt_pk_bf16_f32 v115, v134, v135
	global_store_dwordx4 v[130:131], v[112:115], off
	v_cvt_pk_bf16_f32 v98, v100, v101
	v_cvt_pk_bf16_f32 v99, v102, v103
	v_cvt_pk_bf16_f32 v100, v118, v119
	v_cvt_pk_bf16_f32 v101, v116, v117
	global_store_dwordx4 v[130:131], v[98:101], off offset:256
	s_and_saveexec_b64 s[10:11], vcc
	s_cbranch_execz .LBB0_546
	s_waitcnt lgkmcnt(0)
	v_add_f32_e32 v96, v96, v97
	v_lshl_add_u32 v97, v128, 4, s39
	ds_write_b32 v97, v96
.LBB0_546:
	s_or_b64 exec, exec, s[10:11]
	ds_read_b32 v100, v206 offset:128
	v_lshlrev_b32_e32 v102, 16, v156
	v_and_b32_e32 v103, 0xffff0000, v156
	v_lshlrev_b32_e32 v112, 16, v157
	v_and_b32_e32 v113, 0xffff0000, v157
	s_waitcnt lgkmcnt(0)
	v_pk_mul_f32 v[94:95], v[94:95], v[100:101] op_sel_hi:[1,0]
	v_pk_mul_f32 v[92:93], v[92:93], v[100:101] op_sel_hi:[1,0]
	v_lshlrev_b32_e32 v114, 16, v158
	v_and_b32_e32 v115, 0xffff0000, v158
	v_lshlrev_b32_e32 v116, 16, v159
	v_and_b32_e32 v117, 0xffff0000, v159
	v_pk_fma_f32 v[94:95], v[126:127], v[94:95], v[112:113]
	v_pk_fma_f32 v[92:93], v[124:125], v[92:93], v[102:103]
	v_pk_mul_f32 v[90:91], v[90:91], v[100:101] op_sel_hi:[1,0]
	v_pk_mul_f32 v[88:89], v[88:89], v[100:101] op_sel_hi:[1,0]
	v_pk_fma_f32 v[102:103], v[122:123], v[90:91], v[116:117]
	v_pk_fma_f32 v[90:91], v[120:121], v[88:89], v[114:115]
	v_mul_f32_e32 v88, v93, v93
	v_mul_f32_e32 v89, v95, v95
	v_fmac_f32_e32 v88, v92, v92
	v_fmac_f32_e32 v89, v94, v94
	v_add_f32_e32 v88, v88, v89
	v_mul_f32_e32 v89, v91, v91
	v_mul_f32_e32 v97, v103, v103
	v_fmac_f32_e32 v89, v90, v90
	v_fmac_f32_e32 v97, v102, v102
	v_add_f32_e32 v89, v89, v97
	v_add_f32_e32 v97, v88, v89
	v_cvt_pk_bf16_f32 v88, v92, v93
	v_cvt_pk_bf16_f32 v89, v94, v95
	v_lshlrev_b32_e32 v92, 16, v152
	v_and_b32_e32 v93, 0xffff0000, v152
	v_lshlrev_b32_e32 v94, 16, v153
	v_and_b32_e32 v95, 0xffff0000, v153
	v_pk_mul_f32 v[86:87], v[86:87], v[100:101] op_sel_hi:[1,0]
	v_pk_mul_f32 v[84:85], v[84:85], v[100:101] op_sel_hi:[1,0]
	v_lshlrev_b32_e32 v112, 16, v154
	v_and_b32_e32 v113, 0xffff0000, v154
	v_pk_fma_f32 v[86:87], v[110:111], v[86:87], v[94:95]
	v_pk_fma_f32 v[84:85], v[108:109], v[84:85], v[92:93]
	v_pk_mul_f32 v[80:81], v[80:81], v[100:101] op_sel_hi:[1,0]
	v_lshlrev_b32_e32 v114, 16, v155
	v_and_b32_e32 v115, 0xffff0000, v155
	v_pk_mul_f32 v[82:83], v[82:83], v[100:101] op_sel_hi:[1,0]
	v_pk_fma_f32 v[94:95], v[104:105], v[80:81], v[112:113]
	v_mul_f32_e32 v80, v85, v85
	v_mul_f32_e32 v81, v87, v87
	v_pk_fma_f32 v[92:93], v[106:107], v[82:83], v[114:115]
	v_fmac_f32_e32 v80, v84, v84
	v_fmac_f32_e32 v81, v86, v86
	v_add_f32_e32 v80, v80, v81
	v_mul_f32_e32 v81, v95, v95
	v_mul_f32_e32 v82, v93, v93
	v_fmac_f32_e32 v81, v94, v94
	v_fmac_f32_e32 v82, v92, v92
	v_add_f32_e32 v81, v81, v82
	v_add_f32_e32 v80, v80, v81
	v_add_f32_e32 v80, v97, v80
	v_mov_b32_e32 v81, v80
	s_nop 1
	v_permlane16_swap_b32 v81, v80
	v_add_u32_e32 v96, 32, v207
	v_add_u32_e32 v98, s51, v96
	v_ashrrev_i32_e32 v99, 31, v98
	v_lshlrev_b64 v[98:99], 11, v[98:99]
	s_waitcnt lgkmcnt(0)
	v_add_f32_e32 v80, v80, v81
	v_mov_b32_e32 v81, v80
	s_nop 1
	v_permlane32_swap_b32 v81, v80
	v_lshl_add_u64 v[98:99], v[204:205], 0, v[98:99]
	v_cvt_pk_bf16_f32 v90, v90, v91
	v_cvt_pk_bf16_f32 v91, v102, v103
	global_store_dwordx4 v[98:99], v[88:91], off
	v_cvt_pk_bf16_f32 v82, v84, v85
	v_cvt_pk_bf16_f32 v83, v86, v87
	v_cvt_pk_bf16_f32 v84, v94, v95
	v_cvt_pk_bf16_f32 v85, v92, v93
	global_store_dwordx4 v[98:99], v[82:85], off offset:256
	s_and_saveexec_b64 s[10:11], vcc
	s_cbranch_execz .LBB0_548
	s_waitcnt lgkmcnt(0)
	v_add_f32_e32 v80, v80, v81
	v_lshl_add_u32 v81, v96, 4, s39
	ds_write_b32 v81, v80
.LBB0_548:
	s_or_b64 exec, exec, s[10:11]
	ds_read_b32 v84, v206 offset:192
	v_lshlrev_b32_e32 v86, 16, v148
	v_and_b32_e32 v87, 0xffff0000, v148
	v_lshlrev_b32_e32 v88, 16, v149
	v_and_b32_e32 v89, 0xffff0000, v149
	s_waitcnt lgkmcnt(0)
	v_pk_mul_f32 v[78:79], v[78:79], v[84:85] op_sel_hi:[1,0]
	v_pk_mul_f32 v[76:77], v[76:77], v[84:85] op_sel_hi:[1,0]
	v_lshlrev_b32_e32 v90, 16, v150
	v_and_b32_e32 v91, 0xffff0000, v150
	v_lshlrev_b32_e32 v92, 16, v151
	v_and_b32_e32 v93, 0xffff0000, v151
	v_pk_fma_f32 v[78:79], v[126:127], v[78:79], v[88:89]
	v_pk_fma_f32 v[76:77], v[124:125], v[76:77], v[86:87]
	v_pk_mul_f32 v[74:75], v[74:75], v[84:85] op_sel_hi:[1,0]
	v_pk_mul_f32 v[72:73], v[72:73], v[84:85] op_sel_hi:[1,0]
	v_pk_fma_f32 v[86:87], v[122:123], v[74:75], v[92:93]
	v_pk_fma_f32 v[74:75], v[120:121], v[72:73], v[90:91]
	v_mul_f32_e32 v72, v77, v77
	v_mul_f32_e32 v73, v79, v79
	v_fmac_f32_e32 v72, v76, v76
	v_fmac_f32_e32 v73, v78, v78
	v_add_f32_e32 v72, v72, v73
	v_mul_f32_e32 v73, v75, v75
	v_mul_f32_e32 v81, v87, v87
	v_fmac_f32_e32 v73, v74, v74
	v_fmac_f32_e32 v81, v86, v86
	v_add_f32_e32 v73, v73, v81
	v_add_f32_e32 v81, v72, v73
	v_cvt_pk_bf16_f32 v72, v76, v77
	v_cvt_pk_bf16_f32 v73, v78, v79
	v_lshlrev_b32_e32 v76, 16, v144
	v_and_b32_e32 v77, 0xffff0000, v144
	v_lshlrev_b32_e32 v78, 16, v145
	v_and_b32_e32 v79, 0xffff0000, v145
	v_pk_mul_f32 v[70:71], v[70:71], v[84:85] op_sel_hi:[1,0]
	v_pk_mul_f32 v[68:69], v[68:69], v[84:85] op_sel_hi:[1,0]
	v_lshlrev_b32_e32 v88, 16, v146
	v_and_b32_e32 v89, 0xffff0000, v146
	v_pk_fma_f32 v[70:71], v[110:111], v[70:71], v[78:79]
	v_pk_fma_f32 v[68:69], v[108:109], v[68:69], v[76:77]
	v_pk_mul_f32 v[64:65], v[64:65], v[84:85] op_sel_hi:[1,0]
	v_lshlrev_b32_e32 v90, 16, v147
	v_and_b32_e32 v91, 0xffff0000, v147
	v_pk_mul_f32 v[66:67], v[66:67], v[84:85] op_sel_hi:[1,0]
	v_pk_fma_f32 v[78:79], v[104:105], v[64:65], v[88:89]
	v_mul_f32_e32 v64, v69, v69
	v_mul_f32_e32 v65, v71, v71
	v_pk_fma_f32 v[76:77], v[106:107], v[66:67], v[90:91]
	v_fmac_f32_e32 v64, v68, v68
	v_fmac_f32_e32 v65, v70, v70
	v_add_f32_e32 v64, v64, v65
	v_mul_f32_e32 v65, v79, v79
	v_mul_f32_e32 v66, v77, v77
	v_fmac_f32_e32 v65, v78, v78
	v_fmac_f32_e32 v66, v76, v76
	v_add_f32_e32 v65, v65, v66
	v_add_f32_e32 v64, v64, v65
	v_add_f32_e32 v64, v81, v64
	v_mov_b32_e32 v65, v64
	s_nop 1
	v_permlane16_swap_b32 v65, v64
	v_add_u32_e32 v80, 48, v207
	v_add_u32_e32 v82, s51, v80
	v_ashrrev_i32_e32 v83, 31, v82
	v_lshlrev_b64 v[82:83], 11, v[82:83]
	s_waitcnt lgkmcnt(0)
	v_add_f32_e32 v64, v64, v65
	v_mov_b32_e32 v65, v64
	s_nop 1
	v_permlane32_swap_b32 v65, v64
	v_lshl_add_u64 v[82:83], v[204:205], 0, v[82:83]
	v_cvt_pk_bf16_f32 v74, v74, v75
	v_cvt_pk_bf16_f32 v75, v86, v87
	global_store_dwordx4 v[82:83], v[72:75], off
	v_cvt_pk_bf16_f32 v66, v68, v69
	v_cvt_pk_bf16_f32 v67, v70, v71
	v_cvt_pk_bf16_f32 v68, v78, v79
	v_cvt_pk_bf16_f32 v69, v76, v77
	global_store_dwordx4 v[82:83], v[66:69], off offset:256
	s_and_saveexec_b64 s[10:11], vcc
	s_cbranch_execz .LBB0_550
	s_waitcnt lgkmcnt(0)
	v_add_f32_e32 v64, v64, v65
	v_lshl_add_u32 v65, v80, 4, s39
	ds_write_b32 v65, v64
.LBB0_550:
	s_or_b64 exec, exec, s[10:11]
	v_add_u32_e32 v64, 0x80, v207
	v_add_u32_e32 v66, s51, v64
	v_ashrrev_i32_e32 v67, 31, v66
	v_lshlrev_b64 v[66:67], 11, v[66:67]
	v_lshl_add_u64 v[70:71], v[204:205], 0, v[66:67]
	ds_read_b32 v72, v206 offset:512
	s_waitcnt lgkmcnt(0)
	v_pk_mul_f32 v[62:63], v[62:63], v[72:73] op_sel_hi:[1,0]
	v_pk_mul_f32 v[60:61], v[60:61], v[72:73] op_sel_hi:[1,0]
	v_pk_mul_f32 v[58:59], v[58:59], v[72:73] op_sel_hi:[1,0]
	v_pk_mul_f32 v[56:57], v[56:57], v[72:73] op_sel_hi:[1,0]
	v_pk_mul_f32 v[54:55], v[54:55], v[72:73] op_sel_hi:[1,0]
	v_pk_mul_f32 v[52:53], v[52:53], v[72:73] op_sel_hi:[1,0]
	v_pk_mul_f32 v[50:51], v[50:51], v[72:73] op_sel_hi:[1,0]
	v_pk_mul_f32 v[48:49], v[48:49], v[72:73] op_sel_hi:[1,0]
	v_lshlrev_b32_e32 v74, 16, v236
	v_and_b32_e32 v75, 0xffff0000, v236
	v_lshlrev_b32_e32 v66, 16, v237
	v_and_b32_e32 v67, 0xffff0000, v237
	v_lshlrev_b32_e32 v76, 16, v238
	v_and_b32_e32 v77, 0xffff0000, v238
	v_lshlrev_b32_e32 v68, 16, v239
	v_and_b32_e32 v69, 0xffff0000, v239
	v_pk_fma_f32 v[66:67], v[126:127], v[62:63], v[66:67]
	v_pk_fma_f32 v[74:75], v[124:125], v[60:61], v[74:75]
	v_pk_fma_f32 v[68:69], v[122:123], v[58:59], v[68:69]
	v_pk_fma_f32 v[76:77], v[120:121], v[56:57], v[76:77]
	v_cvt_pk_bf16_f32 v56, v74, v75
	v_cvt_pk_bf16_f32 v57, v66, v67
	v_mul_f32_e32 v65, v75, v75
	v_cvt_pk_bf16_f32 v58, v76, v77
	v_cvt_pk_bf16_f32 v59, v68, v69
	v_mul_f32_e32 v67, v67, v67
	v_mul_f32_e32 v72, v77, v77
	v_mul_f32_e32 v69, v69, v69
	v_fmac_f32_e32 v65, v74, v74
	v_fmac_f32_e32 v67, v66, v66
	v_fmac_f32_e32 v72, v76, v76
	v_fmac_f32_e32 v69, v68, v68
	v_add_f32_e32 v65, v65, v67
	v_add_f32_e32 v66, v72, v69
	v_add_f32_e32 v65, v65, v66
	global_store_dwordx4 v[70:71], v[56:59], off
	v_lshlrev_b32_e32 v66, 16, v240
	v_and_b32_e32 v67, 0xffff0000, v240
	v_lshlrev_b32_e32 v60, 16, v241
	v_and_b32_e32 v61, 0xffff0000, v241
	v_lshlrev_b32_e32 v68, 16, v242
	v_and_b32_e32 v69, 0xffff0000, v242
	v_lshlrev_b32_e32 v62, 16, v243
	v_and_b32_e32 v63, 0xffff0000, v243
	v_pk_fma_f32 v[54:55], v[110:111], v[54:55], v[60:61]
	v_pk_fma_f32 v[52:53], v[108:109], v[52:53], v[66:67]
	v_pk_fma_f32 v[60:61], v[106:107], v[50:51], v[62:63]
	v_pk_fma_f32 v[62:63], v[104:105], v[48:49], v[68:69]
	v_mul_f32_e32 v48, v53, v53
	v_mul_f32_e32 v49, v55, v55
	v_mul_f32_e32 v50, v63, v63
	v_mul_f32_e32 v51, v61, v61
	v_fmac_f32_e32 v48, v52, v52
	v_fmac_f32_e32 v49, v54, v54
	v_fmac_f32_e32 v50, v62, v62
	v_fmac_f32_e32 v51, v60, v60
	v_add_f32_e32 v48, v48, v49
	v_add_f32_e32 v49, v50, v51
	v_add_f32_e32 v48, v48, v49
	v_add_f32_e32 v48, v65, v48
	v_mov_b32_e32 v49, v48
	s_nop 1
	v_permlane16_swap_b32 v49, v48
	v_cvt_pk_bf16_f32 v50, v52, v53
	v_cvt_pk_bf16_f32 v51, v54, v55
	v_cvt_pk_bf16_f32 v52, v62, v63
	v_cvt_pk_bf16_f32 v53, v60, v61
	s_waitcnt lgkmcnt(0)
	v_add_f32_e32 v48, v48, v49
	v_mov_b32_e32 v49, v48
	s_nop 1
	v_permlane32_swap_b32 v49, v48
	global_store_dwordx4 v[70:71], v[50:53], off offset:256
	s_and_saveexec_b64 s[10:11], vcc
	s_cbranch_execz .LBB0_552
	s_waitcnt lgkmcnt(0)
	v_add_f32_e32 v48, v48, v49
	v_lshl_add_u32 v49, v64, 4, s39
	ds_write_b32 v49, v48
.LBB0_552:
	s_or_b64 exec, exec, s[10:11]
	v_add_u32_e32 v48, 0x90, v207
	v_add_u32_e32 v50, s51, v48
	v_ashrrev_i32_e32 v51, 31, v50
	v_lshlrev_b64 v[50:51], 11, v[50:51]
	v_lshl_add_u64 v[54:55], v[204:205], 0, v[50:51]
	ds_read_b32 v56, v206 offset:576
	s_waitcnt lgkmcnt(0)
	v_pk_mul_f32 v[46:47], v[46:47], v[56:57] op_sel_hi:[1,0]
	v_pk_mul_f32 v[44:45], v[44:45], v[56:57] op_sel_hi:[1,0]
	v_pk_mul_f32 v[42:43], v[42:43], v[56:57] op_sel_hi:[1,0]
	v_pk_mul_f32 v[40:41], v[40:41], v[56:57] op_sel_hi:[1,0]
	v_pk_mul_f32 v[38:39], v[38:39], v[56:57] op_sel_hi:[1,0]
	v_pk_mul_f32 v[36:37], v[36:37], v[56:57] op_sel_hi:[1,0]
	v_pk_mul_f32 v[34:35], v[34:35], v[56:57] op_sel_hi:[1,0]
	v_pk_mul_f32 v[32:33], v[32:33], v[56:57] op_sel_hi:[1,0]
	v_lshlrev_b32_e32 v58, 16, v244
	v_and_b32_e32 v59, 0xffff0000, v244
	v_lshlrev_b32_e32 v50, 16, v245
	v_and_b32_e32 v51, 0xffff0000, v245
	v_lshlrev_b32_e32 v60, 16, v246
	v_and_b32_e32 v61, 0xffff0000, v246
	v_lshlrev_b32_e32 v52, 16, v247
	v_and_b32_e32 v53, 0xffff0000, v247
	v_pk_fma_f32 v[50:51], v[126:127], v[46:47], v[50:51]
	v_pk_fma_f32 v[58:59], v[124:125], v[44:45], v[58:59]
	v_pk_fma_f32 v[52:53], v[122:123], v[42:43], v[52:53]
	v_pk_fma_f32 v[60:61], v[120:121], v[40:41], v[60:61]
	v_cvt_pk_bf16_f32 v40, v58, v59
	v_cvt_pk_bf16_f32 v41, v50, v51
	v_mul_f32_e32 v49, v59, v59
	v_cvt_pk_bf16_f32 v42, v60, v61
	v_cvt_pk_bf16_f32 v43, v52, v53
	v_mul_f32_e32 v51, v51, v51
	v_mul_f32_e32 v56, v61, v61
	v_mul_f32_e32 v53, v53, v53
	v_fmac_f32_e32 v49, v58, v58
	v_fmac_f32_e32 v51, v50, v50
	v_fmac_f32_e32 v56, v60, v60
	v_fmac_f32_e32 v53, v52, v52
	v_add_f32_e32 v49, v49, v51
	v_add_f32_e32 v50, v56, v53
	v_add_f32_e32 v49, v49, v50
	global_store_dwordx4 v[54:55], v[40:43], off
	v_lshlrev_b32_e32 v50, 16, v248
	v_and_b32_e32 v51, 0xffff0000, v248
	v_lshlrev_b32_e32 v44, 16, v249
	v_and_b32_e32 v45, 0xffff0000, v249
	v_lshlrev_b32_e32 v52, 16, v250
	v_and_b32_e32 v53, 0xffff0000, v250
	v_lshlrev_b32_e32 v46, 16, v251
	v_and_b32_e32 v47, 0xffff0000, v251
	v_pk_fma_f32 v[38:39], v[110:111], v[38:39], v[44:45]
	v_pk_fma_f32 v[36:37], v[108:109], v[36:37], v[50:51]
	v_pk_fma_f32 v[44:45], v[106:107], v[34:35], v[46:47]
	v_pk_fma_f32 v[46:47], v[104:105], v[32:33], v[52:53]
	v_mul_f32_e32 v32, v37, v37
	v_mul_f32_e32 v33, v39, v39
	v_mul_f32_e32 v34, v47, v47
	v_mul_f32_e32 v35, v45, v45
	v_fmac_f32_e32 v32, v36, v36
	v_fmac_f32_e32 v33, v38, v38
	v_fmac_f32_e32 v34, v46, v46
	v_fmac_f32_e32 v35, v44, v44
	v_add_f32_e32 v32, v32, v33
	v_add_f32_e32 v33, v34, v35
	v_add_f32_e32 v32, v32, v33
	v_add_f32_e32 v32, v49, v32
	v_mov_b32_e32 v33, v32
	s_nop 1
	v_permlane16_swap_b32 v33, v32
	v_cvt_pk_bf16_f32 v34, v36, v37
	v_cvt_pk_bf16_f32 v35, v38, v39
	v_cvt_pk_bf16_f32 v36, v46, v47
	v_cvt_pk_bf16_f32 v37, v44, v45
	s_waitcnt lgkmcnt(0)
	v_add_f32_e32 v32, v32, v33
	v_mov_b32_e32 v33, v32
	s_nop 1
	v_permlane32_swap_b32 v33, v32
	global_store_dwordx4 v[54:55], v[34:37], off offset:256
	s_and_saveexec_b64 s[10:11], vcc
	s_cbranch_execz .LBB0_554
	s_waitcnt lgkmcnt(0)
	v_add_f32_e32 v32, v32, v33
	v_lshl_add_u32 v33, v48, 4, s39
	ds_write_b32 v33, v32
.LBB0_554:
	s_or_b64 exec, exec, s[10:11]
	v_add_u32_e32 v32, 0xa0, v207
	v_add_u32_e32 v34, s51, v32
	v_ashrrev_i32_e32 v35, 31, v34
	v_lshlrev_b64 v[34:35], 11, v[34:35]
	v_lshl_add_u64 v[38:39], v[204:205], 0, v[34:35]
	ds_read_b32 v40, v206 offset:640
	s_waitcnt lgkmcnt(0)
	v_pk_mul_f32 v[30:31], v[30:31], v[40:41] op_sel_hi:[1,0]
	v_pk_mul_f32 v[28:29], v[28:29], v[40:41] op_sel_hi:[1,0]
	v_pk_mul_f32 v[26:27], v[26:27], v[40:41] op_sel_hi:[1,0]
	v_pk_mul_f32 v[24:25], v[24:25], v[40:41] op_sel_hi:[1,0]
	v_pk_mul_f32 v[22:23], v[22:23], v[40:41] op_sel_hi:[1,0]
	v_pk_mul_f32 v[20:21], v[20:21], v[40:41] op_sel_hi:[1,0]
	v_pk_mul_f32 v[18:19], v[18:19], v[40:41] op_sel_hi:[1,0]
	v_pk_mul_f32 v[16:17], v[16:17], v[40:41] op_sel_hi:[1,0]
	s_waitcnt vmcnt(13)
	v_lshlrev_b32_e32 v42, 16, v168
	v_and_b32_e32 v43, 0xffff0000, v168
	v_lshlrev_b32_e32 v34, 16, v169
	v_and_b32_e32 v35, 0xffff0000, v169
	v_lshlrev_b32_e32 v44, 16, v170
	v_and_b32_e32 v45, 0xffff0000, v170
	v_lshlrev_b32_e32 v36, 16, v171
	v_and_b32_e32 v37, 0xffff0000, v171
	v_pk_fma_f32 v[34:35], v[126:127], v[30:31], v[34:35]
	v_pk_fma_f32 v[42:43], v[124:125], v[28:29], v[42:43]
	v_pk_fma_f32 v[36:37], v[122:123], v[26:27], v[36:37]
	v_pk_fma_f32 v[44:45], v[120:121], v[24:25], v[44:45]
	v_cvt_pk_bf16_f32 v24, v42, v43
	v_cvt_pk_bf16_f32 v25, v34, v35
	v_mul_f32_e32 v33, v43, v43
	v_cvt_pk_bf16_f32 v26, v44, v45
	v_cvt_pk_bf16_f32 v27, v36, v37
	v_mul_f32_e32 v35, v35, v35
	v_mul_f32_e32 v40, v45, v45
	v_mul_f32_e32 v37, v37, v37
	v_fmac_f32_e32 v33, v42, v42
	v_fmac_f32_e32 v35, v34, v34
	v_fmac_f32_e32 v40, v44, v44
	v_fmac_f32_e32 v37, v36, v36
	v_add_f32_e32 v33, v33, v35
	v_add_f32_e32 v34, v40, v37
	v_add_f32_e32 v33, v33, v34
	global_store_dwordx4 v[38:39], v[24:27], off
	s_waitcnt vmcnt(13)
	v_lshlrev_b32_e32 v34, 16, v172
	v_and_b32_e32 v35, 0xffff0000, v172
	v_lshlrev_b32_e32 v28, 16, v173
	v_and_b32_e32 v29, 0xffff0000, v173
	v_lshlrev_b32_e32 v36, 16, v174
	v_and_b32_e32 v37, 0xffff0000, v174
	v_lshlrev_b32_e32 v30, 16, v175
	v_and_b32_e32 v31, 0xffff0000, v175
	v_pk_fma_f32 v[22:23], v[110:111], v[22:23], v[28:29]
	v_pk_fma_f32 v[20:21], v[108:109], v[20:21], v[34:35]
	v_pk_fma_f32 v[28:29], v[106:107], v[18:19], v[30:31]
	v_pk_fma_f32 v[30:31], v[104:105], v[16:17], v[36:37]
	v_mul_f32_e32 v16, v21, v21
	v_mul_f32_e32 v17, v23, v23
	v_mul_f32_e32 v18, v31, v31
	v_mul_f32_e32 v19, v29, v29
	v_fmac_f32_e32 v16, v20, v20
	v_fmac_f32_e32 v17, v22, v22
	v_fmac_f32_e32 v18, v30, v30
	v_fmac_f32_e32 v19, v28, v28
	v_add_f32_e32 v16, v16, v17
	v_add_f32_e32 v17, v18, v19
	v_add_f32_e32 v16, v16, v17
	v_add_f32_e32 v16, v33, v16
	v_mov_b32_e32 v17, v16
	s_nop 1
	v_permlane16_swap_b32 v17, v16
	v_cvt_pk_bf16_f32 v18, v20, v21
	v_cvt_pk_bf16_f32 v19, v22, v23
	v_cvt_pk_bf16_f32 v20, v30, v31
	v_cvt_pk_bf16_f32 v21, v28, v29
	s_waitcnt lgkmcnt(0)
	v_add_f32_e32 v16, v16, v17
	v_mov_b32_e32 v17, v16
	s_nop 1
	v_permlane32_swap_b32 v17, v16
	global_store_dwordx4 v[38:39], v[18:21], off offset:256
	s_and_saveexec_b64 s[10:11], vcc
	s_cbranch_execz .LBB0_556
	s_waitcnt lgkmcnt(0)
	v_add_f32_e32 v16, v16, v17
	v_lshl_add_u32 v17, v32, 4, s39
	ds_write_b32 v17, v16
.LBB0_556:
	s_or_b64 exec, exec, s[10:11]
	v_add_u32_e32 v16, 0xb0, v207
	v_add_u32_e32 v18, s51, v16
	v_ashrrev_i32_e32 v19, 31, v18
	v_lshlrev_b64 v[18:19], 11, v[18:19]
	v_lshl_add_u64 v[22:23], v[204:205], 0, v[18:19]
	ds_read_b32 v24, v206 offset:704
	s_waitcnt lgkmcnt(0)
	v_pk_mul_f32 v[14:15], v[14:15], v[24:25] op_sel_hi:[1,0]
	v_pk_mul_f32 v[12:13], v[12:13], v[24:25] op_sel_hi:[1,0]
	v_pk_mul_f32 v[10:11], v[10:11], v[24:25] op_sel_hi:[1,0]
	v_pk_mul_f32 v[8:9], v[8:9], v[24:25] op_sel_hi:[1,0]
	v_pk_mul_f32 v[6:7], v[6:7], v[24:25] op_sel_hi:[1,0]
	v_pk_mul_f32 v[4:5], v[4:5], v[24:25] op_sel_hi:[1,0]
	v_pk_mul_f32 v[2:3], v[2:3], v[24:25] op_sel_hi:[1,0]
	v_pk_mul_f32 v[0:1], v[0:1], v[24:25] op_sel_hi:[1,0]
	s_waitcnt vmcnt(13)
	v_lshlrev_b32_e32 v26, 16, v208
	v_and_b32_e32 v27, 0xffff0000, v208
	v_lshlrev_b32_e32 v18, 16, v209
	v_and_b32_e32 v19, 0xffff0000, v209
	v_lshlrev_b32_e32 v28, 16, v210
	v_and_b32_e32 v29, 0xffff0000, v210
	v_lshlrev_b32_e32 v20, 16, v211
	v_and_b32_e32 v21, 0xffff0000, v211
	v_pk_fma_f32 v[18:19], v[126:127], v[14:15], v[18:19]
	v_pk_fma_f32 v[26:27], v[124:125], v[12:13], v[26:27]
	v_pk_fma_f32 v[20:21], v[122:123], v[10:11], v[20:21]
	v_pk_fma_f32 v[28:29], v[120:121], v[8:9], v[28:29]
	v_cvt_pk_bf16_f32 v8, v26, v27
	v_cvt_pk_bf16_f32 v9, v18, v19
	v_mul_f32_e32 v17, v27, v27
	v_cvt_pk_bf16_f32 v10, v28, v29
	v_cvt_pk_bf16_f32 v11, v20, v21
	v_mul_f32_e32 v19, v19, v19
	v_mul_f32_e32 v24, v29, v29
	v_mul_f32_e32 v21, v21, v21
	v_fmac_f32_e32 v17, v26, v26
	v_fmac_f32_e32 v19, v18, v18
	v_fmac_f32_e32 v24, v28, v28
	v_fmac_f32_e32 v21, v20, v20
	v_add_f32_e32 v17, v17, v19
	v_add_f32_e32 v18, v24, v21
	v_add_f32_e32 v17, v17, v18
	global_store_dwordx4 v[22:23], v[8:11], off
	s_waitcnt vmcnt(13)
	v_lshlrev_b32_e32 v18, 16, v212
	v_and_b32_e32 v19, 0xffff0000, v212
	v_lshlrev_b32_e32 v12, 16, v213
	v_and_b32_e32 v13, 0xffff0000, v213
	v_lshlrev_b32_e32 v20, 16, v214
	v_and_b32_e32 v21, 0xffff0000, v214
	v_lshlrev_b32_e32 v14, 16, v215
	v_and_b32_e32 v15, 0xffff0000, v215
	v_pk_fma_f32 v[6:7], v[110:111], v[6:7], v[12:13]
	v_pk_fma_f32 v[4:5], v[108:109], v[4:5], v[18:19]
	v_pk_fma_f32 v[12:13], v[106:107], v[2:3], v[14:15]
	v_pk_fma_f32 v[14:15], v[104:105], v[0:1], v[20:21]
	v_mul_f32_e32 v0, v5, v5
	v_mul_f32_e32 v1, v7, v7
	v_mul_f32_e32 v2, v15, v15
	v_mul_f32_e32 v3, v13, v13
	v_fmac_f32_e32 v0, v4, v4
	v_fmac_f32_e32 v1, v6, v6
	v_fmac_f32_e32 v2, v14, v14
	v_fmac_f32_e32 v3, v12, v12
	v_add_f32_e32 v0, v0, v1
	v_add_f32_e32 v1, v2, v3
	v_add_f32_e32 v0, v0, v1
	v_add_f32_e32 v0, v17, v0
	v_mov_b32_e32 v1, v0
	s_nop 1
	v_permlane16_swap_b32 v1, v0
	v_cvt_pk_bf16_f32 v2, v4, v5
	v_cvt_pk_bf16_f32 v3, v6, v7
	v_cvt_pk_bf16_f32 v4, v14, v15
	v_cvt_pk_bf16_f32 v5, v12, v13
	s_waitcnt lgkmcnt(0)
	v_add_f32_e32 v0, v0, v1
	v_mov_b32_e32 v1, v0
	s_nop 1
	v_permlane32_swap_b32 v1, v0
	global_store_dwordx4 v[22:23], v[2:5], off offset:256
	s_and_saveexec_b64 s[10:11], vcc
	s_cbranch_execz .LBB0_558
	s_waitcnt lgkmcnt(0)
	v_add_f32_e32 v0, v0, v1
	v_lshl_add_u32 v1, v16, 4, s39
	ds_write_b32 v1, v0

.LBB0_699:
	s_mov_b32 s13, s65
	v_mov_b32_e32 v206, v220
	s_mov_b32 s15, s62
	v_mov_b32_e32 v233, v219
	s_mov_b64 s[10:11], s[0:1]
	v_and_b32_e32 v107, 64, v226
	v_mov_b64_e32 v[104:105], s[10:11]
	flat_load_dwordx2 v[202:203], v[104:105] offset:216
	s_nop 0
	flat_load_dwordx2 v[104:105], v[104:105] offset:200
	v_xor_b32_e32 v106, 16, v226
	v_add_u32_e32 v107, 64, v107
	v_cmp_lt_i32_e32 vcc, v106, v107
	v_mul_f32_e32 v108, v143, v143
	v_fmac_f32_e32 v108, v142, v142
	v_cndmask_b32_e32 v106, v226, v106, vcc
	v_lshlrev_b32_e32 v230, 2, v106
	v_mul_f32_e32 v106, v141, v141
	v_fmac_f32_e32 v106, v140, v140
	v_add_f32_e32 v106, v106, v108
	v_mul_f32_e32 v108, v137, v137
	v_mul_f32_e32 v109, v139, v139
	v_fmac_f32_e32 v108, v136, v136
	v_fmac_f32_e32 v109, v138, v138
	v_add_f32_e32 v108, v108, v109
	v_add_f32_e32 v106, v106, v108
	v_mul_f32_e32 v108, v133, v133
	v_mul_f32_e32 v109, v135, v135
	v_fmac_f32_e32 v108, v132, v132
	v_fmac_f32_e32 v109, v134, v134
	v_add_f32_e32 v108, v108, v109
	v_add_f32_e32 v106, v106, v108
	v_mul_f32_e32 v108, v129, v129
	v_mul_f32_e32 v109, v131, v131
	v_fmac_f32_e32 v108, v128, v128
	v_fmac_f32_e32 v109, v130, v130
	v_add_f32_e32 v108, v108, v109
	v_add_f32_e32 v106, v106, v108
	v_mov_b32_e32 v108, v106
	s_nop 1
	v_permlane16_swap_b32 v108, v106
	v_xor_b32_e32 v109, 32, v226
	v_cmp_lt_i32_e32 vcc, v109, v107
	s_lshl_b32 s79, s13, 2
	s_add_i32 s79, s79, 0x20400
	v_cndmask_b32_e32 v107, v226, v109, vcc
	v_lshlrev_b32_e32 v231, 2, v107
	s_waitcnt lgkmcnt(0)
	v_add_f32_e32 v106, v106, v108
	v_mov_b32_e32 v107, v106
	s_nop 1
	v_permlane32_swap_b32 v107, v106
	v_cmp_eq_u32_e32 vcc, 0, v206
	s_and_saveexec_b64 s[10:11], vcc
	s_cbranch_execz .LBB0_701
	s_lshl_b32 s38, s15, 10
	s_add_i32 s38, s79, s38
	v_lshl_add_u32 v108, v233, 4, s38
	s_waitcnt lgkmcnt(0)
	v_add_f32_e32 v106, v106, v107
	ds_write_b32 v108, v106
.LBB0_701:
	s_or_b64 exec, exec, s[10:11]
	v_mul_f32_e32 v106, v117, v117
	s_waitcnt lgkmcnt(0)
	v_mul_f32_e32 v107, v119, v119
	v_fmac_f32_e32 v106, v116, v116
	v_fmac_f32_e32 v107, v118, v118
	v_add_f32_e32 v106, v106, v107
	v_mul_f32_e32 v107, v113, v113
	v_mul_f32_e32 v108, v115, v115
	v_fmac_f32_e32 v107, v112, v112
	v_fmac_f32_e32 v108, v114, v114
	v_add_f32_e32 v107, v107, v108
	v_add_f32_e32 v106, v106, v107
	v_mul_f32_e32 v107, v101, v101
	v_mul_f32_e32 v108, v103, v103
	v_fmac_f32_e32 v107, v100, v100
	v_fmac_f32_e32 v108, v102, v102
	v_add_f32_e32 v107, v107, v108
	v_add_f32_e32 v106, v106, v107
	v_mul_f32_e32 v107, v97, v97
	v_mul_f32_e32 v108, v99, v99
	v_fmac_f32_e32 v107, v96, v96
	v_fmac_f32_e32 v108, v98, v98
	v_add_f32_e32 v107, v107, v108
	v_add_f32_e32 v106, v106, v107
	v_mov_b32_e32 v107, v106
	s_nop 1
	v_permlane16_swap_b32 v107, v106
	s_waitcnt lgkmcnt(0)
	v_add_f32_e32 v106, v106, v107
	v_mov_b32_e32 v107, v106
	s_nop 1
	v_permlane32_swap_b32 v107, v106
	s_and_saveexec_b64 s[10:11], vcc
	s_cbranch_execz .LBB0_703
	s_lshl_b32 s38, s15, 10
	s_add_i32 s38, s79, s38
	v_lshl_add_u32 v108, v233, 4, s38
	s_waitcnt lgkmcnt(0)
	v_add_f32_e32 v106, v106, v107
	ds_write_b32 v108, v106 offset:256
.LBB0_703:
	s_or_b64 exec, exec, s[10:11]
	v_mul_f32_e32 v106, v93, v93
	s_waitcnt lgkmcnt(0)
	v_mul_f32_e32 v107, v95, v95
	v_fmac_f32_e32 v106, v92, v92
	v_fmac_f32_e32 v107, v94, v94
	v_add_f32_e32 v106, v106, v107
	v_mul_f32_e32 v107, v89, v89
	v_mul_f32_e32 v108, v91, v91
	v_fmac_f32_e32 v107, v88, v88
	v_fmac_f32_e32 v108, v90, v90
	v_add_f32_e32 v107, v107, v108
	v_add_f32_e32 v106, v106, v107
	v_mul_f32_e32 v107, v85, v85
	v_mul_f32_e32 v108, v87, v87
	v_fmac_f32_e32 v107, v84, v84
	v_fmac_f32_e32 v108, v86, v86
	v_add_f32_e32 v107, v107, v108
	v_add_f32_e32 v106, v106, v107
	v_mul_f32_e32 v107, v81, v81
	v_mul_f32_e32 v108, v83, v83
	v_fmac_f32_e32 v107, v80, v80
	v_fmac_f32_e32 v108, v82, v82
	v_add_f32_e32 v107, v107, v108
	v_add_f32_e32 v106, v106, v107
	v_mov_b32_e32 v107, v106
	s_nop 1
	v_permlane16_swap_b32 v107, v106
	s_waitcnt lgkmcnt(0)
	v_add_f32_e32 v106, v106, v107
	v_mov_b32_e32 v107, v106
	s_nop 1
	v_permlane32_swap_b32 v107, v106
	s_and_saveexec_b64 s[10:11], vcc
	s_cbranch_execz .LBB0_705
	s_lshl_b32 s38, s15, 10
	s_add_i32 s38, s79, s38
	v_lshl_add_u32 v108, v233, 4, s38
	s_waitcnt lgkmcnt(0)
	v_add_f32_e32 v106, v106, v107
	ds_write_b32 v108, v106 offset:512
.LBB0_705:
	s_or_b64 exec, exec, s[10:11]
	v_mul_f32_e32 v106, v77, v77
	s_waitcnt lgkmcnt(0)
	v_mul_f32_e32 v107, v79, v79
	v_fmac_f32_e32 v106, v76, v76
	v_fmac_f32_e32 v107, v78, v78
	v_add_f32_e32 v106, v106, v107
	v_mul_f32_e32 v107, v73, v73
	v_mul_f32_e32 v108, v75, v75
	v_fmac_f32_e32 v107, v72, v72
	v_fmac_f32_e32 v108, v74, v74
	v_add_f32_e32 v107, v107, v108
	v_add_f32_e32 v106, v106, v107
	v_mul_f32_e32 v107, v69, v69
	v_mul_f32_e32 v108, v71, v71
	v_fmac_f32_e32 v107, v68, v68
	v_fmac_f32_e32 v108, v70, v70
	v_add_f32_e32 v107, v107, v108
	v_add_f32_e32 v106, v106, v107
	v_mul_f32_e32 v107, v65, v65
	v_mul_f32_e32 v108, v67, v67
	v_fmac_f32_e32 v107, v64, v64
	v_fmac_f32_e32 v108, v66, v66
	v_add_f32_e32 v107, v107, v108
	v_add_f32_e32 v106, v106, v107
	v_mov_b32_e32 v107, v106
	s_nop 1
	v_permlane16_swap_b32 v107, v106
	s_waitcnt lgkmcnt(0)
	v_add_f32_e32 v106, v106, v107
	v_mov_b32_e32 v107, v106
	s_nop 1
	v_permlane32_swap_b32 v107, v106
	s_and_saveexec_b64 s[10:11], vcc
	s_cbranch_execz .LBB0_707
	s_lshl_b32 s38, s15, 10
	s_add_i32 s38, s79, s38
	v_lshl_add_u32 v108, v233, 4, s38
	s_waitcnt lgkmcnt(0)
	v_add_f32_e32 v106, v106, v107
	ds_write_b32 v108, v106 offset:768
.LBB0_707:
	s_or_b64 exec, exec, s[10:11]
	v_mul_f32_e32 v106, v61, v61
	s_waitcnt lgkmcnt(0)
	v_mul_f32_e32 v107, v63, v63
	v_fmac_f32_e32 v106, v60, v60
	v_fmac_f32_e32 v107, v62, v62
	v_add_f32_e32 v106, v106, v107
	v_mul_f32_e32 v107, v57, v57
	v_mul_f32_e32 v108, v59, v59
	v_fmac_f32_e32 v107, v56, v56
	v_fmac_f32_e32 v108, v58, v58
	v_add_f32_e32 v107, v107, v108
	v_add_f32_e32 v106, v106, v107
	v_mul_f32_e32 v107, v53, v53
	v_mul_f32_e32 v108, v55, v55
	v_fmac_f32_e32 v107, v52, v52
	v_fmac_f32_e32 v108, v54, v54
	v_add_f32_e32 v107, v107, v108
	v_add_f32_e32 v106, v106, v107
	v_mul_f32_e32 v107, v49, v49
	v_mul_f32_e32 v108, v51, v51
	v_fmac_f32_e32 v107, v48, v48
	v_fmac_f32_e32 v108, v50, v50
	v_add_f32_e32 v107, v107, v108
	v_add_f32_e32 v106, v106, v107
	v_mov_b32_e32 v107, v106
	s_nop 1
	v_permlane16_swap_b32 v107, v106
	s_waitcnt lgkmcnt(0)
	v_add_f32_e32 v106, v106, v107
	v_mov_b32_e32 v107, v106
	s_nop 1
	v_permlane32_swap_b32 v107, v106
	s_and_saveexec_b64 s[10:11], vcc
	s_cbranch_execz .LBB0_709
	s_lshl_b32 s38, s15, 10
	s_add_i32 s38, s79, s38
	v_lshl_add_u32 v108, v233, 4, s38
	s_waitcnt lgkmcnt(0)
	v_add_f32_e32 v106, v106, v107
	ds_write_b32 v108, v106 offset:2048
.LBB0_709:
	s_or_b64 exec, exec, s[10:11]
	v_mul_f32_e32 v106, v45, v45
	s_waitcnt lgkmcnt(0)
	v_mul_f32_e32 v107, v47, v47
	v_fmac_f32_e32 v106, v44, v44
	v_fmac_f32_e32 v107, v46, v46
	v_add_f32_e32 v106, v106, v107
	v_mul_f32_e32 v107, v41, v41
	v_mul_f32_e32 v108, v43, v43
	v_fmac_f32_e32 v107, v40, v40
	v_fmac_f32_e32 v108, v42, v42
	v_add_f32_e32 v107, v107, v108
	v_add_f32_e32 v106, v106, v107
	v_mul_f32_e32 v107, v37, v37
	v_mul_f32_e32 v108, v39, v39
	v_fmac_f32_e32 v107, v36, v36
	v_fmac_f32_e32 v108, v38, v38
	v_add_f32_e32 v107, v107, v108
	v_add_f32_e32 v106, v106, v107
	v_mul_f32_e32 v107, v33, v33
	v_mul_f32_e32 v108, v35, v35
	v_fmac_f32_e32 v107, v32, v32
	v_fmac_f32_e32 v108, v34, v34
	v_add_f32_e32 v107, v107, v108
	v_add_f32_e32 v106, v106, v107
	v_mov_b32_e32 v107, v106
	s_nop 1
	v_permlane16_swap_b32 v107, v106
	s_waitcnt lgkmcnt(0)
	v_add_f32_e32 v106, v106, v107
	v_mov_b32_e32 v107, v106
	s_nop 1
	v_permlane32_swap_b32 v107, v106
	s_and_saveexec_b64 s[10:11], vcc
	s_cbranch_execz .LBB0_711
	s_lshl_b32 s38, s15, 10
	s_add_i32 s38, s79, s38
	v_lshl_add_u32 v108, v233, 4, s38
	s_waitcnt lgkmcnt(0)
	v_add_f32_e32 v106, v106, v107
	ds_write_b32 v108, v106 offset:2304
.LBB0_711:
	s_or_b64 exec, exec, s[10:11]
	v_mul_f32_e32 v106, v29, v29
	s_waitcnt lgkmcnt(0)
	v_mul_f32_e32 v107, v31, v31
	v_fmac_f32_e32 v106, v28, v28
	v_fmac_f32_e32 v107, v30, v30
	v_add_f32_e32 v106, v106, v107
	v_mul_f32_e32 v107, v25, v25
	v_mul_f32_e32 v108, v27, v27
	v_fmac_f32_e32 v107, v24, v24
	v_fmac_f32_e32 v108, v26, v26
	v_add_f32_e32 v107, v107, v108
	v_add_f32_e32 v106, v106, v107
	v_mul_f32_e32 v107, v21, v21
	v_mul_f32_e32 v108, v23, v23
	v_fmac_f32_e32 v107, v20, v20
	v_fmac_f32_e32 v108, v22, v22
	v_add_f32_e32 v107, v107, v108
	v_add_f32_e32 v106, v106, v107
	v_mul_f32_e32 v107, v17, v17
	v_mul_f32_e32 v108, v19, v19
	v_fmac_f32_e32 v107, v16, v16
	v_fmac_f32_e32 v108, v18, v18
	v_add_f32_e32 v107, v107, v108
	v_add_f32_e32 v106, v106, v107
	v_mov_b32_e32 v107, v106
	s_nop 1
	v_permlane16_swap_b32 v107, v106
	s_waitcnt lgkmcnt(0)
	v_add_f32_e32 v106, v106, v107
	v_mov_b32_e32 v107, v106
	s_nop 1
	v_permlane32_swap_b32 v107, v106
	s_and_saveexec_b64 s[10:11], vcc
	s_cbranch_execz .LBB0_713
	s_lshl_b32 s38, s15, 10
	s_add_i32 s38, s79, s38
	v_lshl_add_u32 v108, v233, 4, s38
	s_waitcnt lgkmcnt(0)
	v_add_f32_e32 v106, v106, v107
	ds_write_b32 v108, v106 offset:2560
.LBB0_713:
	s_or_b64 exec, exec, s[10:11]
	v_mul_f32_e32 v106, v13, v13
	s_waitcnt lgkmcnt(0)
	v_mul_f32_e32 v107, v15, v15
	v_fmac_f32_e32 v106, v12, v12
	v_fmac_f32_e32 v107, v14, v14
	v_add_f32_e32 v106, v106, v107
	v_mul_f32_e32 v107, v9, v9
	v_mul_f32_e32 v108, v11, v11
	v_fmac_f32_e32 v107, v8, v8
	v_fmac_f32_e32 v108, v10, v10
	v_add_f32_e32 v107, v107, v108
	v_add_f32_e32 v106, v106, v107
	v_mul_f32_e32 v107, v5, v5
	v_mul_f32_e32 v108, v7, v7
	v_fmac_f32_e32 v107, v4, v4
	v_fmac_f32_e32 v108, v6, v6
	v_add_f32_e32 v107, v107, v108
	v_add_f32_e32 v106, v106, v107
	v_mul_f32_e32 v107, v1, v1
	v_mul_f32_e32 v108, v3, v3
	v_fmac_f32_e32 v107, v0, v0
	v_fmac_f32_e32 v108, v2, v2
	v_add_f32_e32 v107, v107, v108
	v_add_f32_e32 v106, v106, v107
	v_mov_b32_e32 v107, v106
	s_nop 1
	v_permlane16_swap_b32 v107, v106
	s_waitcnt lgkmcnt(0)
	v_add_f32_e32 v106, v106, v107
	v_mov_b32_e32 v107, v106
	s_nop 1
	v_permlane32_swap_b32 v107, v106
	s_and_saveexec_b64 s[10:11], vcc
	s_cbranch_execz .LBB0_715
	s_lshl_b32 s38, s15, 10
	s_add_i32 s38, s79, s38
	v_lshl_add_u32 v108, v233, 4, s38
	s_waitcnt lgkmcnt(0)
	v_add_f32_e32 v106, v106, v107
	ds_write_b32 v108, v106 offset:2816

.LBB0_730:
	s_or_b64 exec, exec, s[38:39]
	v_add_u32_e32 v207, s81, v233
	s_waitcnt vmcnt(0) lgkmcnt(0)
	s_barrier
	v_lshl_add_u32 v206, v207, 2, v229
	ds_read_b32 v210, v206
	v_lshlrev_b32_e32 v212, 16, v172
	v_and_b32_e32 v213, 0xffff0000, v172
	v_lshlrev_b32_e32 v172, 16, v173
	v_and_b32_e32 v173, 0xffff0000, v173
	s_waitcnt lgkmcnt(0)
	v_pk_mul_f32 v[142:143], v[142:143], v[210:211] op_sel_hi:[1,0]
	v_pk_mul_f32 v[140:141], v[140:141], v[210:211] op_sel_hi:[1,0]
	v_lshlrev_b32_e32 v214, 16, v174
	v_and_b32_e32 v215, 0xffff0000, v174
	v_lshlrev_b32_e32 v174, 16, v175
	v_and_b32_e32 v175, 0xffff0000, v175
	v_pk_fma_f32 v[142:143], v[126:127], v[142:143], v[172:173]
	v_pk_fma_f32 v[140:141], v[124:125], v[140:141], v[212:213]
	v_pk_mul_f32 v[138:139], v[138:139], v[210:211] op_sel_hi:[1,0]
	v_pk_mul_f32 v[136:137], v[136:137], v[210:211] op_sel_hi:[1,0]
	v_pk_fma_f32 v[172:173], v[122:123], v[138:139], v[174:175]
	v_pk_fma_f32 v[138:139], v[120:121], v[136:137], v[214:215]
	v_mul_f32_e32 v136, v141, v141
	v_mul_f32_e32 v137, v143, v143
	v_fmac_f32_e32 v136, v140, v140
	v_fmac_f32_e32 v137, v142, v142
	v_add_f32_e32 v136, v136, v137
	v_mul_f32_e32 v137, v139, v139
	v_mul_f32_e32 v174, v173, v173
	v_fmac_f32_e32 v137, v138, v138
	v_fmac_f32_e32 v174, v172, v172
	v_add_f32_e32 v137, v137, v174
	v_add_f32_e32 v174, v136, v137
	v_cvt_pk_bf16_f32 v136, v140, v141
	v_cvt_pk_bf16_f32 v137, v142, v143
	v_lshlrev_b32_e32 v140, 16, v168
	v_and_b32_e32 v141, 0xffff0000, v168
	v_lshlrev_b32_e32 v142, 16, v169
	v_and_b32_e32 v143, 0xffff0000, v169
	v_pk_mul_f32 v[134:135], v[134:135], v[210:211] op_sel_hi:[1,0]
	v_pk_mul_f32 v[132:133], v[132:133], v[210:211] op_sel_hi:[1,0]
	v_lshlrev_b32_e32 v168, 16, v170
	v_and_b32_e32 v169, 0xffff0000, v170
	v_pk_fma_f32 v[134:135], v[110:111], v[134:135], v[142:143]
	v_pk_fma_f32 v[132:133], v[108:109], v[132:133], v[140:141]
	v_pk_mul_f32 v[128:129], v[128:129], v[210:211] op_sel_hi:[1,0]
	v_lshlrev_b32_e32 v170, 16, v171
	v_and_b32_e32 v171, 0xffff0000, v171
	v_pk_mul_f32 v[130:131], v[130:131], v[210:211] op_sel_hi:[1,0]
	v_pk_fma_f32 v[142:143], v[104:105], v[128:129], v[168:169]
	v_mul_f32_e32 v128, v133, v133
	v_mul_f32_e32 v129, v135, v135
	v_pk_fma_f32 v[140:141], v[106:107], v[130:131], v[170:171]
	v_fmac_f32_e32 v128, v132, v132
	v_fmac_f32_e32 v129, v134, v134
	v_add_f32_e32 v128, v128, v129
	v_mul_f32_e32 v129, v143, v143
	v_mul_f32_e32 v130, v141, v141
	v_fmac_f32_e32 v129, v142, v142
	v_fmac_f32_e32 v130, v140, v140
	v_add_f32_e32 v129, v129, v130
	v_add_f32_e32 v128, v128, v129
	v_add_f32_e32 v128, v174, v128
	v_mov_b32_e32 v129, v128
	s_nop 1
	v_permlane16_swap_b32 v129, v128
	v_add_u32_e32 v208, s80, v207
	v_ashrrev_i32_e32 v209, 31, v208
	v_lshlrev_b64 v[208:209], 11, v[208:209]
	v_lshl_add_u64 v[208:209], v[204:205], 0, v[208:209]
	s_waitcnt lgkmcnt(0)
	v_add_f32_e32 v128, v128, v129
	v_mov_b32_e32 v129, v128
	s_nop 1
	v_permlane32_swap_b32 v129, v128
	v_cvt_pk_bf16_f32 v138, v138, v139
	v_cvt_pk_bf16_f32 v139, v172, v173
	global_store_dwordx4 v[208:209], v[136:139], off
	v_cvt_pk_bf16_f32 v130, v132, v133
	v_cvt_pk_bf16_f32 v131, v134, v135
	v_cvt_pk_bf16_f32 v132, v142, v143
	v_cvt_pk_bf16_f32 v133, v140, v141
	global_store_dwordx4 v[208:209], v[130:133], off offset:256
	s_and_saveexec_b64 s[12:13], vcc
	s_cbranch_execz .LBB0_732
	s_waitcnt lgkmcnt(0)
	v_add_f32_e32 v128, v128, v129
	v_lshl_add_u32 v129, v207, 4, s79
	ds_write_b32 v129, v128
.LBB0_732:
	s_or_b64 exec, exec, s[12:13]
	v_add_u32_e32 v252, 0xa0, v207
	v_add_u32_e32 v252, s80, v252
	v_ashrrev_i32_e32 v253, 31, v252
	v_lshlrev_b64 v[252:253], 11, v[252:253]
	v_lshl_add_u64 v[252:253], v[204:205], 0, v[252:253]
	global_load_dwordx4 v[168:171], v[252:253], off
	global_load_dwordx4 v[172:175], v[252:253], off offset:256
	v_add_u32_e32 v252, 0xb0, v207
	v_add_u32_e32 v252, s80, v252
	v_ashrrev_i32_e32 v253, 31, v252
	v_lshlrev_b64 v[252:253], 11, v[252:253]
	v_lshl_add_u64 v[252:253], v[204:205], 0, v[252:253]
	global_load_dwordx4 v[208:211], v[252:253], off
	global_load_dwordx4 v[212:215], v[252:253], off offset:256
	ds_read_b32 v132, v206 offset:64
	v_lshlrev_b32_e32 v134, 16, v164
	v_and_b32_e32 v135, 0xffff0000, v164
	v_lshlrev_b32_e32 v136, 16, v165
	v_and_b32_e32 v137, 0xffff0000, v165
	s_waitcnt lgkmcnt(0)
	v_pk_mul_f32 v[118:119], v[118:119], v[132:133] op_sel_hi:[1,0]
	v_pk_mul_f32 v[116:117], v[116:117], v[132:133] op_sel_hi:[1,0]
	v_lshlrev_b32_e32 v138, 16, v166
	v_and_b32_e32 v139, 0xffff0000, v166
	v_lshlrev_b32_e32 v140, 16, v167
	v_and_b32_e32 v141, 0xffff0000, v167
	v_pk_fma_f32 v[118:119], v[126:127], v[118:119], v[136:137]
	v_pk_fma_f32 v[116:117], v[124:125], v[116:117], v[134:135]
	v_pk_mul_f32 v[114:115], v[114:115], v[132:133] op_sel_hi:[1,0]
	v_pk_mul_f32 v[112:113], v[112:113], v[132:133] op_sel_hi:[1,0]
	v_pk_fma_f32 v[134:135], v[122:123], v[114:115], v[140:141]
	v_pk_fma_f32 v[114:115], v[120:121], v[112:113], v[138:139]
	v_mul_f32_e32 v112, v117, v117
	v_mul_f32_e32 v113, v119, v119
	v_fmac_f32_e32 v112, v116, v116
	v_fmac_f32_e32 v113, v118, v118
	v_add_f32_e32 v112, v112, v113
	v_mul_f32_e32 v113, v115, v115
	v_mul_f32_e32 v129, v135, v135
	v_fmac_f32_e32 v113, v114, v114
	v_fmac_f32_e32 v129, v134, v134
	v_add_f32_e32 v113, v113, v129
	v_add_f32_e32 v129, v112, v113
	v_cvt_pk_bf16_f32 v112, v116, v117
	v_cvt_pk_bf16_f32 v113, v118, v119
	v_lshlrev_b32_e32 v116, 16, v160
	v_and_b32_e32 v117, 0xffff0000, v160
	v_lshlrev_b32_e32 v118, 16, v161
	v_and_b32_e32 v119, 0xffff0000, v161
	v_pk_mul_f32 v[102:103], v[102:103], v[132:133] op_sel_hi:[1,0]
	v_pk_mul_f32 v[100:101], v[100:101], v[132:133] op_sel_hi:[1,0]
	v_lshlrev_b32_e32 v136, 16, v162
	v_and_b32_e32 v137, 0xffff0000, v162
	v_pk_fma_f32 v[102:103], v[110:111], v[102:103], v[118:119]
	v_pk_fma_f32 v[100:101], v[108:109], v[100:101], v[116:117]
	v_pk_mul_f32 v[96:97], v[96:97], v[132:133] op_sel_hi:[1,0]
	v_lshlrev_b32_e32 v138, 16, v163
	v_and_b32_e32 v139, 0xffff0000, v163
	v_pk_mul_f32 v[98:99], v[98:99], v[132:133] op_sel_hi:[1,0]
	v_pk_fma_f32 v[118:119], v[104:105], v[96:97], v[136:137]
	v_mul_f32_e32 v96, v101, v101
	v_mul_f32_e32 v97, v103, v103
	v_pk_fma_f32 v[116:117], v[106:107], v[98:99], v[138:139]
	v_fmac_f32_e32 v96, v100, v100
	v_fmac_f32_e32 v97, v102, v102
	v_add_f32_e32 v96, v96, v97
	v_mul_f32_e32 v97, v119, v119
	v_mul_f32_e32 v98, v117, v117
	v_fmac_f32_e32 v97, v118, v118
	v_fmac_f32_e32 v98, v116, v116
	v_add_f32_e32 v97, v97, v98
	v_add_f32_e32 v96, v96, v97
	v_add_f32_e32 v96, v129, v96
	v_mov_b32_e32 v97, v96
	s_nop 1
	v_permlane16_swap_b32 v97, v96
	v_add_u32_e32 v128, 16, v207
	v_add_u32_e32 v130, s80, v128
	v_ashrrev_i32_e32 v131, 31, v130
	v_lshlrev_b64 v[130:131], 11, v[130:131]
	s_waitcnt lgkmcnt(0)
	v_add_f32_e32 v96, v96, v97
	v_mov_b32_e32 v97, v96
	s_nop 1
	v_permlane32_swap_b32 v97, v96
	v_lshl_add_u64 v[130:131], v[204:205], 0, v[130:131]
	v_cvt_pk_bf16_f32 v114, v114, v115
	v_cvt_pk_bf16_f32 v115, v134, v135
	global_store_dwordx4 v[130:131], v[112:115], off
	v_cvt_pk_bf16_f32 v98, v100, v101
	v_cvt_pk_bf16_f32 v99, v102, v103
	v_cvt_pk_bf16_f32 v100, v118, v119
	v_cvt_pk_bf16_f32 v101, v116, v117
	global_store_dwordx4 v[130:131], v[98:101], off offset:256
	s_and_saveexec_b64 s[12:13], vcc
	s_cbranch_execz .LBB0_734
	s_waitcnt lgkmcnt(0)
	v_add_f32_e32 v96, v96, v97
	v_lshl_add_u32 v97, v128, 4, s79
	ds_write_b32 v97, v96
.LBB0_734:
	s_or_b64 exec, exec, s[12:13]
	ds_read_b32 v100, v206 offset:128
	v_lshlrev_b32_e32 v102, 16, v156
	v_and_b32_e32 v103, 0xffff0000, v156
	v_lshlrev_b32_e32 v112, 16, v157
	v_and_b32_e32 v113, 0xffff0000, v157
	s_waitcnt lgkmcnt(0)
	v_pk_mul_f32 v[94:95], v[94:95], v[100:101] op_sel_hi:[1,0]
	v_pk_mul_f32 v[92:93], v[92:93], v[100:101] op_sel_hi:[1,0]
	v_lshlrev_b32_e32 v114, 16, v158
	v_and_b32_e32 v115, 0xffff0000, v158
	v_lshlrev_b32_e32 v116, 16, v159
	v_and_b32_e32 v117, 0xffff0000, v159
	v_pk_fma_f32 v[94:95], v[126:127], v[94:95], v[112:113]
	v_pk_fma_f32 v[92:93], v[124:125], v[92:93], v[102:103]
	v_pk_mul_f32 v[90:91], v[90:91], v[100:101] op_sel_hi:[1,0]
	v_pk_mul_f32 v[88:89], v[88:89], v[100:101] op_sel_hi:[1,0]
	v_pk_fma_f32 v[102:103], v[122:123], v[90:91], v[116:117]
	v_pk_fma_f32 v[90:91], v[120:121], v[88:89], v[114:115]
	v_mul_f32_e32 v88, v93, v93
	v_mul_f32_e32 v89, v95, v95
	v_fmac_f32_e32 v88, v92, v92
	v_fmac_f32_e32 v89, v94, v94
	v_add_f32_e32 v88, v88, v89
	v_mul_f32_e32 v89, v91, v91
	v_mul_f32_e32 v97, v103, v103
	v_fmac_f32_e32 v89, v90, v90
	v_fmac_f32_e32 v97, v102, v102
	v_add_f32_e32 v89, v89, v97
	v_add_f32_e32 v97, v88, v89
	v_cvt_pk_bf16_f32 v88, v92, v93
	v_cvt_pk_bf16_f32 v89, v94, v95
	v_lshlrev_b32_e32 v92, 16, v152
	v_and_b32_e32 v93, 0xffff0000, v152
	v_lshlrev_b32_e32 v94, 16, v153
	v_and_b32_e32 v95, 0xffff0000, v153
	v_pk_mul_f32 v[86:87], v[86:87], v[100:101] op_sel_hi:[1,0]
	v_pk_mul_f32 v[84:85], v[84:85], v[100:101] op_sel_hi:[1,0]
	v_lshlrev_b32_e32 v112, 16, v154
	v_and_b32_e32 v113, 0xffff0000, v154
	v_pk_fma_f32 v[86:87], v[110:111], v[86:87], v[94:95]
	v_pk_fma_f32 v[84:85], v[108:109], v[84:85], v[92:93]
	v_pk_mul_f32 v[80:81], v[80:81], v[100:101] op_sel_hi:[1,0]
	v_lshlrev_b32_e32 v114, 16, v155
	v_and_b32_e32 v115, 0xffff0000, v155
	v_pk_mul_f32 v[82:83], v[82:83], v[100:101] op_sel_hi:[1,0]
	v_pk_fma_f32 v[94:95], v[104:105], v[80:81], v[112:113]
	v_mul_f32_e32 v80, v85, v85
	v_mul_f32_e32 v81, v87, v87
	v_pk_fma_f32 v[92:93], v[106:107], v[82:83], v[114:115]
	v_fmac_f32_e32 v80, v84, v84
	v_fmac_f32_e32 v81, v86, v86
	v_add_f32_e32 v80, v80, v81
	v_mul_f32_e32 v81, v95, v95
	v_mul_f32_e32 v82, v93, v93
	v_fmac_f32_e32 v81, v94, v94
	v_fmac_f32_e32 v82, v92, v92
	v_add_f32_e32 v81, v81, v82
	v_add_f32_e32 v80, v80, v81
	v_add_f32_e32 v80, v97, v80
	v_mov_b32_e32 v81, v80
	s_nop 1
	v_permlane16_swap_b32 v81, v80
	v_add_u32_e32 v96, 32, v207
	v_add_u32_e32 v98, s80, v96
	v_ashrrev_i32_e32 v99, 31, v98
	v_lshlrev_b64 v[98:99], 11, v[98:99]
	s_waitcnt lgkmcnt(0)
	v_add_f32_e32 v80, v80, v81
	v_mov_b32_e32 v81, v80
	s_nop 1
	v_permlane32_swap_b32 v81, v80
	v_lshl_add_u64 v[98:99], v[204:205], 0, v[98:99]
	v_cvt_pk_bf16_f32 v90, v90, v91
	v_cvt_pk_bf16_f32 v91, v102, v103
	global_store_dwordx4 v[98:99], v[88:91], off
	v_cvt_pk_bf16_f32 v82, v84, v85
	v_cvt_pk_bf16_f32 v83, v86, v87
	v_cvt_pk_bf16_f32 v84, v94, v95
	v_cvt_pk_bf16_f32 v85, v92, v93
	global_store_dwordx4 v[98:99], v[82:85], off offset:256
	s_and_saveexec_b64 s[12:13], vcc
	s_cbranch_execz .LBB0_736
	s_waitcnt lgkmcnt(0)
	v_add_f32_e32 v80, v80, v81
	v_lshl_add_u32 v81, v96, 4, s79
	ds_write_b32 v81, v80
.LBB0_736:
	s_or_b64 exec, exec, s[12:13]
	ds_read_b32 v84, v206 offset:192
	v_lshlrev_b32_e32 v86, 16, v148
	v_and_b32_e32 v87, 0xffff0000, v148
	v_lshlrev_b32_e32 v88, 16, v149
	v_and_b32_e32 v89, 0xffff0000, v149
	s_waitcnt lgkmcnt(0)
	v_pk_mul_f32 v[78:79], v[78:79], v[84:85] op_sel_hi:[1,0]
	v_pk_mul_f32 v[76:77], v[76:77], v[84:85] op_sel_hi:[1,0]
	v_lshlrev_b32_e32 v90, 16, v150
	v_and_b32_e32 v91, 0xffff0000, v150
	v_lshlrev_b32_e32 v92, 16, v151
	v_and_b32_e32 v93, 0xffff0000, v151
	v_pk_fma_f32 v[78:79], v[126:127], v[78:79], v[88:89]
	v_pk_fma_f32 v[76:77], v[124:125], v[76:77], v[86:87]
	v_pk_mul_f32 v[74:75], v[74:75], v[84:85] op_sel_hi:[1,0]
	v_pk_mul_f32 v[72:73], v[72:73], v[84:85] op_sel_hi:[1,0]
	v_pk_fma_f32 v[86:87], v[122:123], v[74:75], v[92:93]
	v_pk_fma_f32 v[74:75], v[120:121], v[72:73], v[90:91]
	v_mul_f32_e32 v72, v77, v77
	v_mul_f32_e32 v73, v79, v79
	v_fmac_f32_e32 v72, v76, v76
	v_fmac_f32_e32 v73, v78, v78
	v_add_f32_e32 v72, v72, v73
	v_mul_f32_e32 v73, v75, v75
	v_mul_f32_e32 v81, v87, v87
	v_fmac_f32_e32 v73, v74, v74
	v_fmac_f32_e32 v81, v86, v86
	v_add_f32_e32 v73, v73, v81
	v_add_f32_e32 v81, v72, v73
	v_cvt_pk_bf16_f32 v72, v76, v77
	v_cvt_pk_bf16_f32 v73, v78, v79
	v_lshlrev_b32_e32 v76, 16, v144
	v_and_b32_e32 v77, 0xffff0000, v144
	v_lshlrev_b32_e32 v78, 16, v145
	v_and_b32_e32 v79, 0xffff0000, v145
	v_pk_mul_f32 v[70:71], v[70:71], v[84:85] op_sel_hi:[1,0]
	v_pk_mul_f32 v[68:69], v[68:69], v[84:85] op_sel_hi:[1,0]
	v_lshlrev_b32_e32 v88, 16, v146
	v_and_b32_e32 v89, 0xffff0000, v146
	v_pk_fma_f32 v[70:71], v[110:111], v[70:71], v[78:79]
	v_pk_fma_f32 v[68:69], v[108:109], v[68:69], v[76:77]
	v_pk_mul_f32 v[64:65], v[64:65], v[84:85] op_sel_hi:[1,0]
	v_lshlrev_b32_e32 v90, 16, v147
	v_and_b32_e32 v91, 0xffff0000, v147
	v_pk_mul_f32 v[66:67], v[66:67], v[84:85] op_sel_hi:[1,0]
	v_pk_fma_f32 v[78:79], v[104:105], v[64:65], v[88:89]
	v_mul_f32_e32 v64, v69, v69
	v_mul_f32_e32 v65, v71, v71
	v_pk_fma_f32 v[76:77], v[106:107], v[66:67], v[90:91]
	v_fmac_f32_e32 v64, v68, v68
	v_fmac_f32_e32 v65, v70, v70
	v_add_f32_e32 v64, v64, v65
	v_mul_f32_e32 v65, v79, v79
	v_mul_f32_e32 v66, v77, v77
	v_fmac_f32_e32 v65, v78, v78
	v_fmac_f32_e32 v66, v76, v76
	v_add_f32_e32 v65, v65, v66
	v_add_f32_e32 v64, v64, v65
	v_add_f32_e32 v64, v81, v64
	v_mov_b32_e32 v65, v64
	s_nop 1
	v_permlane16_swap_b32 v65, v64
	v_add_u32_e32 v80, 48, v207
	v_add_u32_e32 v82, s80, v80
	v_ashrrev_i32_e32 v83, 31, v82
	v_lshlrev_b64 v[82:83], 11, v[82:83]
	s_waitcnt lgkmcnt(0)
	v_add_f32_e32 v64, v64, v65
	v_mov_b32_e32 v65, v64
	s_nop 1
	v_permlane32_swap_b32 v65, v64
	v_lshl_add_u64 v[82:83], v[204:205], 0, v[82:83]
	v_cvt_pk_bf16_f32 v74, v74, v75
	v_cvt_pk_bf16_f32 v75, v86, v87
	global_store_dwordx4 v[82:83], v[72:75], off
	v_cvt_pk_bf16_f32 v66, v68, v69
	v_cvt_pk_bf16_f32 v67, v70, v71
	v_cvt_pk_bf16_f32 v68, v78, v79
	v_cvt_pk_bf16_f32 v69, v76, v77
	global_store_dwordx4 v[82:83], v[66:69], off offset:256
	s_and_saveexec_b64 s[12:13], vcc
	s_cbranch_execz .LBB0_738
	s_waitcnt lgkmcnt(0)
	v_add_f32_e32 v64, v64, v65
	v_lshl_add_u32 v65, v80, 4, s79
	ds_write_b32 v65, v64
.LBB0_738:
	s_or_b64 exec, exec, s[12:13]
	v_add_u32_e32 v64, 0x80, v207
	v_add_u32_e32 v66, s80, v64
	v_ashrrev_i32_e32 v67, 31, v66
	v_lshlrev_b64 v[66:67], 11, v[66:67]
	v_lshl_add_u64 v[70:71], v[204:205], 0, v[66:67]
	ds_read_b32 v72, v206 offset:512
	s_waitcnt lgkmcnt(0)
	v_pk_mul_f32 v[62:63], v[62:63], v[72:73] op_sel_hi:[1,0]
	v_pk_mul_f32 v[60:61], v[60:61], v[72:73] op_sel_hi:[1,0]
	v_pk_mul_f32 v[58:59], v[58:59], v[72:73] op_sel_hi:[1,0]
	v_pk_mul_f32 v[56:57], v[56:57], v[72:73] op_sel_hi:[1,0]
	v_pk_mul_f32 v[54:55], v[54:55], v[72:73] op_sel_hi:[1,0]
	v_pk_mul_f32 v[52:53], v[52:53], v[72:73] op_sel_hi:[1,0]
	v_pk_mul_f32 v[50:51], v[50:51], v[72:73] op_sel_hi:[1,0]
	v_pk_mul_f32 v[48:49], v[48:49], v[72:73] op_sel_hi:[1,0]
	v_lshlrev_b32_e32 v74, 16, v236
	v_and_b32_e32 v75, 0xffff0000, v236
	v_lshlrev_b32_e32 v66, 16, v237
	v_and_b32_e32 v67, 0xffff0000, v237
	v_lshlrev_b32_e32 v76, 16, v238
	v_and_b32_e32 v77, 0xffff0000, v238
	v_lshlrev_b32_e32 v68, 16, v239
	v_and_b32_e32 v69, 0xffff0000, v239
	v_pk_fma_f32 v[66:67], v[126:127], v[62:63], v[66:67]
	v_pk_fma_f32 v[74:75], v[124:125], v[60:61], v[74:75]
	v_pk_fma_f32 v[68:69], v[122:123], v[58:59], v[68:69]
	v_pk_fma_f32 v[76:77], v[120:121], v[56:57], v[76:77]
	v_cvt_pk_bf16_f32 v56, v74, v75
	v_cvt_pk_bf16_f32 v57, v66, v67
	v_mul_f32_e32 v65, v75, v75
	v_cvt_pk_bf16_f32 v58, v76, v77
	v_cvt_pk_bf16_f32 v59, v68, v69
	v_mul_f32_e32 v67, v67, v67
	v_mul_f32_e32 v72, v77, v77
	v_mul_f32_e32 v69, v69, v69
	v_fmac_f32_e32 v65, v74, v74
	v_fmac_f32_e32 v67, v66, v66
	v_fmac_f32_e32 v72, v76, v76
	v_fmac_f32_e32 v69, v68, v68
	v_add_f32_e32 v65, v65, v67
	v_add_f32_e32 v66, v72, v69
	v_add_f32_e32 v65, v65, v66
	global_store_dwordx4 v[70:71], v[56:59], off
	v_lshlrev_b32_e32 v66, 16, v240
	v_and_b32_e32 v67, 0xffff0000, v240
	v_lshlrev_b32_e32 v60, 16, v241
	v_and_b32_e32 v61, 0xffff0000, v241
	v_lshlrev_b32_e32 v68, 16, v242
	v_and_b32_e32 v69, 0xffff0000, v242
	v_lshlrev_b32_e32 v62, 16, v243
	v_and_b32_e32 v63, 0xffff0000, v243
	v_pk_fma_f32 v[54:55], v[110:111], v[54:55], v[60:61]
	v_pk_fma_f32 v[52:53], v[108:109], v[52:53], v[66:67]
	v_pk_fma_f32 v[60:61], v[106:107], v[50:51], v[62:63]
	v_pk_fma_f32 v[62:63], v[104:105], v[48:49], v[68:69]
	v_mul_f32_e32 v48, v53, v53
	v_mul_f32_e32 v49, v55, v55
	v_mul_f32_e32 v50, v63, v63
	v_mul_f32_e32 v51, v61, v61
	v_fmac_f32_e32 v48, v52, v52
	v_fmac_f32_e32 v49, v54, v54
	v_fmac_f32_e32 v50, v62, v62
	v_fmac_f32_e32 v51, v60, v60
	v_add_f32_e32 v48, v48, v49
	v_add_f32_e32 v49, v50, v51
	v_add_f32_e32 v48, v48, v49
	v_add_f32_e32 v48, v65, v48
	v_mov_b32_e32 v49, v48
	s_nop 1
	v_permlane16_swap_b32 v49, v48
	v_cvt_pk_bf16_f32 v50, v52, v53
	v_cvt_pk_bf16_f32 v51, v54, v55
	v_cvt_pk_bf16_f32 v52, v62, v63
	v_cvt_pk_bf16_f32 v53, v60, v61
	s_waitcnt lgkmcnt(0)
	v_add_f32_e32 v48, v48, v49
	v_mov_b32_e32 v49, v48
	s_nop 1
	v_permlane32_swap_b32 v49, v48
	global_store_dwordx4 v[70:71], v[50:53], off offset:256
	s_and_saveexec_b64 s[12:13], vcc
	s_cbranch_execz .LBB0_740
	s_waitcnt lgkmcnt(0)
	v_add_f32_e32 v48, v48, v49
	v_lshl_add_u32 v49, v64, 4, s79
	ds_write_b32 v49, v48
.LBB0_740:
	s_or_b64 exec, exec, s[12:13]
	v_add_u32_e32 v48, 0x90, v207
	v_add_u32_e32 v50, s80, v48
	v_ashrrev_i32_e32 v51, 31, v50
	v_lshlrev_b64 v[50:51], 11, v[50:51]
	v_lshl_add_u64 v[54:55], v[204:205], 0, v[50:51]
	ds_read_b32 v56, v206 offset:576
	s_waitcnt lgkmcnt(0)
	v_pk_mul_f32 v[46:47], v[46:47], v[56:57] op_sel_hi:[1,0]
	v_pk_mul_f32 v[44:45], v[44:45], v[56:57] op_sel_hi:[1,0]
	v_pk_mul_f32 v[42:43], v[42:43], v[56:57] op_sel_hi:[1,0]
	v_pk_mul_f32 v[40:41], v[40:41], v[56:57] op_sel_hi:[1,0]
	v_pk_mul_f32 v[38:39], v[38:39], v[56:57] op_sel_hi:[1,0]
	v_pk_mul_f32 v[36:37], v[36:37], v[56:57] op_sel_hi:[1,0]
	v_pk_mul_f32 v[34:35], v[34:35], v[56:57] op_sel_hi:[1,0]
	v_pk_mul_f32 v[32:33], v[32:33], v[56:57] op_sel_hi:[1,0]
	v_lshlrev_b32_e32 v58, 16, v244
	v_and_b32_e32 v59, 0xffff0000, v244
	v_lshlrev_b32_e32 v50, 16, v245
	v_and_b32_e32 v51, 0xffff0000, v245
	v_lshlrev_b32_e32 v60, 16, v246
	v_and_b32_e32 v61, 0xffff0000, v246
	v_lshlrev_b32_e32 v52, 16, v247
	v_and_b32_e32 v53, 0xffff0000, v247
	v_pk_fma_f32 v[50:51], v[126:127], v[46:47], v[50:51]
	v_pk_fma_f32 v[58:59], v[124:125], v[44:45], v[58:59]
	v_pk_fma_f32 v[52:53], v[122:123], v[42:43], v[52:53]
	v_pk_fma_f32 v[60:61], v[120:121], v[40:41], v[60:61]
	v_cvt_pk_bf16_f32 v40, v58, v59
	v_cvt_pk_bf16_f32 v41, v50, v51
	v_mul_f32_e32 v49, v59, v59
	v_cvt_pk_bf16_f32 v42, v60, v61
	v_cvt_pk_bf16_f32 v43, v52, v53
	v_mul_f32_e32 v51, v51, v51
	v_mul_f32_e32 v56, v61, v61
	v_mul_f32_e32 v53, v53, v53
	v_fmac_f32_e32 v49, v58, v58
	v_fmac_f32_e32 v51, v50, v50
	v_fmac_f32_e32 v56, v60, v60
	v_fmac_f32_e32 v53, v52, v52
	v_add_f32_e32 v49, v49, v51
	v_add_f32_e32 v50, v56, v53
	v_add_f32_e32 v49, v49, v50
	global_store_dwordx4 v[54:55], v[40:43], off
	v_lshlrev_b32_e32 v50, 16, v248
	v_and_b32_e32 v51, 0xffff0000, v248
	v_lshlrev_b32_e32 v44, 16, v249
	v_and_b32_e32 v45, 0xffff0000, v249
	v_lshlrev_b32_e32 v52, 16, v250
	v_and_b32_e32 v53, 0xffff0000, v250
	v_lshlrev_b32_e32 v46, 16, v251
	v_and_b32_e32 v47, 0xffff0000, v251
	v_pk_fma_f32 v[38:39], v[110:111], v[38:39], v[44:45]
	v_pk_fma_f32 v[36:37], v[108:109], v[36:37], v[50:51]
	v_pk_fma_f32 v[44:45], v[106:107], v[34:35], v[46:47]
	v_pk_fma_f32 v[46:47], v[104:105], v[32:33], v[52:53]
	v_mul_f32_e32 v32, v37, v37
	v_mul_f32_e32 v33, v39, v39
	v_mul_f32_e32 v34, v47, v47
	v_mul_f32_e32 v35, v45, v45
	v_fmac_f32_e32 v32, v36, v36
	v_fmac_f32_e32 v33, v38, v38
	v_fmac_f32_e32 v34, v46, v46
	v_fmac_f32_e32 v35, v44, v44
	v_add_f32_e32 v32, v32, v33
	v_add_f32_e32 v33, v34, v35
	v_add_f32_e32 v32, v32, v33
	v_add_f32_e32 v32, v49, v32
	v_mov_b32_e32 v33, v32
	s_nop 1
	v_permlane16_swap_b32 v33, v32
	v_cvt_pk_bf16_f32 v34, v36, v37
	v_cvt_pk_bf16_f32 v35, v38, v39
	v_cvt_pk_bf16_f32 v36, v46, v47
	v_cvt_pk_bf16_f32 v37, v44, v45
	s_waitcnt lgkmcnt(0)
	v_add_f32_e32 v32, v32, v33
	v_mov_b32_e32 v33, v32
	s_nop 1
	v_permlane32_swap_b32 v33, v32
	global_store_dwordx4 v[54:55], v[34:37], off offset:256
	s_and_saveexec_b64 s[12:13], vcc
	s_cbranch_execz .LBB0_742
	s_waitcnt lgkmcnt(0)
	v_add_f32_e32 v32, v32, v33
	v_lshl_add_u32 v33, v48, 4, s79
	ds_write_b32 v33, v32
.LBB0_742:
	s_or_b64 exec, exec, s[12:13]
	v_add_u32_e32 v32, 0xa0, v207
	v_add_u32_e32 v34, s80, v32
	v_ashrrev_i32_e32 v35, 31, v34
	v_lshlrev_b64 v[34:35], 11, v[34:35]
	v_lshl_add_u64 v[38:39], v[204:205], 0, v[34:35]
	ds_read_b32 v40, v206 offset:640
	s_waitcnt lgkmcnt(0)
	v_pk_mul_f32 v[30:31], v[30:31], v[40:41] op_sel_hi:[1,0]
	v_pk_mul_f32 v[28:29], v[28:29], v[40:41] op_sel_hi:[1,0]
	v_pk_mul_f32 v[26:27], v[26:27], v[40:41] op_sel_hi:[1,0]
	v_pk_mul_f32 v[24:25], v[24:25], v[40:41] op_sel_hi:[1,0]
	v_pk_mul_f32 v[22:23], v[22:23], v[40:41] op_sel_hi:[1,0]
	v_pk_mul_f32 v[20:21], v[20:21], v[40:41] op_sel_hi:[1,0]
	v_pk_mul_f32 v[18:19], v[18:19], v[40:41] op_sel_hi:[1,0]
	v_pk_mul_f32 v[16:17], v[16:17], v[40:41] op_sel_hi:[1,0]
	s_waitcnt vmcnt(13)
	v_lshlrev_b32_e32 v42, 16, v168
	v_and_b32_e32 v43, 0xffff0000, v168
	v_lshlrev_b32_e32 v34, 16, v169
	v_and_b32_e32 v35, 0xffff0000, v169
	v_lshlrev_b32_e32 v44, 16, v170
	v_and_b32_e32 v45, 0xffff0000, v170
	v_lshlrev_b32_e32 v36, 16, v171
	v_and_b32_e32 v37, 0xffff0000, v171
	v_pk_fma_f32 v[34:35], v[126:127], v[30:31], v[34:35]
	v_pk_fma_f32 v[42:43], v[124:125], v[28:29], v[42:43]
	v_pk_fma_f32 v[36:37], v[122:123], v[26:27], v[36:37]
	v_pk_fma_f32 v[44:45], v[120:121], v[24:25], v[44:45]
	v_cvt_pk_bf16_f32 v24, v42, v43
	v_cvt_pk_bf16_f32 v25, v34, v35
	v_mul_f32_e32 v33, v43, v43
	v_cvt_pk_bf16_f32 v26, v44, v45
	v_cvt_pk_bf16_f32 v27, v36, v37
	v_mul_f32_e32 v35, v35, v35
	v_mul_f32_e32 v40, v45, v45
	v_mul_f32_e32 v37, v37, v37
	v_fmac_f32_e32 v33, v42, v42
	v_fmac_f32_e32 v35, v34, v34
	v_fmac_f32_e32 v40, v44, v44
	v_fmac_f32_e32 v37, v36, v36
	v_add_f32_e32 v33, v33, v35
	v_add_f32_e32 v34, v40, v37
	v_add_f32_e32 v33, v33, v34
	global_store_dwordx4 v[38:39], v[24:27], off
	s_waitcnt vmcnt(13)
	v_lshlrev_b32_e32 v34, 16, v172
	v_and_b32_e32 v35, 0xffff0000, v172
	v_lshlrev_b32_e32 v28, 16, v173
	v_and_b32_e32 v29, 0xffff0000, v173
	v_lshlrev_b32_e32 v36, 16, v174
	v_and_b32_e32 v37, 0xffff0000, v174
	v_lshlrev_b32_e32 v30, 16, v175
	v_and_b32_e32 v31, 0xffff0000, v175
	v_pk_fma_f32 v[22:23], v[110:111], v[22:23], v[28:29]
	v_pk_fma_f32 v[20:21], v[108:109], v[20:21], v[34:35]
	v_pk_fma_f32 v[28:29], v[106:107], v[18:19], v[30:31]
	v_pk_fma_f32 v[30:31], v[104:105], v[16:17], v[36:37]
	v_mul_f32_e32 v16, v21, v21
	v_mul_f32_e32 v17, v23, v23
	v_mul_f32_e32 v18, v31, v31
	v_mul_f32_e32 v19, v29, v29
	v_fmac_f32_e32 v16, v20, v20
	v_fmac_f32_e32 v17, v22, v22
	v_fmac_f32_e32 v18, v30, v30
	v_fmac_f32_e32 v19, v28, v28
	v_add_f32_e32 v16, v16, v17
	v_add_f32_e32 v17, v18, v19
	v_add_f32_e32 v16, v16, v17
	v_add_f32_e32 v16, v33, v16
	v_mov_b32_e32 v17, v16
	s_nop 1
	v_permlane16_swap_b32 v17, v16
	v_cvt_pk_bf16_f32 v18, v20, v21
	v_cvt_pk_bf16_f32 v19, v22, v23
	v_cvt_pk_bf16_f32 v20, v30, v31
	v_cvt_pk_bf16_f32 v21, v28, v29
	s_waitcnt lgkmcnt(0)
	v_add_f32_e32 v16, v16, v17
	v_mov_b32_e32 v17, v16
	s_nop 1
	v_permlane32_swap_b32 v17, v16
	global_store_dwordx4 v[38:39], v[18:21], off offset:256
	s_and_saveexec_b64 s[12:13], vcc
	s_cbranch_execz .LBB0_744
	s_waitcnt lgkmcnt(0)
	v_add_f32_e32 v16, v16, v17
	v_lshl_add_u32 v17, v32, 4, s79
	ds_write_b32 v17, v16
.LBB0_744:
	s_or_b64 exec, exec, s[12:13]
	v_add_u32_e32 v16, 0xb0, v207
	v_add_u32_e32 v18, s80, v16
	v_ashrrev_i32_e32 v19, 31, v18
	v_lshlrev_b64 v[18:19], 11, v[18:19]
	v_lshl_add_u64 v[22:23], v[204:205], 0, v[18:19]
	ds_read_b32 v24, v206 offset:704
	s_waitcnt lgkmcnt(0)
	v_pk_mul_f32 v[14:15], v[14:15], v[24:25] op_sel_hi:[1,0]
	v_pk_mul_f32 v[12:13], v[12:13], v[24:25] op_sel_hi:[1,0]
	v_pk_mul_f32 v[10:11], v[10:11], v[24:25] op_sel_hi:[1,0]
	v_pk_mul_f32 v[8:9], v[8:9], v[24:25] op_sel_hi:[1,0]
	v_pk_mul_f32 v[6:7], v[6:7], v[24:25] op_sel_hi:[1,0]
	v_pk_mul_f32 v[4:5], v[4:5], v[24:25] op_sel_hi:[1,0]
	v_pk_mul_f32 v[2:3], v[2:3], v[24:25] op_sel_hi:[1,0]
	v_pk_mul_f32 v[0:1], v[0:1], v[24:25] op_sel_hi:[1,0]
	s_waitcnt vmcnt(13)
	v_lshlrev_b32_e32 v26, 16, v208
	v_and_b32_e32 v27, 0xffff0000, v208
	v_lshlrev_b32_e32 v18, 16, v209
	v_and_b32_e32 v19, 0xffff0000, v209
	v_lshlrev_b32_e32 v28, 16, v210
	v_and_b32_e32 v29, 0xffff0000, v210
	v_lshlrev_b32_e32 v20, 16, v211
	v_and_b32_e32 v21, 0xffff0000, v211
	v_pk_fma_f32 v[18:19], v[126:127], v[14:15], v[18:19]
	v_pk_fma_f32 v[26:27], v[124:125], v[12:13], v[26:27]
	v_pk_fma_f32 v[20:21], v[122:123], v[10:11], v[20:21]
	v_pk_fma_f32 v[28:29], v[120:121], v[8:9], v[28:29]
	v_cvt_pk_bf16_f32 v8, v26, v27
	v_cvt_pk_bf16_f32 v9, v18, v19
	v_mul_f32_e32 v17, v27, v27
	v_cvt_pk_bf16_f32 v10, v28, v29
	v_cvt_pk_bf16_f32 v11, v20, v21
	v_mul_f32_e32 v19, v19, v19
	v_mul_f32_e32 v24, v29, v29
	v_mul_f32_e32 v21, v21, v21
	v_fmac_f32_e32 v17, v26, v26
	v_fmac_f32_e32 v19, v18, v18
	v_fmac_f32_e32 v24, v28, v28
	v_fmac_f32_e32 v21, v20, v20
	v_add_f32_e32 v17, v17, v19
	v_add_f32_e32 v18, v24, v21
	v_add_f32_e32 v17, v17, v18
	global_store_dwordx4 v[22:23], v[8:11], off
	s_waitcnt vmcnt(13)
	v_lshlrev_b32_e32 v18, 16, v212
	v_and_b32_e32 v19, 0xffff0000, v212
	v_lshlrev_b32_e32 v12, 16, v213
	v_and_b32_e32 v13, 0xffff0000, v213
	v_lshlrev_b32_e32 v20, 16, v214
	v_and_b32_e32 v21, 0xffff0000, v214
	v_lshlrev_b32_e32 v14, 16, v215
	v_and_b32_e32 v15, 0xffff0000, v215
	v_pk_fma_f32 v[6:7], v[110:111], v[6:7], v[12:13]
	v_pk_fma_f32 v[4:5], v[108:109], v[4:5], v[18:19]
	v_pk_fma_f32 v[12:13], v[106:107], v[2:3], v[14:15]
	v_pk_fma_f32 v[14:15], v[104:105], v[0:1], v[20:21]
	v_mul_f32_e32 v0, v5, v5
	v_mul_f32_e32 v1, v7, v7
	v_mul_f32_e32 v2, v15, v15
	v_mul_f32_e32 v3, v13, v13
	v_fmac_f32_e32 v0, v4, v4
	v_fmac_f32_e32 v1, v6, v6
	v_fmac_f32_e32 v2, v14, v14
	v_fmac_f32_e32 v3, v12, v12
	v_add_f32_e32 v0, v0, v1
	v_add_f32_e32 v1, v2, v3
	v_add_f32_e32 v0, v0, v1
	v_add_f32_e32 v0, v17, v0
	v_mov_b32_e32 v1, v0
	s_nop 1
	v_permlane16_swap_b32 v1, v0
	v_cvt_pk_bf16_f32 v2, v4, v5
	v_cvt_pk_bf16_f32 v3, v6, v7
	v_cvt_pk_bf16_f32 v4, v14, v15
	v_cvt_pk_bf16_f32 v5, v12, v13
	s_waitcnt lgkmcnt(0)
	v_add_f32_e32 v0, v0, v1
	v_mov_b32_e32 v1, v0
	s_nop 1
	v_permlane32_swap_b32 v1, v0
	global_store_dwordx4 v[22:23], v[2:5], off offset:256
	s_and_saveexec_b64 s[12:13], vcc
	s_cbranch_execz .LBB0_746
	s_waitcnt lgkmcnt(0)
	v_add_f32_e32 v0, v0, v1
	v_lshl_add_u32 v1, v16, 4, s79
	ds_write_b32 v1, v0

.LBB0_887:
	s_mov_b32 s40, s67
	v_mov_b32_e32 v206, v220
	s_mov_b32 s41, s64
	v_mov_b32_e32 v233, v219
	s_mov_b64 s[10:11], s[0:1]
	v_and_b32_e32 v107, 64, v226
	v_mov_b64_e32 v[104:105], s[10:11]
	flat_load_dwordx2 v[202:203], v[104:105] offset:216
	s_nop 0
	flat_load_dwordx2 v[104:105], v[104:105] offset:32
	v_xor_b32_e32 v106, 16, v226
	v_add_u32_e32 v107, 64, v107
	v_cmp_lt_i32_e32 vcc, v106, v107
	v_mul_f32_e32 v108, v143, v143
	v_fmac_f32_e32 v108, v142, v142
	v_cndmask_b32_e32 v106, v226, v106, vcc
	v_lshlrev_b32_e32 v230, 2, v106
	v_mul_f32_e32 v106, v141, v141
	v_fmac_f32_e32 v106, v140, v140
	v_add_f32_e32 v106, v106, v108
	v_mul_f32_e32 v108, v137, v137
	v_mul_f32_e32 v109, v139, v139
	v_fmac_f32_e32 v108, v136, v136
	v_fmac_f32_e32 v109, v138, v138
	v_add_f32_e32 v108, v108, v109
	v_add_f32_e32 v106, v106, v108
	v_mul_f32_e32 v108, v133, v133
	v_mul_f32_e32 v109, v135, v135
	v_fmac_f32_e32 v108, v132, v132
	v_fmac_f32_e32 v109, v134, v134
	v_add_f32_e32 v108, v108, v109
	v_add_f32_e32 v106, v106, v108
	v_mul_f32_e32 v108, v129, v129
	v_mul_f32_e32 v109, v131, v131
	v_fmac_f32_e32 v108, v128, v128
	v_fmac_f32_e32 v109, v130, v130
	v_add_f32_e32 v108, v108, v109
	v_add_f32_e32 v106, v106, v108
	v_mov_b32_e32 v108, v106
	s_nop 1
	v_permlane16_swap_b32 v108, v106
	v_xor_b32_e32 v109, 32, v226
	v_cmp_lt_i32_e32 vcc, v109, v107
	s_lshl_b32 s81, s40, 2
	v_cmp_eq_u32_e64 s[10:11], 0, v206
	v_cndmask_b32_e32 v107, v226, v109, vcc
	v_lshlrev_b32_e32 v231, 2, v107
	s_waitcnt lgkmcnt(0)
	v_add_f32_e32 v106, v106, v108
	v_mov_b32_e32 v107, v106
	s_nop 1
	v_permlane32_swap_b32 v107, v106
	s_add_i32 s81, s81, 0x20400
	s_and_saveexec_b64 s[12:13], s[10:11]
	s_cbranch_execz .LBB0_889
	s_lshl_b32 s50, s41, 10
	s_add_i32 s50, s81, s50
	v_lshl_add_u32 v108, v233, 4, s50
	s_waitcnt lgkmcnt(0)
	v_add_f32_e32 v106, v106, v107
	ds_write_b32 v108, v106
.LBB0_889:
	s_or_b64 exec, exec, s[12:13]
	v_mul_f32_e32 v106, v117, v117
	s_waitcnt lgkmcnt(0)
	v_mul_f32_e32 v107, v119, v119
	v_fmac_f32_e32 v106, v116, v116
	v_fmac_f32_e32 v107, v118, v118
	v_add_f32_e32 v106, v106, v107
	v_mul_f32_e32 v107, v113, v113
	v_mul_f32_e32 v108, v115, v115
	v_fmac_f32_e32 v107, v112, v112
	v_fmac_f32_e32 v108, v114, v114
	v_add_f32_e32 v107, v107, v108
	v_add_f32_e32 v106, v106, v107
	v_mul_f32_e32 v107, v101, v101
	v_mul_f32_e32 v108, v103, v103
	v_fmac_f32_e32 v107, v100, v100
	v_fmac_f32_e32 v108, v102, v102
	v_add_f32_e32 v107, v107, v108
	v_add_f32_e32 v106, v106, v107
	v_mul_f32_e32 v107, v97, v97
	v_mul_f32_e32 v108, v99, v99
	v_fmac_f32_e32 v107, v96, v96
	v_fmac_f32_e32 v108, v98, v98
	v_add_f32_e32 v107, v107, v108
	v_add_f32_e32 v106, v106, v107
	v_mov_b32_e32 v107, v106
	s_nop 1
	v_permlane16_swap_b32 v107, v106
	s_waitcnt lgkmcnt(0)
	v_add_f32_e32 v106, v106, v107
	v_mov_b32_e32 v107, v106
	s_nop 1
	v_permlane32_swap_b32 v107, v106
	s_and_saveexec_b64 s[12:13], s[10:11]
	s_cbranch_execz .LBB0_891
	s_lshl_b32 s50, s41, 10
	s_add_i32 s50, s81, s50
	v_lshl_add_u32 v108, v233, 4, s50
	s_waitcnt lgkmcnt(0)
	v_add_f32_e32 v106, v106, v107
	ds_write_b32 v108, v106 offset:256
.LBB0_891:
	s_or_b64 exec, exec, s[12:13]
	v_mul_f32_e32 v106, v93, v93
	s_waitcnt lgkmcnt(0)
	v_mul_f32_e32 v107, v95, v95
	v_fmac_f32_e32 v106, v92, v92
	v_fmac_f32_e32 v107, v94, v94
	v_add_f32_e32 v106, v106, v107
	v_mul_f32_e32 v107, v89, v89
	v_mul_f32_e32 v108, v91, v91
	v_fmac_f32_e32 v107, v88, v88
	v_fmac_f32_e32 v108, v90, v90
	v_add_f32_e32 v107, v107, v108
	v_add_f32_e32 v106, v106, v107
	v_mul_f32_e32 v107, v85, v85
	v_mul_f32_e32 v108, v87, v87
	v_fmac_f32_e32 v107, v84, v84
	v_fmac_f32_e32 v108, v86, v86
	v_add_f32_e32 v107, v107, v108
	v_add_f32_e32 v106, v106, v107
	v_mul_f32_e32 v107, v81, v81
	v_mul_f32_e32 v108, v83, v83
	v_fmac_f32_e32 v107, v80, v80
	v_fmac_f32_e32 v108, v82, v82
	v_add_f32_e32 v107, v107, v108
	v_add_f32_e32 v106, v106, v107
	v_mov_b32_e32 v107, v106
	s_nop 1
	v_permlane16_swap_b32 v107, v106
	s_waitcnt lgkmcnt(0)
	v_add_f32_e32 v106, v106, v107
	v_mov_b32_e32 v107, v106
	s_nop 1
	v_permlane32_swap_b32 v107, v106
	s_and_saveexec_b64 s[12:13], s[10:11]
	s_cbranch_execz .LBB0_893
	s_lshl_b32 s50, s41, 10
	s_add_i32 s50, s81, s50
	v_lshl_add_u32 v108, v233, 4, s50
	s_waitcnt lgkmcnt(0)
	v_add_f32_e32 v106, v106, v107
	ds_write_b32 v108, v106 offset:512
.LBB0_893:
	s_or_b64 exec, exec, s[12:13]
	v_mul_f32_e32 v106, v77, v77
	s_waitcnt lgkmcnt(0)
	v_mul_f32_e32 v107, v79, v79
	v_fmac_f32_e32 v106, v76, v76
	v_fmac_f32_e32 v107, v78, v78
	v_add_f32_e32 v106, v106, v107
	v_mul_f32_e32 v107, v73, v73
	v_mul_f32_e32 v108, v75, v75
	v_fmac_f32_e32 v107, v72, v72
	v_fmac_f32_e32 v108, v74, v74
	v_add_f32_e32 v107, v107, v108
	v_add_f32_e32 v106, v106, v107
	v_mul_f32_e32 v107, v69, v69
	v_mul_f32_e32 v108, v71, v71
	v_fmac_f32_e32 v107, v68, v68
	v_fmac_f32_e32 v108, v70, v70
	v_add_f32_e32 v107, v107, v108
	v_add_f32_e32 v106, v106, v107
	v_mul_f32_e32 v107, v65, v65
	v_mul_f32_e32 v108, v67, v67
	v_fmac_f32_e32 v107, v64, v64
	v_fmac_f32_e32 v108, v66, v66
	v_add_f32_e32 v107, v107, v108
	v_add_f32_e32 v106, v106, v107
	v_mov_b32_e32 v107, v106
	s_nop 1
	v_permlane16_swap_b32 v107, v106
	s_waitcnt lgkmcnt(0)
	v_add_f32_e32 v106, v106, v107
	v_mov_b32_e32 v107, v106
	s_nop 1
	v_permlane32_swap_b32 v107, v106
	s_and_saveexec_b64 s[12:13], s[10:11]
	s_cbranch_execz .LBB0_895
	s_lshl_b32 s50, s41, 10
	s_add_i32 s50, s81, s50
	v_lshl_add_u32 v108, v233, 4, s50
	s_waitcnt lgkmcnt(0)
	v_add_f32_e32 v106, v106, v107
	ds_write_b32 v108, v106 offset:768
.LBB0_895:
	s_or_b64 exec, exec, s[12:13]
	v_mul_f32_e32 v106, v61, v61
	s_waitcnt lgkmcnt(0)
	v_mul_f32_e32 v107, v63, v63
	v_fmac_f32_e32 v106, v60, v60
	v_fmac_f32_e32 v107, v62, v62
	v_add_f32_e32 v106, v106, v107
	v_mul_f32_e32 v107, v57, v57
	v_mul_f32_e32 v108, v59, v59
	v_fmac_f32_e32 v107, v56, v56
	v_fmac_f32_e32 v108, v58, v58
	v_add_f32_e32 v107, v107, v108
	v_add_f32_e32 v106, v106, v107
	v_mul_f32_e32 v107, v53, v53
	v_mul_f32_e32 v108, v55, v55
	v_fmac_f32_e32 v107, v52, v52
	v_fmac_f32_e32 v108, v54, v54
	v_add_f32_e32 v107, v107, v108
	v_add_f32_e32 v106, v106, v107
	v_mul_f32_e32 v107, v49, v49
	v_mul_f32_e32 v108, v51, v51
	v_fmac_f32_e32 v107, v48, v48
	v_fmac_f32_e32 v108, v50, v50
	v_add_f32_e32 v107, v107, v108
	v_add_f32_e32 v106, v106, v107
	v_mov_b32_e32 v107, v106
	s_nop 1
	v_permlane16_swap_b32 v107, v106
	s_waitcnt lgkmcnt(0)
	v_add_f32_e32 v106, v106, v107
	v_mov_b32_e32 v107, v106
	s_nop 1
	v_permlane32_swap_b32 v107, v106
	s_and_saveexec_b64 s[12:13], s[10:11]
	s_cbranch_execz .LBB0_897
	s_lshl_b32 s50, s41, 10
	s_add_i32 s50, s81, s50
	v_lshl_add_u32 v108, v233, 4, s50
	s_waitcnt lgkmcnt(0)
	v_add_f32_e32 v106, v106, v107
	ds_write_b32 v108, v106 offset:2048
.LBB0_897:
	s_or_b64 exec, exec, s[12:13]
	v_mul_f32_e32 v106, v45, v45
	s_waitcnt lgkmcnt(0)
	v_mul_f32_e32 v107, v47, v47
	v_fmac_f32_e32 v106, v44, v44
	v_fmac_f32_e32 v107, v46, v46
	v_add_f32_e32 v106, v106, v107
	v_mul_f32_e32 v107, v41, v41
	v_mul_f32_e32 v108, v43, v43
	v_fmac_f32_e32 v107, v40, v40
	v_fmac_f32_e32 v108, v42, v42
	v_add_f32_e32 v107, v107, v108
	v_add_f32_e32 v106, v106, v107
	v_mul_f32_e32 v107, v37, v37
	v_mul_f32_e32 v108, v39, v39
	v_fmac_f32_e32 v107, v36, v36
	v_fmac_f32_e32 v108, v38, v38
	v_add_f32_e32 v107, v107, v108
	v_add_f32_e32 v106, v106, v107
	v_mul_f32_e32 v107, v33, v33
	v_mul_f32_e32 v108, v35, v35
	v_fmac_f32_e32 v107, v32, v32
	v_fmac_f32_e32 v108, v34, v34
	v_add_f32_e32 v107, v107, v108
	v_add_f32_e32 v106, v106, v107
	v_mov_b32_e32 v107, v106
	s_nop 1
	v_permlane16_swap_b32 v107, v106
	s_waitcnt lgkmcnt(0)
	v_add_f32_e32 v106, v106, v107
	v_mov_b32_e32 v107, v106
	s_nop 1
	v_permlane32_swap_b32 v107, v106
	s_and_saveexec_b64 s[12:13], s[10:11]
	s_cbranch_execz .LBB0_899
	s_lshl_b32 s50, s41, 10
	s_add_i32 s50, s81, s50
	v_lshl_add_u32 v108, v233, 4, s50
	s_waitcnt lgkmcnt(0)
	v_add_f32_e32 v106, v106, v107
	ds_write_b32 v108, v106 offset:2304
.LBB0_899:
	s_or_b64 exec, exec, s[12:13]
	v_mul_f32_e32 v106, v29, v29
	s_waitcnt lgkmcnt(0)
	v_mul_f32_e32 v107, v31, v31
	v_fmac_f32_e32 v106, v28, v28
	v_fmac_f32_e32 v107, v30, v30
	v_add_f32_e32 v106, v106, v107
	v_mul_f32_e32 v107, v25, v25
	v_mul_f32_e32 v108, v27, v27
	v_fmac_f32_e32 v107, v24, v24
	v_fmac_f32_e32 v108, v26, v26
	v_add_f32_e32 v107, v107, v108
	v_add_f32_e32 v106, v106, v107
	v_mul_f32_e32 v107, v21, v21
	v_mul_f32_e32 v108, v23, v23
	v_fmac_f32_e32 v107, v20, v20
	v_fmac_f32_e32 v108, v22, v22
	v_add_f32_e32 v107, v107, v108
	v_add_f32_e32 v106, v106, v107
	v_mul_f32_e32 v107, v17, v17
	v_mul_f32_e32 v108, v19, v19
	v_fmac_f32_e32 v107, v16, v16
	v_fmac_f32_e32 v108, v18, v18
	v_add_f32_e32 v107, v107, v108
	v_add_f32_e32 v106, v106, v107
	v_mov_b32_e32 v107, v106
	s_nop 1
	v_permlane16_swap_b32 v107, v106
	s_waitcnt lgkmcnt(0)
	v_add_f32_e32 v106, v106, v107
	v_mov_b32_e32 v107, v106
	s_nop 1
	v_permlane32_swap_b32 v107, v106
	s_and_saveexec_b64 s[12:13], s[10:11]
	s_cbranch_execz .LBB0_901
	s_lshl_b32 s50, s41, 10
	s_add_i32 s50, s81, s50
	v_lshl_add_u32 v108, v233, 4, s50
	s_waitcnt lgkmcnt(0)
	v_add_f32_e32 v106, v106, v107
	ds_write_b32 v108, v106 offset:2560
.LBB0_901:
	s_or_b64 exec, exec, s[12:13]
	v_mul_f32_e32 v106, v13, v13
	s_waitcnt lgkmcnt(0)
	v_mul_f32_e32 v107, v15, v15
	v_fmac_f32_e32 v106, v12, v12
	v_fmac_f32_e32 v107, v14, v14
	v_add_f32_e32 v106, v106, v107
	v_mul_f32_e32 v107, v9, v9
	v_mul_f32_e32 v108, v11, v11
	v_fmac_f32_e32 v107, v8, v8
	v_fmac_f32_e32 v108, v10, v10
	v_add_f32_e32 v107, v107, v108
	v_add_f32_e32 v106, v106, v107
	v_mul_f32_e32 v107, v5, v5
	v_mul_f32_e32 v108, v7, v7
	v_fmac_f32_e32 v107, v4, v4
	v_fmac_f32_e32 v108, v6, v6
	v_add_f32_e32 v107, v107, v108
	v_add_f32_e32 v106, v106, v107
	v_mul_f32_e32 v107, v1, v1
	v_mul_f32_e32 v108, v3, v3
	v_fmac_f32_e32 v107, v0, v0
	v_fmac_f32_e32 v108, v2, v2
	v_add_f32_e32 v107, v107, v108
	v_add_f32_e32 v106, v106, v107
	v_mov_b32_e32 v107, v106
	s_nop 1
	v_permlane16_swap_b32 v107, v106
	s_waitcnt lgkmcnt(0)
	v_add_f32_e32 v106, v106, v107
	v_mov_b32_e32 v107, v106
	s_nop 1
	v_permlane32_swap_b32 v107, v106
	s_and_saveexec_b64 s[12:13], s[10:11]
	s_cbranch_execz .LBB0_903
	s_lshl_b32 s50, s41, 10
	s_add_i32 s50, s81, s50
	v_lshl_add_u32 v108, v233, 4, s50
	s_waitcnt lgkmcnt(0)
	v_add_f32_e32 v106, v106, v107
	ds_write_b32 v108, v106 offset:2816

.LBB0_918:
	s_or_b64 exec, exec, s[40:41]
	v_add_u32_e32 v207, s83, v233
	s_waitcnt vmcnt(0) lgkmcnt(0)
	s_barrier
	v_lshl_add_u32 v206, v207, 2, v229
	ds_read_b32 v210, v206
	v_lshlrev_b32_e32 v212, 16, v172
	v_and_b32_e32 v213, 0xffff0000, v172
	v_lshlrev_b32_e32 v172, 16, v173
	v_and_b32_e32 v173, 0xffff0000, v173
	s_waitcnt lgkmcnt(0)
	v_pk_mul_f32 v[142:143], v[142:143], v[210:211] op_sel_hi:[1,0]
	v_pk_mul_f32 v[140:141], v[140:141], v[210:211] op_sel_hi:[1,0]
	v_lshlrev_b32_e32 v214, 16, v174
	v_and_b32_e32 v215, 0xffff0000, v174
	v_lshlrev_b32_e32 v174, 16, v175
	v_and_b32_e32 v175, 0xffff0000, v175
	v_pk_fma_f32 v[142:143], v[126:127], v[142:143], v[172:173]
	v_pk_fma_f32 v[140:141], v[124:125], v[140:141], v[212:213]
	v_pk_mul_f32 v[138:139], v[138:139], v[210:211] op_sel_hi:[1,0]
	v_pk_mul_f32 v[136:137], v[136:137], v[210:211] op_sel_hi:[1,0]
	v_pk_fma_f32 v[172:173], v[122:123], v[138:139], v[174:175]
	v_pk_fma_f32 v[138:139], v[120:121], v[136:137], v[214:215]
	v_mul_f32_e32 v136, v141, v141
	v_mul_f32_e32 v137, v143, v143
	v_fmac_f32_e32 v136, v140, v140
	v_fmac_f32_e32 v137, v142, v142
	v_add_f32_e32 v136, v136, v137
	v_mul_f32_e32 v137, v139, v139
	v_mul_f32_e32 v174, v173, v173
	v_fmac_f32_e32 v137, v138, v138
	v_fmac_f32_e32 v174, v172, v172
	v_add_f32_e32 v137, v137, v174
	v_add_f32_e32 v174, v136, v137
	v_cvt_pk_bf16_f32 v136, v140, v141
	v_cvt_pk_bf16_f32 v137, v142, v143
	v_lshlrev_b32_e32 v140, 16, v168
	v_and_b32_e32 v141, 0xffff0000, v168
	v_lshlrev_b32_e32 v142, 16, v169
	v_and_b32_e32 v143, 0xffff0000, v169
	v_pk_mul_f32 v[134:135], v[134:135], v[210:211] op_sel_hi:[1,0]
	v_pk_mul_f32 v[132:133], v[132:133], v[210:211] op_sel_hi:[1,0]
	v_lshlrev_b32_e32 v168, 16, v170
	v_and_b32_e32 v169, 0xffff0000, v170
	v_pk_fma_f32 v[134:135], v[110:111], v[134:135], v[142:143]
	v_pk_fma_f32 v[132:133], v[108:109], v[132:133], v[140:141]
	v_pk_mul_f32 v[128:129], v[128:129], v[210:211] op_sel_hi:[1,0]
	v_lshlrev_b32_e32 v170, 16, v171
	v_and_b32_e32 v171, 0xffff0000, v171
	v_pk_mul_f32 v[130:131], v[130:131], v[210:211] op_sel_hi:[1,0]
	v_pk_fma_f32 v[142:143], v[104:105], v[128:129], v[168:169]
	v_mul_f32_e32 v128, v133, v133
	v_mul_f32_e32 v129, v135, v135
	v_pk_fma_f32 v[140:141], v[106:107], v[130:131], v[170:171]
	v_fmac_f32_e32 v128, v132, v132
	v_fmac_f32_e32 v129, v134, v134
	v_add_f32_e32 v128, v128, v129
	v_mul_f32_e32 v129, v143, v143
	v_mul_f32_e32 v130, v141, v141
	v_fmac_f32_e32 v129, v142, v142
	v_fmac_f32_e32 v130, v140, v140
	v_add_f32_e32 v129, v129, v130
	v_add_f32_e32 v128, v128, v129
	v_add_f32_e32 v128, v174, v128
	v_mov_b32_e32 v129, v128
	s_nop 1
	v_permlane16_swap_b32 v129, v128
	v_add_u32_e32 v208, s82, v207
	v_ashrrev_i32_e32 v209, 31, v208
	v_lshlrev_b64 v[208:209], 11, v[208:209]
	v_lshl_add_u64 v[208:209], v[204:205], 0, v[208:209]
	s_waitcnt lgkmcnt(0)
	v_add_f32_e32 v128, v128, v129
	v_mov_b32_e32 v129, v128
	s_nop 1
	v_permlane32_swap_b32 v129, v128
	v_cvt_pk_bf16_f32 v138, v138, v139
	v_cvt_pk_bf16_f32 v139, v172, v173
	global_store_dwordx4 v[208:209], v[136:139], off
	v_cvt_pk_bf16_f32 v130, v132, v133
	v_cvt_pk_bf16_f32 v131, v134, v135
	v_cvt_pk_bf16_f32 v132, v142, v143
	v_cvt_pk_bf16_f32 v133, v140, v141
	global_store_dwordx4 v[208:209], v[130:133], off offset:256
	s_and_saveexec_b64 s[12:13], s[10:11]
	s_cbranch_execz .LBB0_920
	s_waitcnt lgkmcnt(0)
	v_add_f32_e32 v128, v128, v129
	v_lshl_add_u32 v129, v207, 4, s81
	ds_write_b32 v129, v128
.LBB0_920:
	s_or_b64 exec, exec, s[12:13]
	v_add_u32_e32 v252, 0xa0, v207
	v_add_u32_e32 v252, s82, v252
	v_ashrrev_i32_e32 v253, 31, v252
	v_lshlrev_b64 v[252:253], 11, v[252:253]
	v_lshl_add_u64 v[252:253], v[204:205], 0, v[252:253]
	global_load_dwordx4 v[168:171], v[252:253], off
	global_load_dwordx4 v[172:175], v[252:253], off offset:256
	v_add_u32_e32 v252, 0xb0, v207
	v_add_u32_e32 v252, s82, v252
	v_ashrrev_i32_e32 v253, 31, v252
	v_lshlrev_b64 v[252:253], 11, v[252:253]
	v_lshl_add_u64 v[252:253], v[204:205], 0, v[252:253]
	global_load_dwordx4 v[208:211], v[252:253], off
	global_load_dwordx4 v[212:215], v[252:253], off offset:256
	ds_read_b32 v132, v206 offset:64
	v_lshlrev_b32_e32 v134, 16, v164
	v_and_b32_e32 v135, 0xffff0000, v164
	v_lshlrev_b32_e32 v136, 16, v165
	v_and_b32_e32 v137, 0xffff0000, v165
	s_waitcnt lgkmcnt(0)
	v_pk_mul_f32 v[118:119], v[118:119], v[132:133] op_sel_hi:[1,0]
	v_pk_mul_f32 v[116:117], v[116:117], v[132:133] op_sel_hi:[1,0]
	v_lshlrev_b32_e32 v138, 16, v166
	v_and_b32_e32 v139, 0xffff0000, v166
	v_lshlrev_b32_e32 v140, 16, v167
	v_and_b32_e32 v141, 0xffff0000, v167
	v_pk_fma_f32 v[118:119], v[126:127], v[118:119], v[136:137]
	v_pk_fma_f32 v[116:117], v[124:125], v[116:117], v[134:135]
	v_pk_mul_f32 v[114:115], v[114:115], v[132:133] op_sel_hi:[1,0]
	v_pk_mul_f32 v[112:113], v[112:113], v[132:133] op_sel_hi:[1,0]
	v_pk_fma_f32 v[134:135], v[122:123], v[114:115], v[140:141]
	v_pk_fma_f32 v[114:115], v[120:121], v[112:113], v[138:139]
	v_mul_f32_e32 v112, v117, v117
	v_mul_f32_e32 v113, v119, v119
	v_fmac_f32_e32 v112, v116, v116
	v_fmac_f32_e32 v113, v118, v118
	v_add_f32_e32 v112, v112, v113
	v_mul_f32_e32 v113, v115, v115
	v_mul_f32_e32 v129, v135, v135
	v_fmac_f32_e32 v113, v114, v114
	v_fmac_f32_e32 v129, v134, v134
	v_add_f32_e32 v113, v113, v129
	v_add_f32_e32 v129, v112, v113
	v_cvt_pk_bf16_f32 v112, v116, v117
	v_cvt_pk_bf16_f32 v113, v118, v119
	v_lshlrev_b32_e32 v116, 16, v160
	v_and_b32_e32 v117, 0xffff0000, v160
	v_lshlrev_b32_e32 v118, 16, v161
	v_and_b32_e32 v119, 0xffff0000, v161
	v_pk_mul_f32 v[102:103], v[102:103], v[132:133] op_sel_hi:[1,0]
	v_pk_mul_f32 v[100:101], v[100:101], v[132:133] op_sel_hi:[1,0]
	v_lshlrev_b32_e32 v136, 16, v162
	v_and_b32_e32 v137, 0xffff0000, v162
	v_pk_fma_f32 v[102:103], v[110:111], v[102:103], v[118:119]
	v_pk_fma_f32 v[100:101], v[108:109], v[100:101], v[116:117]
	v_pk_mul_f32 v[96:97], v[96:97], v[132:133] op_sel_hi:[1,0]
	v_lshlrev_b32_e32 v138, 16, v163
	v_and_b32_e32 v139, 0xffff0000, v163
	v_pk_mul_f32 v[98:99], v[98:99], v[132:133] op_sel_hi:[1,0]
	v_pk_fma_f32 v[118:119], v[104:105], v[96:97], v[136:137]
	v_mul_f32_e32 v96, v101, v101
	v_mul_f32_e32 v97, v103, v103
	v_pk_fma_f32 v[116:117], v[106:107], v[98:99], v[138:139]
	v_fmac_f32_e32 v96, v100, v100
	v_fmac_f32_e32 v97, v102, v102
	v_add_f32_e32 v96, v96, v97
	v_mul_f32_e32 v97, v119, v119
	v_mul_f32_e32 v98, v117, v117
	v_fmac_f32_e32 v97, v118, v118
	v_fmac_f32_e32 v98, v116, v116
	v_add_f32_e32 v97, v97, v98
	v_add_f32_e32 v96, v96, v97
	v_add_f32_e32 v96, v129, v96
	v_mov_b32_e32 v97, v96
	s_nop 1
	v_permlane16_swap_b32 v97, v96
	v_add_u32_e32 v128, 16, v207
	v_add_u32_e32 v130, s82, v128
	v_ashrrev_i32_e32 v131, 31, v130
	v_lshlrev_b64 v[130:131], 11, v[130:131]
	s_waitcnt lgkmcnt(0)
	v_add_f32_e32 v96, v96, v97
	v_mov_b32_e32 v97, v96
	s_nop 1
	v_permlane32_swap_b32 v97, v96
	v_lshl_add_u64 v[130:131], v[204:205], 0, v[130:131]
	v_cvt_pk_bf16_f32 v114, v114, v115
	v_cvt_pk_bf16_f32 v115, v134, v135
	global_store_dwordx4 v[130:131], v[112:115], off
	v_cvt_pk_bf16_f32 v98, v100, v101
	v_cvt_pk_bf16_f32 v99, v102, v103
	v_cvt_pk_bf16_f32 v100, v118, v119
	v_cvt_pk_bf16_f32 v101, v116, v117
	global_store_dwordx4 v[130:131], v[98:101], off offset:256
	s_and_saveexec_b64 s[12:13], s[10:11]
	s_cbranch_execz .LBB0_922
	s_waitcnt lgkmcnt(0)
	v_add_f32_e32 v96, v96, v97
	v_lshl_add_u32 v97, v128, 4, s81
	ds_write_b32 v97, v96
.LBB0_922:
	s_or_b64 exec, exec, s[12:13]
	ds_read_b32 v100, v206 offset:128
	v_lshlrev_b32_e32 v102, 16, v156
	v_and_b32_e32 v103, 0xffff0000, v156
	v_lshlrev_b32_e32 v112, 16, v157
	v_and_b32_e32 v113, 0xffff0000, v157
	s_waitcnt lgkmcnt(0)
	v_pk_mul_f32 v[94:95], v[94:95], v[100:101] op_sel_hi:[1,0]
	v_pk_mul_f32 v[92:93], v[92:93], v[100:101] op_sel_hi:[1,0]
	v_lshlrev_b32_e32 v114, 16, v158
	v_and_b32_e32 v115, 0xffff0000, v158
	v_lshlrev_b32_e32 v116, 16, v159
	v_and_b32_e32 v117, 0xffff0000, v159
	v_pk_fma_f32 v[94:95], v[126:127], v[94:95], v[112:113]
	v_pk_fma_f32 v[92:93], v[124:125], v[92:93], v[102:103]
	v_pk_mul_f32 v[90:91], v[90:91], v[100:101] op_sel_hi:[1,0]
	v_pk_mul_f32 v[88:89], v[88:89], v[100:101] op_sel_hi:[1,0]
	v_pk_fma_f32 v[102:103], v[122:123], v[90:91], v[116:117]
	v_pk_fma_f32 v[90:91], v[120:121], v[88:89], v[114:115]
	v_mul_f32_e32 v88, v93, v93
	v_mul_f32_e32 v89, v95, v95
	v_fmac_f32_e32 v88, v92, v92
	v_fmac_f32_e32 v89, v94, v94
	v_add_f32_e32 v88, v88, v89
	v_mul_f32_e32 v89, v91, v91
	v_mul_f32_e32 v97, v103, v103
	v_fmac_f32_e32 v89, v90, v90
	v_fmac_f32_e32 v97, v102, v102
	v_add_f32_e32 v89, v89, v97
	v_add_f32_e32 v97, v88, v89
	v_cvt_pk_bf16_f32 v88, v92, v93
	v_cvt_pk_bf16_f32 v89, v94, v95
	v_lshlrev_b32_e32 v92, 16, v152
	v_and_b32_e32 v93, 0xffff0000, v152
	v_lshlrev_b32_e32 v94, 16, v153
	v_and_b32_e32 v95, 0xffff0000, v153
	v_pk_mul_f32 v[86:87], v[86:87], v[100:101] op_sel_hi:[1,0]
	v_pk_mul_f32 v[84:85], v[84:85], v[100:101] op_sel_hi:[1,0]
	v_lshlrev_b32_e32 v112, 16, v154
	v_and_b32_e32 v113, 0xffff0000, v154
	v_pk_fma_f32 v[86:87], v[110:111], v[86:87], v[94:95]
	v_pk_fma_f32 v[84:85], v[108:109], v[84:85], v[92:93]
	v_pk_mul_f32 v[80:81], v[80:81], v[100:101] op_sel_hi:[1,0]
	v_lshlrev_b32_e32 v114, 16, v155
	v_and_b32_e32 v115, 0xffff0000, v155
	v_pk_mul_f32 v[82:83], v[82:83], v[100:101] op_sel_hi:[1,0]
	v_pk_fma_f32 v[94:95], v[104:105], v[80:81], v[112:113]
	v_mul_f32_e32 v80, v85, v85
	v_mul_f32_e32 v81, v87, v87
	v_pk_fma_f32 v[92:93], v[106:107], v[82:83], v[114:115]
	v_fmac_f32_e32 v80, v84, v84
	v_fmac_f32_e32 v81, v86, v86
	v_add_f32_e32 v80, v80, v81
	v_mul_f32_e32 v81, v95, v95
	v_mul_f32_e32 v82, v93, v93
	v_fmac_f32_e32 v81, v94, v94
	v_fmac_f32_e32 v82, v92, v92
	v_add_f32_e32 v81, v81, v82
	v_add_f32_e32 v80, v80, v81
	v_add_f32_e32 v80, v97, v80
	v_mov_b32_e32 v81, v80
	s_nop 1
	v_permlane16_swap_b32 v81, v80
	v_add_u32_e32 v96, 32, v207
	v_add_u32_e32 v98, s82, v96
	v_ashrrev_i32_e32 v99, 31, v98
	v_lshlrev_b64 v[98:99], 11, v[98:99]
	s_waitcnt lgkmcnt(0)
	v_add_f32_e32 v80, v80, v81
	v_mov_b32_e32 v81, v80
	s_nop 1
	v_permlane32_swap_b32 v81, v80
	v_lshl_add_u64 v[98:99], v[204:205], 0, v[98:99]
	v_cvt_pk_bf16_f32 v90, v90, v91
	v_cvt_pk_bf16_f32 v91, v102, v103
	global_store_dwordx4 v[98:99], v[88:91], off
	v_cvt_pk_bf16_f32 v82, v84, v85
	v_cvt_pk_bf16_f32 v83, v86, v87
	v_cvt_pk_bf16_f32 v84, v94, v95
	v_cvt_pk_bf16_f32 v85, v92, v93
	global_store_dwordx4 v[98:99], v[82:85], off offset:256
	s_and_saveexec_b64 s[12:13], s[10:11]
	s_cbranch_execz .LBB0_924
	s_waitcnt lgkmcnt(0)
	v_add_f32_e32 v80, v80, v81
	v_lshl_add_u32 v81, v96, 4, s81
	ds_write_b32 v81, v80
.LBB0_924:
	s_or_b64 exec, exec, s[12:13]
	ds_read_b32 v84, v206 offset:192
	v_lshlrev_b32_e32 v86, 16, v148
	v_and_b32_e32 v87, 0xffff0000, v148
	v_lshlrev_b32_e32 v88, 16, v149
	v_and_b32_e32 v89, 0xffff0000, v149
	s_waitcnt lgkmcnt(0)
	v_pk_mul_f32 v[78:79], v[78:79], v[84:85] op_sel_hi:[1,0]
	v_pk_mul_f32 v[76:77], v[76:77], v[84:85] op_sel_hi:[1,0]
	v_lshlrev_b32_e32 v90, 16, v150
	v_and_b32_e32 v91, 0xffff0000, v150
	v_lshlrev_b32_e32 v92, 16, v151
	v_and_b32_e32 v93, 0xffff0000, v151
	v_pk_fma_f32 v[78:79], v[126:127], v[78:79], v[88:89]
	v_pk_fma_f32 v[76:77], v[124:125], v[76:77], v[86:87]
	v_pk_mul_f32 v[74:75], v[74:75], v[84:85] op_sel_hi:[1,0]
	v_pk_mul_f32 v[72:73], v[72:73], v[84:85] op_sel_hi:[1,0]
	v_pk_fma_f32 v[86:87], v[122:123], v[74:75], v[92:93]
	v_pk_fma_f32 v[74:75], v[120:121], v[72:73], v[90:91]
	v_mul_f32_e32 v72, v77, v77
	v_mul_f32_e32 v73, v79, v79
	v_fmac_f32_e32 v72, v76, v76
	v_fmac_f32_e32 v73, v78, v78
	v_add_f32_e32 v72, v72, v73
	v_mul_f32_e32 v73, v75, v75
	v_mul_f32_e32 v81, v87, v87
	v_fmac_f32_e32 v73, v74, v74
	v_fmac_f32_e32 v81, v86, v86
	v_add_f32_e32 v73, v73, v81
	v_add_f32_e32 v81, v72, v73
	v_cvt_pk_bf16_f32 v72, v76, v77
	v_cvt_pk_bf16_f32 v73, v78, v79
	v_lshlrev_b32_e32 v76, 16, v144
	v_and_b32_e32 v77, 0xffff0000, v144
	v_lshlrev_b32_e32 v78, 16, v145
	v_and_b32_e32 v79, 0xffff0000, v145
	v_pk_mul_f32 v[70:71], v[70:71], v[84:85] op_sel_hi:[1,0]
	v_pk_mul_f32 v[68:69], v[68:69], v[84:85] op_sel_hi:[1,0]
	v_lshlrev_b32_e32 v88, 16, v146
	v_and_b32_e32 v89, 0xffff0000, v146
	v_pk_fma_f32 v[70:71], v[110:111], v[70:71], v[78:79]
	v_pk_fma_f32 v[68:69], v[108:109], v[68:69], v[76:77]
	v_pk_mul_f32 v[64:65], v[64:65], v[84:85] op_sel_hi:[1,0]
	v_lshlrev_b32_e32 v90, 16, v147
	v_and_b32_e32 v91, 0xffff0000, v147
	v_pk_mul_f32 v[66:67], v[66:67], v[84:85] op_sel_hi:[1,0]
	v_pk_fma_f32 v[78:79], v[104:105], v[64:65], v[88:89]
	v_mul_f32_e32 v64, v69, v69
	v_mul_f32_e32 v65, v71, v71
	v_pk_fma_f32 v[76:77], v[106:107], v[66:67], v[90:91]
	v_fmac_f32_e32 v64, v68, v68
	v_fmac_f32_e32 v65, v70, v70
	v_add_f32_e32 v64, v64, v65
	v_mul_f32_e32 v65, v79, v79
	v_mul_f32_e32 v66, v77, v77
	v_fmac_f32_e32 v65, v78, v78
	v_fmac_f32_e32 v66, v76, v76
	v_add_f32_e32 v65, v65, v66
	v_add_f32_e32 v64, v64, v65
	v_add_f32_e32 v64, v81, v64
	v_mov_b32_e32 v65, v64
	s_nop 1
	v_permlane16_swap_b32 v65, v64
	v_add_u32_e32 v80, 48, v207
	v_add_u32_e32 v82, s82, v80
	v_ashrrev_i32_e32 v83, 31, v82
	v_lshlrev_b64 v[82:83], 11, v[82:83]
	s_waitcnt lgkmcnt(0)
	v_add_f32_e32 v64, v64, v65
	v_mov_b32_e32 v65, v64
	s_nop 1
	v_permlane32_swap_b32 v65, v64
	v_lshl_add_u64 v[82:83], v[204:205], 0, v[82:83]
	v_cvt_pk_bf16_f32 v74, v74, v75
	v_cvt_pk_bf16_f32 v75, v86, v87
	global_store_dwordx4 v[82:83], v[72:75], off
	v_cvt_pk_bf16_f32 v66, v68, v69
	v_cvt_pk_bf16_f32 v67, v70, v71
	v_cvt_pk_bf16_f32 v68, v78, v79
	v_cvt_pk_bf16_f32 v69, v76, v77
	global_store_dwordx4 v[82:83], v[66:69], off offset:256
	s_and_saveexec_b64 s[12:13], s[10:11]
	s_cbranch_execz .LBB0_926
	s_waitcnt lgkmcnt(0)
	v_add_f32_e32 v64, v64, v65
	v_lshl_add_u32 v65, v80, 4, s81
	ds_write_b32 v65, v64
.LBB0_926:
	s_or_b64 exec, exec, s[12:13]
	v_add_u32_e32 v64, 0x80, v207
	v_add_u32_e32 v66, s82, v64
	v_ashrrev_i32_e32 v67, 31, v66
	v_lshlrev_b64 v[66:67], 11, v[66:67]
	v_lshl_add_u64 v[70:71], v[204:205], 0, v[66:67]
	ds_read_b32 v72, v206 offset:512
	s_waitcnt lgkmcnt(0)
	v_pk_mul_f32 v[62:63], v[62:63], v[72:73] op_sel_hi:[1,0]
	v_pk_mul_f32 v[60:61], v[60:61], v[72:73] op_sel_hi:[1,0]
	v_pk_mul_f32 v[58:59], v[58:59], v[72:73] op_sel_hi:[1,0]
	v_pk_mul_f32 v[56:57], v[56:57], v[72:73] op_sel_hi:[1,0]
	v_pk_mul_f32 v[54:55], v[54:55], v[72:73] op_sel_hi:[1,0]
	v_pk_mul_f32 v[52:53], v[52:53], v[72:73] op_sel_hi:[1,0]
	v_pk_mul_f32 v[50:51], v[50:51], v[72:73] op_sel_hi:[1,0]
	v_pk_mul_f32 v[48:49], v[48:49], v[72:73] op_sel_hi:[1,0]
	v_lshlrev_b32_e32 v74, 16, v236
	v_and_b32_e32 v75, 0xffff0000, v236
	v_lshlrev_b32_e32 v66, 16, v237
	v_and_b32_e32 v67, 0xffff0000, v237
	v_lshlrev_b32_e32 v76, 16, v238
	v_and_b32_e32 v77, 0xffff0000, v238
	v_lshlrev_b32_e32 v68, 16, v239
	v_and_b32_e32 v69, 0xffff0000, v239
	v_pk_fma_f32 v[66:67], v[126:127], v[62:63], v[66:67]
	v_pk_fma_f32 v[74:75], v[124:125], v[60:61], v[74:75]
	v_pk_fma_f32 v[68:69], v[122:123], v[58:59], v[68:69]
	v_pk_fma_f32 v[76:77], v[120:121], v[56:57], v[76:77]
	v_cvt_pk_bf16_f32 v56, v74, v75
	v_cvt_pk_bf16_f32 v57, v66, v67
	v_mul_f32_e32 v65, v75, v75
	v_cvt_pk_bf16_f32 v58, v76, v77
	v_cvt_pk_bf16_f32 v59, v68, v69
	v_mul_f32_e32 v67, v67, v67
	v_mul_f32_e32 v72, v77, v77
	v_mul_f32_e32 v69, v69, v69
	v_fmac_f32_e32 v65, v74, v74
	v_fmac_f32_e32 v67, v66, v66
	v_fmac_f32_e32 v72, v76, v76
	v_fmac_f32_e32 v69, v68, v68
	v_add_f32_e32 v65, v65, v67
	v_add_f32_e32 v66, v72, v69
	v_add_f32_e32 v65, v65, v66
	global_store_dwordx4 v[70:71], v[56:59], off
	v_lshlrev_b32_e32 v66, 16, v240
	v_and_b32_e32 v67, 0xffff0000, v240
	v_lshlrev_b32_e32 v60, 16, v241
	v_and_b32_e32 v61, 0xffff0000, v241
	v_lshlrev_b32_e32 v68, 16, v242
	v_and_b32_e32 v69, 0xffff0000, v242
	v_lshlrev_b32_e32 v62, 16, v243
	v_and_b32_e32 v63, 0xffff0000, v243
	v_pk_fma_f32 v[54:55], v[110:111], v[54:55], v[60:61]
	v_pk_fma_f32 v[52:53], v[108:109], v[52:53], v[66:67]
	v_pk_fma_f32 v[60:61], v[106:107], v[50:51], v[62:63]
	v_pk_fma_f32 v[62:63], v[104:105], v[48:49], v[68:69]
	v_mul_f32_e32 v48, v53, v53
	v_mul_f32_e32 v49, v55, v55
	v_mul_f32_e32 v50, v63, v63
	v_mul_f32_e32 v51, v61, v61
	v_fmac_f32_e32 v48, v52, v52
	v_fmac_f32_e32 v49, v54, v54
	v_fmac_f32_e32 v50, v62, v62
	v_fmac_f32_e32 v51, v60, v60
	v_add_f32_e32 v48, v48, v49
	v_add_f32_e32 v49, v50, v51
	v_add_f32_e32 v48, v48, v49
	v_add_f32_e32 v48, v65, v48
	v_mov_b32_e32 v49, v48
	s_nop 1
	v_permlane16_swap_b32 v49, v48
	v_cvt_pk_bf16_f32 v50, v52, v53
	v_cvt_pk_bf16_f32 v51, v54, v55
	v_cvt_pk_bf16_f32 v52, v62, v63
	v_cvt_pk_bf16_f32 v53, v60, v61
	s_waitcnt lgkmcnt(0)
	v_add_f32_e32 v48, v48, v49
	v_mov_b32_e32 v49, v48
	s_nop 1
	v_permlane32_swap_b32 v49, v48
	global_store_dwordx4 v[70:71], v[50:53], off offset:256
	s_and_saveexec_b64 s[12:13], s[10:11]
	s_cbranch_execz .LBB0_928
	s_waitcnt lgkmcnt(0)
	v_add_f32_e32 v48, v48, v49
	v_lshl_add_u32 v49, v64, 4, s81
	ds_write_b32 v49, v48
.LBB0_928:
	s_or_b64 exec, exec, s[12:13]
	v_add_u32_e32 v48, 0x90, v207
	v_add_u32_e32 v50, s82, v48
	v_ashrrev_i32_e32 v51, 31, v50
	v_lshlrev_b64 v[50:51], 11, v[50:51]
	v_lshl_add_u64 v[54:55], v[204:205], 0, v[50:51]
	ds_read_b32 v56, v206 offset:576
	s_waitcnt lgkmcnt(0)
	v_pk_mul_f32 v[46:47], v[46:47], v[56:57] op_sel_hi:[1,0]
	v_pk_mul_f32 v[44:45], v[44:45], v[56:57] op_sel_hi:[1,0]
	v_pk_mul_f32 v[42:43], v[42:43], v[56:57] op_sel_hi:[1,0]
	v_pk_mul_f32 v[40:41], v[40:41], v[56:57] op_sel_hi:[1,0]
	v_pk_mul_f32 v[38:39], v[38:39], v[56:57] op_sel_hi:[1,0]
	v_pk_mul_f32 v[36:37], v[36:37], v[56:57] op_sel_hi:[1,0]
	v_pk_mul_f32 v[34:35], v[34:35], v[56:57] op_sel_hi:[1,0]
	v_pk_mul_f32 v[32:33], v[32:33], v[56:57] op_sel_hi:[1,0]
	v_lshlrev_b32_e32 v58, 16, v244
	v_and_b32_e32 v59, 0xffff0000, v244
	v_lshlrev_b32_e32 v50, 16, v245
	v_and_b32_e32 v51, 0xffff0000, v245
	v_lshlrev_b32_e32 v60, 16, v246
	v_and_b32_e32 v61, 0xffff0000, v246
	v_lshlrev_b32_e32 v52, 16, v247
	v_and_b32_e32 v53, 0xffff0000, v247
	v_pk_fma_f32 v[50:51], v[126:127], v[46:47], v[50:51]
	v_pk_fma_f32 v[58:59], v[124:125], v[44:45], v[58:59]
	v_pk_fma_f32 v[52:53], v[122:123], v[42:43], v[52:53]
	v_pk_fma_f32 v[60:61], v[120:121], v[40:41], v[60:61]
	v_cvt_pk_bf16_f32 v40, v58, v59
	v_cvt_pk_bf16_f32 v41, v50, v51
	v_mul_f32_e32 v49, v59, v59
	v_cvt_pk_bf16_f32 v42, v60, v61
	v_cvt_pk_bf16_f32 v43, v52, v53
	v_mul_f32_e32 v51, v51, v51
	v_mul_f32_e32 v56, v61, v61
	v_mul_f32_e32 v53, v53, v53
	v_fmac_f32_e32 v49, v58, v58
	v_fmac_f32_e32 v51, v50, v50
	v_fmac_f32_e32 v56, v60, v60
	v_fmac_f32_e32 v53, v52, v52
	v_add_f32_e32 v49, v49, v51
	v_add_f32_e32 v50, v56, v53
	v_add_f32_e32 v49, v49, v50
	global_store_dwordx4 v[54:55], v[40:43], off
	v_lshlrev_b32_e32 v50, 16, v248
	v_and_b32_e32 v51, 0xffff0000, v248
	v_lshlrev_b32_e32 v44, 16, v249
	v_and_b32_e32 v45, 0xffff0000, v249
	v_lshlrev_b32_e32 v52, 16, v250
	v_and_b32_e32 v53, 0xffff0000, v250
	v_lshlrev_b32_e32 v46, 16, v251
	v_and_b32_e32 v47, 0xffff0000, v251
	v_pk_fma_f32 v[38:39], v[110:111], v[38:39], v[44:45]
	v_pk_fma_f32 v[36:37], v[108:109], v[36:37], v[50:51]
	v_pk_fma_f32 v[44:45], v[106:107], v[34:35], v[46:47]
	v_pk_fma_f32 v[46:47], v[104:105], v[32:33], v[52:53]
	v_mul_f32_e32 v32, v37, v37
	v_mul_f32_e32 v33, v39, v39
	v_mul_f32_e32 v34, v47, v47
	v_mul_f32_e32 v35, v45, v45
	v_fmac_f32_e32 v32, v36, v36
	v_fmac_f32_e32 v33, v38, v38
	v_fmac_f32_e32 v34, v46, v46
	v_fmac_f32_e32 v35, v44, v44
	v_add_f32_e32 v32, v32, v33
	v_add_f32_e32 v33, v34, v35
	v_add_f32_e32 v32, v32, v33
	v_add_f32_e32 v32, v49, v32
	v_mov_b32_e32 v33, v32
	s_nop 1
	v_permlane16_swap_b32 v33, v32
	v_cvt_pk_bf16_f32 v34, v36, v37
	v_cvt_pk_bf16_f32 v35, v38, v39
	v_cvt_pk_bf16_f32 v36, v46, v47
	v_cvt_pk_bf16_f32 v37, v44, v45
	s_waitcnt lgkmcnt(0)
	v_add_f32_e32 v32, v32, v33
	v_mov_b32_e32 v33, v32
	s_nop 1
	v_permlane32_swap_b32 v33, v32
	global_store_dwordx4 v[54:55], v[34:37], off offset:256
	s_and_saveexec_b64 s[12:13], s[10:11]
	s_cbranch_execz .LBB0_930
	s_waitcnt lgkmcnt(0)
	v_add_f32_e32 v32, v32, v33
	v_lshl_add_u32 v33, v48, 4, s81
	ds_write_b32 v33, v32
.LBB0_930:
	s_or_b64 exec, exec, s[12:13]
	v_add_u32_e32 v32, 0xa0, v207
	v_add_u32_e32 v34, s82, v32
	v_ashrrev_i32_e32 v35, 31, v34
	v_lshlrev_b64 v[34:35], 11, v[34:35]
	v_lshl_add_u64 v[38:39], v[204:205], 0, v[34:35]
	ds_read_b32 v40, v206 offset:640
	s_waitcnt lgkmcnt(0)
	v_pk_mul_f32 v[30:31], v[30:31], v[40:41] op_sel_hi:[1,0]
	v_pk_mul_f32 v[28:29], v[28:29], v[40:41] op_sel_hi:[1,0]
	v_pk_mul_f32 v[26:27], v[26:27], v[40:41] op_sel_hi:[1,0]
	v_pk_mul_f32 v[24:25], v[24:25], v[40:41] op_sel_hi:[1,0]
	v_pk_mul_f32 v[22:23], v[22:23], v[40:41] op_sel_hi:[1,0]
	v_pk_mul_f32 v[20:21], v[20:21], v[40:41] op_sel_hi:[1,0]
	v_pk_mul_f32 v[18:19], v[18:19], v[40:41] op_sel_hi:[1,0]
	v_pk_mul_f32 v[16:17], v[16:17], v[40:41] op_sel_hi:[1,0]
	s_waitcnt vmcnt(13)
	v_lshlrev_b32_e32 v42, 16, v168
	v_and_b32_e32 v43, 0xffff0000, v168
	v_lshlrev_b32_e32 v34, 16, v169
	v_and_b32_e32 v35, 0xffff0000, v169
	v_lshlrev_b32_e32 v44, 16, v170
	v_and_b32_e32 v45, 0xffff0000, v170
	v_lshlrev_b32_e32 v36, 16, v171
	v_and_b32_e32 v37, 0xffff0000, v171
	v_pk_fma_f32 v[34:35], v[126:127], v[30:31], v[34:35]
	v_pk_fma_f32 v[42:43], v[124:125], v[28:29], v[42:43]
	v_pk_fma_f32 v[36:37], v[122:123], v[26:27], v[36:37]
	v_pk_fma_f32 v[44:45], v[120:121], v[24:25], v[44:45]
	v_cvt_pk_bf16_f32 v24, v42, v43
	v_cvt_pk_bf16_f32 v25, v34, v35
	v_mul_f32_e32 v33, v43, v43
	v_cvt_pk_bf16_f32 v26, v44, v45
	v_cvt_pk_bf16_f32 v27, v36, v37
	v_mul_f32_e32 v35, v35, v35
	v_mul_f32_e32 v40, v45, v45
	v_mul_f32_e32 v37, v37, v37
	v_fmac_f32_e32 v33, v42, v42
	v_fmac_f32_e32 v35, v34, v34
	v_fmac_f32_e32 v40, v44, v44
	v_fmac_f32_e32 v37, v36, v36
	v_add_f32_e32 v33, v33, v35
	v_add_f32_e32 v34, v40, v37
	v_add_f32_e32 v33, v33, v34
	global_store_dwordx4 v[38:39], v[24:27], off
	s_waitcnt vmcnt(13)
	v_lshlrev_b32_e32 v34, 16, v172
	v_and_b32_e32 v35, 0xffff0000, v172
	v_lshlrev_b32_e32 v28, 16, v173
	v_and_b32_e32 v29, 0xffff0000, v173
	v_lshlrev_b32_e32 v36, 16, v174
	v_and_b32_e32 v37, 0xffff0000, v174
	v_lshlrev_b32_e32 v30, 16, v175
	v_and_b32_e32 v31, 0xffff0000, v175
	v_pk_fma_f32 v[22:23], v[110:111], v[22:23], v[28:29]
	v_pk_fma_f32 v[20:21], v[108:109], v[20:21], v[34:35]
	v_pk_fma_f32 v[28:29], v[106:107], v[18:19], v[30:31]
	v_pk_fma_f32 v[30:31], v[104:105], v[16:17], v[36:37]
	v_mul_f32_e32 v16, v21, v21
	v_mul_f32_e32 v17, v23, v23
	v_mul_f32_e32 v18, v31, v31
	v_mul_f32_e32 v19, v29, v29
	v_fmac_f32_e32 v16, v20, v20
	v_fmac_f32_e32 v17, v22, v22
	v_fmac_f32_e32 v18, v30, v30
	v_fmac_f32_e32 v19, v28, v28
	v_add_f32_e32 v16, v16, v17
	v_add_f32_e32 v17, v18, v19
	v_add_f32_e32 v16, v16, v17
	v_add_f32_e32 v16, v33, v16
	v_mov_b32_e32 v17, v16
	s_nop 1
	v_permlane16_swap_b32 v17, v16
	v_cvt_pk_bf16_f32 v18, v20, v21
	v_cvt_pk_bf16_f32 v19, v22, v23
	v_cvt_pk_bf16_f32 v20, v30, v31
	v_cvt_pk_bf16_f32 v21, v28, v29
	s_waitcnt lgkmcnt(0)
	v_add_f32_e32 v16, v16, v17
	v_mov_b32_e32 v17, v16
	s_nop 1
	v_permlane32_swap_b32 v17, v16
	global_store_dwordx4 v[38:39], v[18:21], off offset:256
	s_and_saveexec_b64 s[12:13], s[10:11]
	s_cbranch_execz .LBB0_932
	s_waitcnt lgkmcnt(0)
	v_add_f32_e32 v16, v16, v17
	v_lshl_add_u32 v17, v32, 4, s81
	ds_write_b32 v17, v16
.LBB0_932:
	s_or_b64 exec, exec, s[12:13]
	v_add_u32_e32 v16, 0xb0, v207
	v_add_u32_e32 v18, s82, v16
	v_ashrrev_i32_e32 v19, 31, v18
	v_lshlrev_b64 v[18:19], 11, v[18:19]
	v_lshl_add_u64 v[22:23], v[204:205], 0, v[18:19]
	ds_read_b32 v24, v206 offset:704
	s_waitcnt lgkmcnt(0)
	v_pk_mul_f32 v[14:15], v[14:15], v[24:25] op_sel_hi:[1,0]
	v_pk_mul_f32 v[12:13], v[12:13], v[24:25] op_sel_hi:[1,0]
	v_pk_mul_f32 v[10:11], v[10:11], v[24:25] op_sel_hi:[1,0]
	v_pk_mul_f32 v[8:9], v[8:9], v[24:25] op_sel_hi:[1,0]
	v_pk_mul_f32 v[6:7], v[6:7], v[24:25] op_sel_hi:[1,0]
	v_pk_mul_f32 v[4:5], v[4:5], v[24:25] op_sel_hi:[1,0]
	v_pk_mul_f32 v[2:3], v[2:3], v[24:25] op_sel_hi:[1,0]
	v_pk_mul_f32 v[0:1], v[0:1], v[24:25] op_sel_hi:[1,0]
	s_waitcnt vmcnt(13)
	v_lshlrev_b32_e32 v26, 16, v208
	v_and_b32_e32 v27, 0xffff0000, v208
	v_lshlrev_b32_e32 v18, 16, v209
	v_and_b32_e32 v19, 0xffff0000, v209
	v_lshlrev_b32_e32 v28, 16, v210
	v_and_b32_e32 v29, 0xffff0000, v210
	v_lshlrev_b32_e32 v20, 16, v211
	v_and_b32_e32 v21, 0xffff0000, v211
	v_pk_fma_f32 v[18:19], v[126:127], v[14:15], v[18:19]
	v_pk_fma_f32 v[26:27], v[124:125], v[12:13], v[26:27]
	v_pk_fma_f32 v[20:21], v[122:123], v[10:11], v[20:21]
	v_pk_fma_f32 v[28:29], v[120:121], v[8:9], v[28:29]
	v_cvt_pk_bf16_f32 v8, v26, v27
	v_cvt_pk_bf16_f32 v9, v18, v19
	v_mul_f32_e32 v17, v27, v27
	v_cvt_pk_bf16_f32 v10, v28, v29
	v_cvt_pk_bf16_f32 v11, v20, v21
	v_mul_f32_e32 v19, v19, v19
	v_mul_f32_e32 v24, v29, v29
	v_mul_f32_e32 v21, v21, v21
	v_fmac_f32_e32 v17, v26, v26
	v_fmac_f32_e32 v19, v18, v18
	v_fmac_f32_e32 v24, v28, v28
	v_fmac_f32_e32 v21, v20, v20
	v_add_f32_e32 v17, v17, v19
	v_add_f32_e32 v18, v24, v21
	v_add_f32_e32 v17, v17, v18
	global_store_dwordx4 v[22:23], v[8:11], off
	s_waitcnt vmcnt(13)
	v_lshlrev_b32_e32 v18, 16, v212
	v_and_b32_e32 v19, 0xffff0000, v212
	v_lshlrev_b32_e32 v12, 16, v213
	v_and_b32_e32 v13, 0xffff0000, v213
	v_lshlrev_b32_e32 v20, 16, v214
	v_and_b32_e32 v21, 0xffff0000, v214
	v_lshlrev_b32_e32 v14, 16, v215
	v_and_b32_e32 v15, 0xffff0000, v215
	v_pk_fma_f32 v[6:7], v[110:111], v[6:7], v[12:13]
	v_pk_fma_f32 v[4:5], v[108:109], v[4:5], v[18:19]
	v_pk_fma_f32 v[12:13], v[106:107], v[2:3], v[14:15]
	v_pk_fma_f32 v[14:15], v[104:105], v[0:1], v[20:21]
	v_mul_f32_e32 v0, v5, v5
	v_mul_f32_e32 v1, v7, v7
	v_mul_f32_e32 v2, v15, v15
	v_mul_f32_e32 v3, v13, v13
	v_fmac_f32_e32 v0, v4, v4
	v_fmac_f32_e32 v1, v6, v6
	v_fmac_f32_e32 v2, v14, v14
	v_fmac_f32_e32 v3, v12, v12
	v_add_f32_e32 v0, v0, v1
	v_add_f32_e32 v1, v2, v3
	v_add_f32_e32 v0, v0, v1
	v_add_f32_e32 v0, v17, v0
	v_mov_b32_e32 v1, v0
	s_nop 1
	v_permlane16_swap_b32 v1, v0
	v_cvt_pk_bf16_f32 v2, v4, v5
	v_cvt_pk_bf16_f32 v3, v6, v7
	v_cvt_pk_bf16_f32 v4, v14, v15
	v_cvt_pk_bf16_f32 v5, v12, v13
	s_waitcnt lgkmcnt(0)
	v_add_f32_e32 v0, v0, v1
	v_mov_b32_e32 v1, v0
	s_nop 1
	v_permlane32_swap_b32 v1, v0
	global_store_dwordx4 v[22:23], v[2:5], off offset:256
	s_and_saveexec_b64 s[12:13], s[10:11]
	s_cbranch_execz .LBB0_934
	s_waitcnt lgkmcnt(0)
	v_add_f32_e32 v0, v0, v1
	v_lshl_add_u32 v1, v16, 4, s81
	ds_write_b32 v1, v0

.LBB0_1248:
	s_mov_b32 s13, s70
	v_mov_b32_e32 v232, v218
	s_mov_b32 s15, s73
	v_mov_b32_e32 v206, v219
	s_mov_b64 s[10:11], s[0:1]
	v_and_b32_e32 v107, 64, v225
	v_mov_b64_e32 v[104:105], s[10:11]
	flat_load_dwordx2 v[202:203], v[104:105] offset:216
	s_nop 0
	flat_load_dwordx2 v[104:105], v[104:105] offset:168
	v_xor_b32_e32 v106, 16, v225
	v_add_u32_e32 v107, 64, v107
	v_cmp_lt_i32_e32 vcc, v106, v107
	v_mul_f32_e32 v108, v143, v143
	v_fmac_f32_e32 v108, v142, v142
	v_cndmask_b32_e32 v106, v225, v106, vcc
	v_lshlrev_b32_e32 v229, 2, v106
	v_mul_f32_e32 v106, v141, v141
	v_fmac_f32_e32 v106, v140, v140
	v_add_f32_e32 v106, v106, v108
	v_mul_f32_e32 v108, v137, v137
	v_mul_f32_e32 v109, v139, v139
	v_fmac_f32_e32 v108, v136, v136
	v_fmac_f32_e32 v109, v138, v138
	v_add_f32_e32 v108, v108, v109
	v_add_f32_e32 v106, v106, v108
	v_mul_f32_e32 v108, v133, v133
	v_mul_f32_e32 v109, v135, v135
	v_fmac_f32_e32 v108, v132, v132
	v_fmac_f32_e32 v109, v134, v134
	v_add_f32_e32 v108, v108, v109
	v_add_f32_e32 v106, v106, v108
	v_mul_f32_e32 v108, v129, v129
	v_mul_f32_e32 v109, v131, v131
	v_fmac_f32_e32 v108, v128, v128
	v_fmac_f32_e32 v109, v130, v130
	v_add_f32_e32 v108, v108, v109
	v_add_f32_e32 v106, v106, v108
	v_mov_b32_e32 v108, v106
	s_nop 1
	v_permlane16_swap_b32 v108, v106
	v_xor_b32_e32 v109, 32, v225
	v_cmp_lt_i32_e32 vcc, v109, v107
	s_lshl_b32 s49, s15, 2
	v_cmp_eq_u32_e64 s[10:11], 0, v206
	v_cndmask_b32_e32 v107, v225, v109, vcc
	v_lshlrev_b32_e32 v230, 2, v107
	s_waitcnt lgkmcnt(0)
	v_add_f32_e32 v106, v106, v108
	v_mov_b32_e32 v107, v106
	s_nop 1
	v_permlane32_swap_b32 v107, v106
	s_add_i32 s49, s49, 0x20400
	s_and_saveexec_b64 s[52:53], s[10:11]
	s_cbranch_execz .LBB0_1250
	s_lshl_b32 s51, s13, 10
	s_add_i32 s51, s49, s51
	v_lshl_add_u32 v108, v232, 4, s51
	s_waitcnt lgkmcnt(0)
	v_add_f32_e32 v106, v106, v107
	ds_write_b32 v108, v106
.LBB0_1250:
	s_or_b64 exec, exec, s[52:53]
	v_mul_f32_e32 v106, v117, v117
	s_waitcnt lgkmcnt(0)
	v_mul_f32_e32 v107, v119, v119
	v_fmac_f32_e32 v106, v116, v116
	v_fmac_f32_e32 v107, v118, v118
	v_add_f32_e32 v106, v106, v107
	v_mul_f32_e32 v107, v113, v113
	v_mul_f32_e32 v108, v115, v115
	v_fmac_f32_e32 v107, v112, v112
	v_fmac_f32_e32 v108, v114, v114
	v_add_f32_e32 v107, v107, v108
	v_add_f32_e32 v106, v106, v107
	v_mul_f32_e32 v107, v101, v101
	v_mul_f32_e32 v108, v103, v103
	v_fmac_f32_e32 v107, v100, v100
	v_fmac_f32_e32 v108, v102, v102
	v_add_f32_e32 v107, v107, v108
	v_add_f32_e32 v106, v106, v107
	v_mul_f32_e32 v107, v97, v97
	v_mul_f32_e32 v108, v99, v99
	v_fmac_f32_e32 v107, v96, v96
	v_fmac_f32_e32 v108, v98, v98
	v_add_f32_e32 v107, v107, v108
	v_add_f32_e32 v106, v106, v107
	v_mov_b32_e32 v107, v106
	s_nop 1
	v_permlane16_swap_b32 v107, v106
	s_waitcnt lgkmcnt(0)
	v_add_f32_e32 v106, v106, v107
	v_mov_b32_e32 v107, v106
	s_nop 1
	v_permlane32_swap_b32 v107, v106
	s_and_saveexec_b64 s[52:53], s[10:11]
	s_cbranch_execz .LBB0_1252
	s_lshl_b32 s51, s13, 10
	s_add_i32 s51, s49, s51
	v_lshl_add_u32 v108, v232, 4, s51
	s_waitcnt lgkmcnt(0)
	v_add_f32_e32 v106, v106, v107
	ds_write_b32 v108, v106 offset:256
.LBB0_1252:
	s_or_b64 exec, exec, s[52:53]
	v_mul_f32_e32 v106, v93, v93
	s_waitcnt lgkmcnt(0)
	v_mul_f32_e32 v107, v95, v95
	v_fmac_f32_e32 v106, v92, v92
	v_fmac_f32_e32 v107, v94, v94
	v_add_f32_e32 v106, v106, v107
	v_mul_f32_e32 v107, v89, v89
	v_mul_f32_e32 v108, v91, v91
	v_fmac_f32_e32 v107, v88, v88
	v_fmac_f32_e32 v108, v90, v90
	v_add_f32_e32 v107, v107, v108
	v_add_f32_e32 v106, v106, v107
	v_mul_f32_e32 v107, v85, v85
	v_mul_f32_e32 v108, v87, v87
	v_fmac_f32_e32 v107, v84, v84
	v_fmac_f32_e32 v108, v86, v86
	v_add_f32_e32 v107, v107, v108
	v_add_f32_e32 v106, v106, v107
	v_mul_f32_e32 v107, v81, v81
	v_mul_f32_e32 v108, v83, v83
	v_fmac_f32_e32 v107, v80, v80
	v_fmac_f32_e32 v108, v82, v82
	v_add_f32_e32 v107, v107, v108
	v_add_f32_e32 v106, v106, v107
	v_mov_b32_e32 v107, v106
	s_nop 1
	v_permlane16_swap_b32 v107, v106
	s_waitcnt lgkmcnt(0)
	v_add_f32_e32 v106, v106, v107
	v_mov_b32_e32 v107, v106
	s_nop 1
	v_permlane32_swap_b32 v107, v106
	s_and_saveexec_b64 s[52:53], s[10:11]
	s_cbranch_execz .LBB0_1254
	s_lshl_b32 s51, s13, 10
	s_add_i32 s51, s49, s51
	v_lshl_add_u32 v108, v232, 4, s51
	s_waitcnt lgkmcnt(0)
	v_add_f32_e32 v106, v106, v107
	ds_write_b32 v108, v106 offset:512
.LBB0_1254:
	s_or_b64 exec, exec, s[52:53]
	v_mul_f32_e32 v106, v77, v77
	s_waitcnt lgkmcnt(0)
	v_mul_f32_e32 v107, v79, v79
	v_fmac_f32_e32 v106, v76, v76
	v_fmac_f32_e32 v107, v78, v78
	v_add_f32_e32 v106, v106, v107
	v_mul_f32_e32 v107, v73, v73
	v_mul_f32_e32 v108, v75, v75
	v_fmac_f32_e32 v107, v72, v72
	v_fmac_f32_e32 v108, v74, v74
	v_add_f32_e32 v107, v107, v108
	v_add_f32_e32 v106, v106, v107
	v_mul_f32_e32 v107, v69, v69
	v_mul_f32_e32 v108, v71, v71
	v_fmac_f32_e32 v107, v68, v68
	v_fmac_f32_e32 v108, v70, v70
	v_add_f32_e32 v107, v107, v108
	v_add_f32_e32 v106, v106, v107
	v_mul_f32_e32 v107, v65, v65
	v_mul_f32_e32 v108, v67, v67
	v_fmac_f32_e32 v107, v64, v64
	v_fmac_f32_e32 v108, v66, v66
	v_add_f32_e32 v107, v107, v108
	v_add_f32_e32 v106, v106, v107
	v_mov_b32_e32 v107, v106
	s_nop 1
	v_permlane16_swap_b32 v107, v106
	s_waitcnt lgkmcnt(0)
	v_add_f32_e32 v106, v106, v107
	v_mov_b32_e32 v107, v106
	s_nop 1
	v_permlane32_swap_b32 v107, v106
	s_and_saveexec_b64 s[52:53], s[10:11]
	s_cbranch_execz .LBB0_1256
	s_lshl_b32 s51, s13, 10
	s_add_i32 s51, s49, s51
	v_lshl_add_u32 v108, v232, 4, s51
	s_waitcnt lgkmcnt(0)
	v_add_f32_e32 v106, v106, v107
	ds_write_b32 v108, v106 offset:768
.LBB0_1256:
	s_or_b64 exec, exec, s[52:53]
	v_mul_f32_e32 v106, v61, v61
	s_waitcnt lgkmcnt(0)
	v_mul_f32_e32 v107, v63, v63
	v_fmac_f32_e32 v106, v60, v60
	v_fmac_f32_e32 v107, v62, v62
	v_add_f32_e32 v106, v106, v107
	v_mul_f32_e32 v107, v57, v57
	v_mul_f32_e32 v108, v59, v59
	v_fmac_f32_e32 v107, v56, v56
	v_fmac_f32_e32 v108, v58, v58
	v_add_f32_e32 v107, v107, v108
	v_add_f32_e32 v106, v106, v107
	v_mul_f32_e32 v107, v53, v53
	v_mul_f32_e32 v108, v55, v55
	v_fmac_f32_e32 v107, v52, v52
	v_fmac_f32_e32 v108, v54, v54
	v_add_f32_e32 v107, v107, v108
	v_add_f32_e32 v106, v106, v107
	v_mul_f32_e32 v107, v49, v49
	v_mul_f32_e32 v108, v51, v51
	v_fmac_f32_e32 v107, v48, v48
	v_fmac_f32_e32 v108, v50, v50
	v_add_f32_e32 v107, v107, v108
	v_add_f32_e32 v106, v106, v107
	v_mov_b32_e32 v107, v106
	s_nop 1
	v_permlane16_swap_b32 v107, v106
	s_waitcnt lgkmcnt(0)
	v_add_f32_e32 v106, v106, v107
	v_mov_b32_e32 v107, v106
	s_nop 1
	v_permlane32_swap_b32 v107, v106
	s_and_saveexec_b64 s[52:53], s[10:11]
	s_cbranch_execz .LBB0_1258
	s_lshl_b32 s51, s13, 10
	s_add_i32 s51, s49, s51
	v_lshl_add_u32 v108, v232, 4, s51
	s_waitcnt lgkmcnt(0)
	v_add_f32_e32 v106, v106, v107
	ds_write_b32 v108, v106 offset:2048
.LBB0_1258:
	s_or_b64 exec, exec, s[52:53]
	v_mul_f32_e32 v106, v45, v45
	s_waitcnt lgkmcnt(0)
	v_mul_f32_e32 v107, v47, v47
	v_fmac_f32_e32 v106, v44, v44
	v_fmac_f32_e32 v107, v46, v46
	v_add_f32_e32 v106, v106, v107
	v_mul_f32_e32 v107, v41, v41
	v_mul_f32_e32 v108, v43, v43
	v_fmac_f32_e32 v107, v40, v40
	v_fmac_f32_e32 v108, v42, v42
	v_add_f32_e32 v107, v107, v108
	v_add_f32_e32 v106, v106, v107
	v_mul_f32_e32 v107, v37, v37
	v_mul_f32_e32 v108, v39, v39
	v_fmac_f32_e32 v107, v36, v36
	v_fmac_f32_e32 v108, v38, v38
	v_add_f32_e32 v107, v107, v108
	v_add_f32_e32 v106, v106, v107
	v_mul_f32_e32 v107, v33, v33
	v_mul_f32_e32 v108, v35, v35
	v_fmac_f32_e32 v107, v32, v32
	v_fmac_f32_e32 v108, v34, v34
	v_add_f32_e32 v107, v107, v108
	v_add_f32_e32 v106, v106, v107
	v_mov_b32_e32 v107, v106
	s_nop 1
	v_permlane16_swap_b32 v107, v106
	s_waitcnt lgkmcnt(0)
	v_add_f32_e32 v106, v106, v107
	v_mov_b32_e32 v107, v106
	s_nop 1
	v_permlane32_swap_b32 v107, v106
	s_and_saveexec_b64 s[52:53], s[10:11]
	s_cbranch_execz .LBB0_1260
	s_lshl_b32 s51, s13, 10
	s_add_i32 s51, s49, s51
	v_lshl_add_u32 v108, v232, 4, s51
	s_waitcnt lgkmcnt(0)
	v_add_f32_e32 v106, v106, v107
	ds_write_b32 v108, v106 offset:2304
.LBB0_1260:
	s_or_b64 exec, exec, s[52:53]
	v_mul_f32_e32 v106, v29, v29
	s_waitcnt lgkmcnt(0)
	v_mul_f32_e32 v107, v31, v31
	v_fmac_f32_e32 v106, v28, v28
	v_fmac_f32_e32 v107, v30, v30
	v_add_f32_e32 v106, v106, v107
	v_mul_f32_e32 v107, v25, v25
	v_mul_f32_e32 v108, v27, v27
	v_fmac_f32_e32 v107, v24, v24
	v_fmac_f32_e32 v108, v26, v26
	v_add_f32_e32 v107, v107, v108
	v_add_f32_e32 v106, v106, v107
	v_mul_f32_e32 v107, v21, v21
	v_mul_f32_e32 v108, v23, v23
	v_fmac_f32_e32 v107, v20, v20
	v_fmac_f32_e32 v108, v22, v22
	v_add_f32_e32 v107, v107, v108
	v_add_f32_e32 v106, v106, v107
	v_mul_f32_e32 v107, v17, v17
	v_mul_f32_e32 v108, v19, v19
	v_fmac_f32_e32 v107, v16, v16
	v_fmac_f32_e32 v108, v18, v18
	v_add_f32_e32 v107, v107, v108
	v_add_f32_e32 v106, v106, v107
	v_mov_b32_e32 v107, v106
	s_nop 1
	v_permlane16_swap_b32 v107, v106
	s_waitcnt lgkmcnt(0)
	v_add_f32_e32 v106, v106, v107
	v_mov_b32_e32 v107, v106
	s_nop 1
	v_permlane32_swap_b32 v107, v106
	s_and_saveexec_b64 s[52:53], s[10:11]
	s_cbranch_execz .LBB0_1262
	s_lshl_b32 s51, s13, 10
	s_add_i32 s51, s49, s51
	v_lshl_add_u32 v108, v232, 4, s51
	s_waitcnt lgkmcnt(0)
	v_add_f32_e32 v106, v106, v107
	ds_write_b32 v108, v106 offset:2560
.LBB0_1262:
	s_or_b64 exec, exec, s[52:53]
	v_mul_f32_e32 v106, v13, v13
	s_waitcnt lgkmcnt(0)
	v_mul_f32_e32 v107, v15, v15
	v_fmac_f32_e32 v106, v12, v12
	v_fmac_f32_e32 v107, v14, v14
	v_add_f32_e32 v106, v106, v107
	v_mul_f32_e32 v107, v9, v9
	v_mul_f32_e32 v108, v11, v11
	v_fmac_f32_e32 v107, v8, v8
	v_fmac_f32_e32 v108, v10, v10
	v_add_f32_e32 v107, v107, v108
	v_add_f32_e32 v106, v106, v107
	v_mul_f32_e32 v107, v5, v5
	v_mul_f32_e32 v108, v7, v7
	v_fmac_f32_e32 v107, v4, v4
	v_fmac_f32_e32 v108, v6, v6
	v_add_f32_e32 v107, v107, v108
	v_add_f32_e32 v106, v106, v107
	v_mul_f32_e32 v107, v1, v1
	v_mul_f32_e32 v108, v3, v3
	v_fmac_f32_e32 v107, v0, v0
	v_fmac_f32_e32 v108, v2, v2
	v_add_f32_e32 v107, v107, v108
	v_add_f32_e32 v106, v106, v107
	v_mov_b32_e32 v107, v106
	s_nop 1
	v_permlane16_swap_b32 v107, v106
	s_waitcnt lgkmcnt(0)
	v_add_f32_e32 v106, v106, v107
	v_mov_b32_e32 v107, v106
	s_nop 1
	v_permlane32_swap_b32 v107, v106
	s_and_saveexec_b64 s[52:53], s[10:11]
	s_cbranch_execz .LBB0_1264
	s_lshl_b32 s51, s13, 10
	s_add_i32 s51, s49, s51
	v_lshl_add_u32 v108, v232, 4, s51
	s_waitcnt lgkmcnt(0)
	v_add_f32_e32 v106, v106, v107
	ds_write_b32 v108, v106 offset:2816

.LBB0_1279:
	s_or_b64 exec, exec, s[52:53]
	v_add_u32_e32 v207, s85, v232
	s_waitcnt vmcnt(0) lgkmcnt(0)
	s_barrier
	v_lshl_add_u32 v206, v207, 2, v228
	ds_read_b32 v210, v206
	v_lshlrev_b32_e32 v212, 16, v172
	v_and_b32_e32 v213, 0xffff0000, v172
	v_lshlrev_b32_e32 v172, 16, v173
	v_and_b32_e32 v173, 0xffff0000, v173
	s_waitcnt lgkmcnt(0)
	v_pk_mul_f32 v[142:143], v[142:143], v[210:211] op_sel_hi:[1,0]
	v_pk_mul_f32 v[140:141], v[140:141], v[210:211] op_sel_hi:[1,0]
	v_lshlrev_b32_e32 v214, 16, v174
	v_and_b32_e32 v215, 0xffff0000, v174
	v_lshlrev_b32_e32 v174, 16, v175
	v_and_b32_e32 v175, 0xffff0000, v175
	v_pk_fma_f32 v[142:143], v[126:127], v[142:143], v[172:173]
	v_pk_fma_f32 v[140:141], v[124:125], v[140:141], v[212:213]
	v_pk_mul_f32 v[138:139], v[138:139], v[210:211] op_sel_hi:[1,0]
	v_pk_mul_f32 v[136:137], v[136:137], v[210:211] op_sel_hi:[1,0]
	v_pk_fma_f32 v[172:173], v[122:123], v[138:139], v[174:175]
	v_pk_fma_f32 v[138:139], v[120:121], v[136:137], v[214:215]
	v_mul_f32_e32 v136, v141, v141
	v_mul_f32_e32 v137, v143, v143
	v_fmac_f32_e32 v136, v140, v140
	v_fmac_f32_e32 v137, v142, v142
	v_add_f32_e32 v136, v136, v137
	v_mul_f32_e32 v137, v139, v139
	v_mul_f32_e32 v174, v173, v173
	v_fmac_f32_e32 v137, v138, v138
	v_fmac_f32_e32 v174, v172, v172
	v_add_f32_e32 v137, v137, v174
	v_add_f32_e32 v174, v136, v137
	v_cvt_pk_bf16_f32 v136, v140, v141
	v_cvt_pk_bf16_f32 v137, v142, v143
	v_lshlrev_b32_e32 v140, 16, v168
	v_and_b32_e32 v141, 0xffff0000, v168
	v_lshlrev_b32_e32 v142, 16, v169
	v_and_b32_e32 v143, 0xffff0000, v169
	v_pk_mul_f32 v[134:135], v[134:135], v[210:211] op_sel_hi:[1,0]
	v_pk_mul_f32 v[132:133], v[132:133], v[210:211] op_sel_hi:[1,0]
	v_lshlrev_b32_e32 v168, 16, v170
	v_and_b32_e32 v169, 0xffff0000, v170
	v_pk_fma_f32 v[134:135], v[110:111], v[134:135], v[142:143]
	v_pk_fma_f32 v[132:133], v[108:109], v[132:133], v[140:141]
	v_pk_mul_f32 v[128:129], v[128:129], v[210:211] op_sel_hi:[1,0]
	v_lshlrev_b32_e32 v170, 16, v171
	v_and_b32_e32 v171, 0xffff0000, v171
	v_pk_mul_f32 v[130:131], v[130:131], v[210:211] op_sel_hi:[1,0]
	v_pk_fma_f32 v[142:143], v[104:105], v[128:129], v[168:169]
	v_mul_f32_e32 v128, v133, v133
	v_mul_f32_e32 v129, v135, v135
	v_pk_fma_f32 v[140:141], v[106:107], v[130:131], v[170:171]
	v_fmac_f32_e32 v128, v132, v132
	v_fmac_f32_e32 v129, v134, v134
	v_add_f32_e32 v128, v128, v129
	v_mul_f32_e32 v129, v143, v143
	v_mul_f32_e32 v130, v141, v141
	v_fmac_f32_e32 v129, v142, v142
	v_fmac_f32_e32 v130, v140, v140
	v_add_f32_e32 v129, v129, v130
	v_add_f32_e32 v128, v128, v129
	v_add_f32_e32 v128, v174, v128
	v_mov_b32_e32 v129, v128
	s_nop 1
	v_permlane16_swap_b32 v129, v128
	v_add_u32_e32 v208, s51, v207
	v_ashrrev_i32_e32 v209, 31, v208
	v_lshlrev_b64 v[208:209], 11, v[208:209]
	v_lshl_add_u64 v[208:209], v[204:205], 0, v[208:209]
	s_waitcnt lgkmcnt(0)
	v_add_f32_e32 v128, v128, v129
	v_mov_b32_e32 v129, v128
	s_nop 1
	v_permlane32_swap_b32 v129, v128
	v_cvt_pk_bf16_f32 v138, v138, v139
	v_cvt_pk_bf16_f32 v139, v172, v173
	global_store_dwordx4 v[208:209], v[136:139], off
	v_cvt_pk_bf16_f32 v130, v132, v133
	v_cvt_pk_bf16_f32 v131, v134, v135
	v_cvt_pk_bf16_f32 v132, v142, v143
	v_cvt_pk_bf16_f32 v133, v140, v141
	global_store_dwordx4 v[208:209], v[130:133], off offset:256
	s_and_saveexec_b64 s[12:13], s[10:11]
	s_cbranch_execz .LBB0_1281
	s_waitcnt lgkmcnt(0)
	v_add_f32_e32 v128, v128, v129
	v_lshl_add_u32 v129, v207, 4, s49
	ds_write_b32 v129, v128
.LBB0_1281:
	s_or_b64 exec, exec, s[12:13]
	v_add_u32_e32 v252, 0xa0, v207
	v_add_u32_e32 v252, s51, v252
	v_ashrrev_i32_e32 v253, 31, v252
	v_lshlrev_b64 v[252:253], 11, v[252:253]
	v_lshl_add_u64 v[252:253], v[204:205], 0, v[252:253]
	global_load_dwordx4 v[168:171], v[252:253], off
	global_load_dwordx4 v[172:175], v[252:253], off offset:256
	v_add_u32_e32 v252, 0xb0, v207
	v_add_u32_e32 v252, s51, v252
	v_ashrrev_i32_e32 v253, 31, v252
	v_lshlrev_b64 v[252:253], 11, v[252:253]
	v_lshl_add_u64 v[252:253], v[204:205], 0, v[252:253]
	global_load_dwordx4 v[208:211], v[252:253], off
	global_load_dwordx4 v[212:215], v[252:253], off offset:256
	ds_read_b32 v132, v206 offset:64
	v_lshlrev_b32_e32 v134, 16, v164
	v_and_b32_e32 v135, 0xffff0000, v164
	v_lshlrev_b32_e32 v136, 16, v165
	v_and_b32_e32 v137, 0xffff0000, v165
	s_waitcnt lgkmcnt(0)
	v_pk_mul_f32 v[118:119], v[118:119], v[132:133] op_sel_hi:[1,0]
	v_pk_mul_f32 v[116:117], v[116:117], v[132:133] op_sel_hi:[1,0]
	v_lshlrev_b32_e32 v138, 16, v166
	v_and_b32_e32 v139, 0xffff0000, v166
	v_lshlrev_b32_e32 v140, 16, v167
	v_and_b32_e32 v141, 0xffff0000, v167
	v_pk_fma_f32 v[118:119], v[126:127], v[118:119], v[136:137]
	v_pk_fma_f32 v[116:117], v[124:125], v[116:117], v[134:135]
	v_pk_mul_f32 v[114:115], v[114:115], v[132:133] op_sel_hi:[1,0]
	v_pk_mul_f32 v[112:113], v[112:113], v[132:133] op_sel_hi:[1,0]
	v_pk_fma_f32 v[134:135], v[122:123], v[114:115], v[140:141]
	v_pk_fma_f32 v[114:115], v[120:121], v[112:113], v[138:139]
	v_mul_f32_e32 v112, v117, v117
	v_mul_f32_e32 v113, v119, v119
	v_fmac_f32_e32 v112, v116, v116
	v_fmac_f32_e32 v113, v118, v118
	v_add_f32_e32 v112, v112, v113
	v_mul_f32_e32 v113, v115, v115
	v_mul_f32_e32 v129, v135, v135
	v_fmac_f32_e32 v113, v114, v114
	v_fmac_f32_e32 v129, v134, v134
	v_add_f32_e32 v113, v113, v129
	v_add_f32_e32 v129, v112, v113
	v_cvt_pk_bf16_f32 v112, v116, v117
	v_cvt_pk_bf16_f32 v113, v118, v119
	v_lshlrev_b32_e32 v116, 16, v160
	v_and_b32_e32 v117, 0xffff0000, v160
	v_lshlrev_b32_e32 v118, 16, v161
	v_and_b32_e32 v119, 0xffff0000, v161
	v_pk_mul_f32 v[102:103], v[102:103], v[132:133] op_sel_hi:[1,0]
	v_pk_mul_f32 v[100:101], v[100:101], v[132:133] op_sel_hi:[1,0]
	v_lshlrev_b32_e32 v136, 16, v162
	v_and_b32_e32 v137, 0xffff0000, v162
	v_pk_fma_f32 v[102:103], v[110:111], v[102:103], v[118:119]
	v_pk_fma_f32 v[100:101], v[108:109], v[100:101], v[116:117]
	v_pk_mul_f32 v[96:97], v[96:97], v[132:133] op_sel_hi:[1,0]
	v_lshlrev_b32_e32 v138, 16, v163
	v_and_b32_e32 v139, 0xffff0000, v163
	v_pk_mul_f32 v[98:99], v[98:99], v[132:133] op_sel_hi:[1,0]
	v_pk_fma_f32 v[118:119], v[104:105], v[96:97], v[136:137]
	v_mul_f32_e32 v96, v101, v101
	v_mul_f32_e32 v97, v103, v103
	v_pk_fma_f32 v[116:117], v[106:107], v[98:99], v[138:139]
	v_fmac_f32_e32 v96, v100, v100
	v_fmac_f32_e32 v97, v102, v102
	v_add_f32_e32 v96, v96, v97
	v_mul_f32_e32 v97, v119, v119
	v_mul_f32_e32 v98, v117, v117
	v_fmac_f32_e32 v97, v118, v118
	v_fmac_f32_e32 v98, v116, v116
	v_add_f32_e32 v97, v97, v98
	v_add_f32_e32 v96, v96, v97
	v_add_f32_e32 v96, v129, v96
	v_mov_b32_e32 v97, v96
	s_nop 1
	v_permlane16_swap_b32 v97, v96
	v_add_u32_e32 v128, 16, v207
	v_add_u32_e32 v130, s51, v128
	v_ashrrev_i32_e32 v131, 31, v130
	v_lshlrev_b64 v[130:131], 11, v[130:131]
	s_waitcnt lgkmcnt(0)
	v_add_f32_e32 v96, v96, v97
	v_mov_b32_e32 v97, v96
	s_nop 1
	v_permlane32_swap_b32 v97, v96
	v_lshl_add_u64 v[130:131], v[204:205], 0, v[130:131]
	v_cvt_pk_bf16_f32 v114, v114, v115
	v_cvt_pk_bf16_f32 v115, v134, v135
	global_store_dwordx4 v[130:131], v[112:115], off
	v_cvt_pk_bf16_f32 v98, v100, v101
	v_cvt_pk_bf16_f32 v99, v102, v103
	v_cvt_pk_bf16_f32 v100, v118, v119
	v_cvt_pk_bf16_f32 v101, v116, v117
	global_store_dwordx4 v[130:131], v[98:101], off offset:256
	s_and_saveexec_b64 s[12:13], s[10:11]
	s_cbranch_execz .LBB0_1283
	s_waitcnt lgkmcnt(0)
	v_add_f32_e32 v96, v96, v97
	v_lshl_add_u32 v97, v128, 4, s49
	ds_write_b32 v97, v96
.LBB0_1283:
	s_or_b64 exec, exec, s[12:13]
	ds_read_b32 v100, v206 offset:128
	v_lshlrev_b32_e32 v102, 16, v156
	v_and_b32_e32 v103, 0xffff0000, v156
	v_lshlrev_b32_e32 v112, 16, v157
	v_and_b32_e32 v113, 0xffff0000, v157
	s_waitcnt lgkmcnt(0)
	v_pk_mul_f32 v[94:95], v[94:95], v[100:101] op_sel_hi:[1,0]
	v_pk_mul_f32 v[92:93], v[92:93], v[100:101] op_sel_hi:[1,0]
	v_lshlrev_b32_e32 v114, 16, v158
	v_and_b32_e32 v115, 0xffff0000, v158
	v_lshlrev_b32_e32 v116, 16, v159
	v_and_b32_e32 v117, 0xffff0000, v159
	v_pk_fma_f32 v[94:95], v[126:127], v[94:95], v[112:113]
	v_pk_fma_f32 v[92:93], v[124:125], v[92:93], v[102:103]
	v_pk_mul_f32 v[90:91], v[90:91], v[100:101] op_sel_hi:[1,0]
	v_pk_mul_f32 v[88:89], v[88:89], v[100:101] op_sel_hi:[1,0]
	v_pk_fma_f32 v[102:103], v[122:123], v[90:91], v[116:117]
	v_pk_fma_f32 v[90:91], v[120:121], v[88:89], v[114:115]
	v_mul_f32_e32 v88, v93, v93
	v_mul_f32_e32 v89, v95, v95
	v_fmac_f32_e32 v88, v92, v92
	v_fmac_f32_e32 v89, v94, v94
	v_add_f32_e32 v88, v88, v89
	v_mul_f32_e32 v89, v91, v91
	v_mul_f32_e32 v97, v103, v103
	v_fmac_f32_e32 v89, v90, v90
	v_fmac_f32_e32 v97, v102, v102
	v_add_f32_e32 v89, v89, v97
	v_add_f32_e32 v97, v88, v89
	v_cvt_pk_bf16_f32 v88, v92, v93
	v_cvt_pk_bf16_f32 v89, v94, v95
	v_lshlrev_b32_e32 v92, 16, v152
	v_and_b32_e32 v93, 0xffff0000, v152
	v_lshlrev_b32_e32 v94, 16, v153
	v_and_b32_e32 v95, 0xffff0000, v153
	v_pk_mul_f32 v[86:87], v[86:87], v[100:101] op_sel_hi:[1,0]
	v_pk_mul_f32 v[84:85], v[84:85], v[100:101] op_sel_hi:[1,0]
	v_lshlrev_b32_e32 v112, 16, v154
	v_and_b32_e32 v113, 0xffff0000, v154
	v_pk_fma_f32 v[86:87], v[110:111], v[86:87], v[94:95]
	v_pk_fma_f32 v[84:85], v[108:109], v[84:85], v[92:93]
	v_pk_mul_f32 v[80:81], v[80:81], v[100:101] op_sel_hi:[1,0]
	v_lshlrev_b32_e32 v114, 16, v155
	v_and_b32_e32 v115, 0xffff0000, v155
	v_pk_mul_f32 v[82:83], v[82:83], v[100:101] op_sel_hi:[1,0]
	v_pk_fma_f32 v[94:95], v[104:105], v[80:81], v[112:113]
	v_mul_f32_e32 v80, v85, v85
	v_mul_f32_e32 v81, v87, v87
	v_pk_fma_f32 v[92:93], v[106:107], v[82:83], v[114:115]
	v_fmac_f32_e32 v80, v84, v84
	v_fmac_f32_e32 v81, v86, v86
	v_add_f32_e32 v80, v80, v81
	v_mul_f32_e32 v81, v95, v95
	v_mul_f32_e32 v82, v93, v93
	v_fmac_f32_e32 v81, v94, v94
	v_fmac_f32_e32 v82, v92, v92
	v_add_f32_e32 v81, v81, v82
	v_add_f32_e32 v80, v80, v81
	v_add_f32_e32 v80, v97, v80
	v_mov_b32_e32 v81, v80
	s_nop 1
	v_permlane16_swap_b32 v81, v80
	v_add_u32_e32 v96, 32, v207
	v_add_u32_e32 v98, s51, v96
	v_ashrrev_i32_e32 v99, 31, v98
	v_lshlrev_b64 v[98:99], 11, v[98:99]
	s_waitcnt lgkmcnt(0)
	v_add_f32_e32 v80, v80, v81
	v_mov_b32_e32 v81, v80
	s_nop 1
	v_permlane32_swap_b32 v81, v80
	v_lshl_add_u64 v[98:99], v[204:205], 0, v[98:99]
	v_cvt_pk_bf16_f32 v90, v90, v91
	v_cvt_pk_bf16_f32 v91, v102, v103
	global_store_dwordx4 v[98:99], v[88:91], off
	v_cvt_pk_bf16_f32 v82, v84, v85
	v_cvt_pk_bf16_f32 v83, v86, v87
	v_cvt_pk_bf16_f32 v84, v94, v95
	v_cvt_pk_bf16_f32 v85, v92, v93
	global_store_dwordx4 v[98:99], v[82:85], off offset:256
	s_and_saveexec_b64 s[12:13], s[10:11]
	s_cbranch_execz .LBB0_1285
	s_waitcnt lgkmcnt(0)
	v_add_f32_e32 v80, v80, v81
	v_lshl_add_u32 v81, v96, 4, s49
	ds_write_b32 v81, v80
.LBB0_1285:
	s_or_b64 exec, exec, s[12:13]
	ds_read_b32 v84, v206 offset:192
	v_lshlrev_b32_e32 v86, 16, v148
	v_and_b32_e32 v87, 0xffff0000, v148
	v_lshlrev_b32_e32 v88, 16, v149
	v_and_b32_e32 v89, 0xffff0000, v149
	s_waitcnt lgkmcnt(0)
	v_pk_mul_f32 v[78:79], v[78:79], v[84:85] op_sel_hi:[1,0]
	v_pk_mul_f32 v[76:77], v[76:77], v[84:85] op_sel_hi:[1,0]
	v_lshlrev_b32_e32 v90, 16, v150
	v_and_b32_e32 v91, 0xffff0000, v150
	v_lshlrev_b32_e32 v92, 16, v151
	v_and_b32_e32 v93, 0xffff0000, v151
	v_pk_fma_f32 v[78:79], v[126:127], v[78:79], v[88:89]
	v_pk_fma_f32 v[76:77], v[124:125], v[76:77], v[86:87]
	v_pk_mul_f32 v[74:75], v[74:75], v[84:85] op_sel_hi:[1,0]
	v_pk_mul_f32 v[72:73], v[72:73], v[84:85] op_sel_hi:[1,0]
	v_pk_fma_f32 v[86:87], v[122:123], v[74:75], v[92:93]
	v_pk_fma_f32 v[74:75], v[120:121], v[72:73], v[90:91]
	v_mul_f32_e32 v72, v77, v77
	v_mul_f32_e32 v73, v79, v79
	v_fmac_f32_e32 v72, v76, v76
	v_fmac_f32_e32 v73, v78, v78
	v_add_f32_e32 v72, v72, v73
	v_mul_f32_e32 v73, v75, v75
	v_mul_f32_e32 v81, v87, v87
	v_fmac_f32_e32 v73, v74, v74
	v_fmac_f32_e32 v81, v86, v86
	v_add_f32_e32 v73, v73, v81
	v_add_f32_e32 v81, v72, v73
	v_cvt_pk_bf16_f32 v72, v76, v77
	v_cvt_pk_bf16_f32 v73, v78, v79
	v_lshlrev_b32_e32 v76, 16, v144
	v_and_b32_e32 v77, 0xffff0000, v144
	v_lshlrev_b32_e32 v78, 16, v145
	v_and_b32_e32 v79, 0xffff0000, v145
	v_pk_mul_f32 v[70:71], v[70:71], v[84:85] op_sel_hi:[1,0]
	v_pk_mul_f32 v[68:69], v[68:69], v[84:85] op_sel_hi:[1,0]
	v_lshlrev_b32_e32 v88, 16, v146
	v_and_b32_e32 v89, 0xffff0000, v146
	v_pk_fma_f32 v[70:71], v[110:111], v[70:71], v[78:79]
	v_pk_fma_f32 v[68:69], v[108:109], v[68:69], v[76:77]
	v_pk_mul_f32 v[64:65], v[64:65], v[84:85] op_sel_hi:[1,0]
	v_lshlrev_b32_e32 v90, 16, v147
	v_and_b32_e32 v91, 0xffff0000, v147
	v_pk_mul_f32 v[66:67], v[66:67], v[84:85] op_sel_hi:[1,0]
	v_pk_fma_f32 v[78:79], v[104:105], v[64:65], v[88:89]
	v_mul_f32_e32 v64, v69, v69
	v_mul_f32_e32 v65, v71, v71
	v_pk_fma_f32 v[76:77], v[106:107], v[66:67], v[90:91]
	v_fmac_f32_e32 v64, v68, v68
	v_fmac_f32_e32 v65, v70, v70
	v_add_f32_e32 v64, v64, v65
	v_mul_f32_e32 v65, v79, v79
	v_mul_f32_e32 v66, v77, v77
	v_fmac_f32_e32 v65, v78, v78
	v_fmac_f32_e32 v66, v76, v76
	v_add_f32_e32 v65, v65, v66
	v_add_f32_e32 v64, v64, v65
	v_add_f32_e32 v64, v81, v64
	v_mov_b32_e32 v65, v64
	s_nop 1
	v_permlane16_swap_b32 v65, v64
	v_add_u32_e32 v80, 48, v207
	v_add_u32_e32 v82, s51, v80
	v_ashrrev_i32_e32 v83, 31, v82
	v_lshlrev_b64 v[82:83], 11, v[82:83]
	s_waitcnt lgkmcnt(0)
	v_add_f32_e32 v64, v64, v65
	v_mov_b32_e32 v65, v64
	s_nop 1
	v_permlane32_swap_b32 v65, v64
	v_lshl_add_u64 v[82:83], v[204:205], 0, v[82:83]
	v_cvt_pk_bf16_f32 v74, v74, v75
	v_cvt_pk_bf16_f32 v75, v86, v87
	global_store_dwordx4 v[82:83], v[72:75], off
	v_cvt_pk_bf16_f32 v66, v68, v69
	v_cvt_pk_bf16_f32 v67, v70, v71
	v_cvt_pk_bf16_f32 v68, v78, v79
	v_cvt_pk_bf16_f32 v69, v76, v77
	global_store_dwordx4 v[82:83], v[66:69], off offset:256
	s_and_saveexec_b64 s[12:13], s[10:11]
	s_cbranch_execz .LBB0_1287
	s_waitcnt lgkmcnt(0)
	v_add_f32_e32 v64, v64, v65
	v_lshl_add_u32 v65, v80, 4, s49
	ds_write_b32 v65, v64
.LBB0_1287:
	s_or_b64 exec, exec, s[12:13]
	v_add_u32_e32 v64, 0x80, v207
	v_add_u32_e32 v66, s51, v64
	v_ashrrev_i32_e32 v67, 31, v66
	v_lshlrev_b64 v[66:67], 11, v[66:67]
	v_lshl_add_u64 v[70:71], v[204:205], 0, v[66:67]
	ds_read_b32 v72, v206 offset:512
	s_waitcnt lgkmcnt(0)
	v_pk_mul_f32 v[62:63], v[62:63], v[72:73] op_sel_hi:[1,0]
	v_pk_mul_f32 v[60:61], v[60:61], v[72:73] op_sel_hi:[1,0]
	v_pk_mul_f32 v[58:59], v[58:59], v[72:73] op_sel_hi:[1,0]
	v_pk_mul_f32 v[56:57], v[56:57], v[72:73] op_sel_hi:[1,0]
	v_pk_mul_f32 v[54:55], v[54:55], v[72:73] op_sel_hi:[1,0]
	v_pk_mul_f32 v[52:53], v[52:53], v[72:73] op_sel_hi:[1,0]
	v_pk_mul_f32 v[50:51], v[50:51], v[72:73] op_sel_hi:[1,0]
	v_pk_mul_f32 v[48:49], v[48:49], v[72:73] op_sel_hi:[1,0]
	v_lshlrev_b32_e32 v74, 16, v236
	v_and_b32_e32 v75, 0xffff0000, v236
	v_lshlrev_b32_e32 v66, 16, v237
	v_and_b32_e32 v67, 0xffff0000, v237
	v_lshlrev_b32_e32 v76, 16, v238
	v_and_b32_e32 v77, 0xffff0000, v238
	v_lshlrev_b32_e32 v68, 16, v239
	v_and_b32_e32 v69, 0xffff0000, v239
	v_pk_fma_f32 v[66:67], v[126:127], v[62:63], v[66:67]
	v_pk_fma_f32 v[74:75], v[124:125], v[60:61], v[74:75]
	v_pk_fma_f32 v[68:69], v[122:123], v[58:59], v[68:69]
	v_pk_fma_f32 v[76:77], v[120:121], v[56:57], v[76:77]
	v_cvt_pk_bf16_f32 v56, v74, v75
	v_cvt_pk_bf16_f32 v57, v66, v67
	v_mul_f32_e32 v65, v75, v75
	v_cvt_pk_bf16_f32 v58, v76, v77
	v_cvt_pk_bf16_f32 v59, v68, v69
	v_mul_f32_e32 v67, v67, v67
	v_mul_f32_e32 v72, v77, v77
	v_mul_f32_e32 v69, v69, v69
	v_fmac_f32_e32 v65, v74, v74
	v_fmac_f32_e32 v67, v66, v66
	v_fmac_f32_e32 v72, v76, v76
	v_fmac_f32_e32 v69, v68, v68
	v_add_f32_e32 v65, v65, v67
	v_add_f32_e32 v66, v72, v69
	v_add_f32_e32 v65, v65, v66
	global_store_dwordx4 v[70:71], v[56:59], off
	v_lshlrev_b32_e32 v66, 16, v240
	v_and_b32_e32 v67, 0xffff0000, v240
	v_lshlrev_b32_e32 v60, 16, v241
	v_and_b32_e32 v61, 0xffff0000, v241
	v_lshlrev_b32_e32 v68, 16, v242
	v_and_b32_e32 v69, 0xffff0000, v242
	v_lshlrev_b32_e32 v62, 16, v243
	v_and_b32_e32 v63, 0xffff0000, v243
	v_pk_fma_f32 v[54:55], v[110:111], v[54:55], v[60:61]
	v_pk_fma_f32 v[52:53], v[108:109], v[52:53], v[66:67]
	v_pk_fma_f32 v[60:61], v[106:107], v[50:51], v[62:63]
	v_pk_fma_f32 v[62:63], v[104:105], v[48:49], v[68:69]
	v_mul_f32_e32 v48, v53, v53
	v_mul_f32_e32 v49, v55, v55
	v_mul_f32_e32 v50, v63, v63
	v_mul_f32_e32 v51, v61, v61
	v_fmac_f32_e32 v48, v52, v52
	v_fmac_f32_e32 v49, v54, v54
	v_fmac_f32_e32 v50, v62, v62
	v_fmac_f32_e32 v51, v60, v60
	v_add_f32_e32 v48, v48, v49
	v_add_f32_e32 v49, v50, v51
	v_add_f32_e32 v48, v48, v49
	v_add_f32_e32 v48, v65, v48
	v_mov_b32_e32 v49, v48
	s_nop 1
	v_permlane16_swap_b32 v49, v48
	v_cvt_pk_bf16_f32 v50, v52, v53
	v_cvt_pk_bf16_f32 v51, v54, v55
	v_cvt_pk_bf16_f32 v52, v62, v63
	v_cvt_pk_bf16_f32 v53, v60, v61
	s_waitcnt lgkmcnt(0)
	v_add_f32_e32 v48, v48, v49
	v_mov_b32_e32 v49, v48
	s_nop 1
	v_permlane32_swap_b32 v49, v48
	global_store_dwordx4 v[70:71], v[50:53], off offset:256
	s_and_saveexec_b64 s[12:13], s[10:11]
	s_cbranch_execz .LBB0_1289
	s_waitcnt lgkmcnt(0)
	v_add_f32_e32 v48, v48, v49
	v_lshl_add_u32 v49, v64, 4, s49
	ds_write_b32 v49, v48
.LBB0_1289:
	s_or_b64 exec, exec, s[12:13]
	v_add_u32_e32 v48, 0x90, v207
	v_add_u32_e32 v50, s51, v48
	v_ashrrev_i32_e32 v51, 31, v50
	v_lshlrev_b64 v[50:51], 11, v[50:51]
	v_lshl_add_u64 v[54:55], v[204:205], 0, v[50:51]
	ds_read_b32 v56, v206 offset:576
	s_waitcnt lgkmcnt(0)
	v_pk_mul_f32 v[46:47], v[46:47], v[56:57] op_sel_hi:[1,0]
	v_pk_mul_f32 v[44:45], v[44:45], v[56:57] op_sel_hi:[1,0]
	v_pk_mul_f32 v[42:43], v[42:43], v[56:57] op_sel_hi:[1,0]
	v_pk_mul_f32 v[40:41], v[40:41], v[56:57] op_sel_hi:[1,0]
	v_pk_mul_f32 v[38:39], v[38:39], v[56:57] op_sel_hi:[1,0]
	v_pk_mul_f32 v[36:37], v[36:37], v[56:57] op_sel_hi:[1,0]
	v_pk_mul_f32 v[34:35], v[34:35], v[56:57] op_sel_hi:[1,0]
	v_pk_mul_f32 v[32:33], v[32:33], v[56:57] op_sel_hi:[1,0]
	v_lshlrev_b32_e32 v58, 16, v244
	v_and_b32_e32 v59, 0xffff0000, v244
	v_lshlrev_b32_e32 v50, 16, v245
	v_and_b32_e32 v51, 0xffff0000, v245
	v_lshlrev_b32_e32 v60, 16, v246
	v_and_b32_e32 v61, 0xffff0000, v246
	v_lshlrev_b32_e32 v52, 16, v247
	v_and_b32_e32 v53, 0xffff0000, v247
	v_pk_fma_f32 v[50:51], v[126:127], v[46:47], v[50:51]
	v_pk_fma_f32 v[58:59], v[124:125], v[44:45], v[58:59]
	v_pk_fma_f32 v[52:53], v[122:123], v[42:43], v[52:53]
	v_pk_fma_f32 v[60:61], v[120:121], v[40:41], v[60:61]
	v_cvt_pk_bf16_f32 v40, v58, v59
	v_cvt_pk_bf16_f32 v41, v50, v51
	v_mul_f32_e32 v49, v59, v59
	v_cvt_pk_bf16_f32 v42, v60, v61
	v_cvt_pk_bf16_f32 v43, v52, v53
	v_mul_f32_e32 v51, v51, v51
	v_mul_f32_e32 v56, v61, v61
	v_mul_f32_e32 v53, v53, v53
	v_fmac_f32_e32 v49, v58, v58
	v_fmac_f32_e32 v51, v50, v50
	v_fmac_f32_e32 v56, v60, v60
	v_fmac_f32_e32 v53, v52, v52
	v_add_f32_e32 v49, v49, v51
	v_add_f32_e32 v50, v56, v53
	v_add_f32_e32 v49, v49, v50
	global_store_dwordx4 v[54:55], v[40:43], off
	v_lshlrev_b32_e32 v50, 16, v248
	v_and_b32_e32 v51, 0xffff0000, v248
	v_lshlrev_b32_e32 v44, 16, v249
	v_and_b32_e32 v45, 0xffff0000, v249
	v_lshlrev_b32_e32 v52, 16, v250
	v_and_b32_e32 v53, 0xffff0000, v250
	v_lshlrev_b32_e32 v46, 16, v251
	v_and_b32_e32 v47, 0xffff0000, v251
	v_pk_fma_f32 v[38:39], v[110:111], v[38:39], v[44:45]
	v_pk_fma_f32 v[36:37], v[108:109], v[36:37], v[50:51]
	v_pk_fma_f32 v[44:45], v[106:107], v[34:35], v[46:47]
	v_pk_fma_f32 v[46:47], v[104:105], v[32:33], v[52:53]
	v_mul_f32_e32 v32, v37, v37
	v_mul_f32_e32 v33, v39, v39
	v_mul_f32_e32 v34, v47, v47
	v_mul_f32_e32 v35, v45, v45
	v_fmac_f32_e32 v32, v36, v36
	v_fmac_f32_e32 v33, v38, v38
	v_fmac_f32_e32 v34, v46, v46
	v_fmac_f32_e32 v35, v44, v44
	v_add_f32_e32 v32, v32, v33
	v_add_f32_e32 v33, v34, v35
	v_add_f32_e32 v32, v32, v33
	v_add_f32_e32 v32, v49, v32
	v_mov_b32_e32 v33, v32
	s_nop 1
	v_permlane16_swap_b32 v33, v32
	v_cvt_pk_bf16_f32 v34, v36, v37
	v_cvt_pk_bf16_f32 v35, v38, v39
	v_cvt_pk_bf16_f32 v36, v46, v47
	v_cvt_pk_bf16_f32 v37, v44, v45
	s_waitcnt lgkmcnt(0)
	v_add_f32_e32 v32, v32, v33
	v_mov_b32_e32 v33, v32
	s_nop 1
	v_permlane32_swap_b32 v33, v32
	global_store_dwordx4 v[54:55], v[34:37], off offset:256
	s_and_saveexec_b64 s[12:13], s[10:11]
	s_cbranch_execz .LBB0_1291
	s_waitcnt lgkmcnt(0)
	v_add_f32_e32 v32, v32, v33
	v_lshl_add_u32 v33, v48, 4, s49
	ds_write_b32 v33, v32
.LBB0_1291:
	s_or_b64 exec, exec, s[12:13]
	v_add_u32_e32 v32, 0xa0, v207
	v_add_u32_e32 v34, s51, v32
	v_ashrrev_i32_e32 v35, 31, v34
	v_lshlrev_b64 v[34:35], 11, v[34:35]
	v_lshl_add_u64 v[38:39], v[204:205], 0, v[34:35]
	ds_read_b32 v40, v206 offset:640
	s_waitcnt lgkmcnt(0)
	v_pk_mul_f32 v[30:31], v[30:31], v[40:41] op_sel_hi:[1,0]
	v_pk_mul_f32 v[28:29], v[28:29], v[40:41] op_sel_hi:[1,0]
	v_pk_mul_f32 v[26:27], v[26:27], v[40:41] op_sel_hi:[1,0]
	v_pk_mul_f32 v[24:25], v[24:25], v[40:41] op_sel_hi:[1,0]
	v_pk_mul_f32 v[22:23], v[22:23], v[40:41] op_sel_hi:[1,0]
	v_pk_mul_f32 v[20:21], v[20:21], v[40:41] op_sel_hi:[1,0]
	v_pk_mul_f32 v[18:19], v[18:19], v[40:41] op_sel_hi:[1,0]
	v_pk_mul_f32 v[16:17], v[16:17], v[40:41] op_sel_hi:[1,0]
	s_waitcnt vmcnt(13)
	v_lshlrev_b32_e32 v42, 16, v168
	v_and_b32_e32 v43, 0xffff0000, v168
	v_lshlrev_b32_e32 v34, 16, v169
	v_and_b32_e32 v35, 0xffff0000, v169
	v_lshlrev_b32_e32 v44, 16, v170
	v_and_b32_e32 v45, 0xffff0000, v170
	v_lshlrev_b32_e32 v36, 16, v171
	v_and_b32_e32 v37, 0xffff0000, v171
	v_pk_fma_f32 v[34:35], v[126:127], v[30:31], v[34:35]
	v_pk_fma_f32 v[42:43], v[124:125], v[28:29], v[42:43]
	v_pk_fma_f32 v[36:37], v[122:123], v[26:27], v[36:37]
	v_pk_fma_f32 v[44:45], v[120:121], v[24:25], v[44:45]
	v_cvt_pk_bf16_f32 v24, v42, v43
	v_cvt_pk_bf16_f32 v25, v34, v35
	v_mul_f32_e32 v33, v43, v43
	v_cvt_pk_bf16_f32 v26, v44, v45
	v_cvt_pk_bf16_f32 v27, v36, v37
	v_mul_f32_e32 v35, v35, v35
	v_mul_f32_e32 v40, v45, v45
	v_mul_f32_e32 v37, v37, v37
	v_fmac_f32_e32 v33, v42, v42
	v_fmac_f32_e32 v35, v34, v34
	v_fmac_f32_e32 v40, v44, v44
	v_fmac_f32_e32 v37, v36, v36
	v_add_f32_e32 v33, v33, v35
	v_add_f32_e32 v34, v40, v37
	v_add_f32_e32 v33, v33, v34
	global_store_dwordx4 v[38:39], v[24:27], off
	s_waitcnt vmcnt(13)
	v_lshlrev_b32_e32 v34, 16, v172
	v_and_b32_e32 v35, 0xffff0000, v172
	v_lshlrev_b32_e32 v28, 16, v173
	v_and_b32_e32 v29, 0xffff0000, v173
	v_lshlrev_b32_e32 v36, 16, v174
	v_and_b32_e32 v37, 0xffff0000, v174
	v_lshlrev_b32_e32 v30, 16, v175
	v_and_b32_e32 v31, 0xffff0000, v175
	v_pk_fma_f32 v[22:23], v[110:111], v[22:23], v[28:29]
	v_pk_fma_f32 v[20:21], v[108:109], v[20:21], v[34:35]
	v_pk_fma_f32 v[28:29], v[106:107], v[18:19], v[30:31]
	v_pk_fma_f32 v[30:31], v[104:105], v[16:17], v[36:37]
	v_mul_f32_e32 v16, v21, v21
	v_mul_f32_e32 v17, v23, v23
	v_mul_f32_e32 v18, v31, v31
	v_mul_f32_e32 v19, v29, v29
	v_fmac_f32_e32 v16, v20, v20
	v_fmac_f32_e32 v17, v22, v22
	v_fmac_f32_e32 v18, v30, v30
	v_fmac_f32_e32 v19, v28, v28
	v_add_f32_e32 v16, v16, v17
	v_add_f32_e32 v17, v18, v19
	v_add_f32_e32 v16, v16, v17
	v_add_f32_e32 v16, v33, v16
	v_mov_b32_e32 v17, v16
	s_nop 1
	v_permlane16_swap_b32 v17, v16
	v_cvt_pk_bf16_f32 v18, v20, v21
	v_cvt_pk_bf16_f32 v19, v22, v23
	v_cvt_pk_bf16_f32 v20, v30, v31
	v_cvt_pk_bf16_f32 v21, v28, v29
	s_waitcnt lgkmcnt(0)
	v_add_f32_e32 v16, v16, v17
	v_mov_b32_e32 v17, v16
	s_nop 1
	v_permlane32_swap_b32 v17, v16
	global_store_dwordx4 v[38:39], v[18:21], off offset:256
	s_and_saveexec_b64 s[12:13], s[10:11]
	s_cbranch_execz .LBB0_1293
	s_waitcnt lgkmcnt(0)
	v_add_f32_e32 v16, v16, v17
	v_lshl_add_u32 v17, v32, 4, s49
	ds_write_b32 v17, v16
.LBB0_1293:
	s_or_b64 exec, exec, s[12:13]
	v_add_u32_e32 v16, 0xb0, v207
	v_add_u32_e32 v18, s51, v16
	v_ashrrev_i32_e32 v19, 31, v18
	v_lshlrev_b64 v[18:19], 11, v[18:19]
	v_lshl_add_u64 v[22:23], v[204:205], 0, v[18:19]
	ds_read_b32 v24, v206 offset:704
	s_waitcnt lgkmcnt(0)
	v_pk_mul_f32 v[14:15], v[14:15], v[24:25] op_sel_hi:[1,0]
	v_pk_mul_f32 v[12:13], v[12:13], v[24:25] op_sel_hi:[1,0]
	v_pk_mul_f32 v[10:11], v[10:11], v[24:25] op_sel_hi:[1,0]
	v_pk_mul_f32 v[8:9], v[8:9], v[24:25] op_sel_hi:[1,0]
	v_pk_mul_f32 v[6:7], v[6:7], v[24:25] op_sel_hi:[1,0]
	v_pk_mul_f32 v[4:5], v[4:5], v[24:25] op_sel_hi:[1,0]
	v_pk_mul_f32 v[2:3], v[2:3], v[24:25] op_sel_hi:[1,0]
	v_pk_mul_f32 v[0:1], v[0:1], v[24:25] op_sel_hi:[1,0]
	s_waitcnt vmcnt(13)
	v_lshlrev_b32_e32 v26, 16, v208
	v_and_b32_e32 v27, 0xffff0000, v208
	v_lshlrev_b32_e32 v18, 16, v209
	v_and_b32_e32 v19, 0xffff0000, v209
	v_lshlrev_b32_e32 v28, 16, v210
	v_and_b32_e32 v29, 0xffff0000, v210
	v_lshlrev_b32_e32 v20, 16, v211
	v_and_b32_e32 v21, 0xffff0000, v211
	v_pk_fma_f32 v[18:19], v[126:127], v[14:15], v[18:19]
	v_pk_fma_f32 v[26:27], v[124:125], v[12:13], v[26:27]
	v_pk_fma_f32 v[20:21], v[122:123], v[10:11], v[20:21]
	v_pk_fma_f32 v[28:29], v[120:121], v[8:9], v[28:29]
	v_cvt_pk_bf16_f32 v8, v26, v27
	v_cvt_pk_bf16_f32 v9, v18, v19
	v_mul_f32_e32 v17, v27, v27
	v_cvt_pk_bf16_f32 v10, v28, v29
	v_cvt_pk_bf16_f32 v11, v20, v21
	v_mul_f32_e32 v19, v19, v19
	v_mul_f32_e32 v24, v29, v29
	v_mul_f32_e32 v21, v21, v21
	v_fmac_f32_e32 v17, v26, v26
	v_fmac_f32_e32 v19, v18, v18
	v_fmac_f32_e32 v24, v28, v28
	v_fmac_f32_e32 v21, v20, v20
	v_add_f32_e32 v17, v17, v19
	v_add_f32_e32 v18, v24, v21
	v_add_f32_e32 v17, v17, v18
	global_store_dwordx4 v[22:23], v[8:11], off
	s_waitcnt vmcnt(13)
	v_lshlrev_b32_e32 v18, 16, v212
	v_and_b32_e32 v19, 0xffff0000, v212
	v_lshlrev_b32_e32 v12, 16, v213
	v_and_b32_e32 v13, 0xffff0000, v213
	v_lshlrev_b32_e32 v20, 16, v214
	v_and_b32_e32 v21, 0xffff0000, v214
	v_lshlrev_b32_e32 v14, 16, v215
	v_and_b32_e32 v15, 0xffff0000, v215
	v_pk_fma_f32 v[6:7], v[110:111], v[6:7], v[12:13]
	v_pk_fma_f32 v[4:5], v[108:109], v[4:5], v[18:19]
	v_pk_fma_f32 v[12:13], v[106:107], v[2:3], v[14:15]
	v_pk_fma_f32 v[14:15], v[104:105], v[0:1], v[20:21]
	v_mul_f32_e32 v0, v5, v5
	v_mul_f32_e32 v1, v7, v7
	v_mul_f32_e32 v2, v15, v15
	v_mul_f32_e32 v3, v13, v13
	v_fmac_f32_e32 v0, v4, v4
	v_fmac_f32_e32 v1, v6, v6
	v_fmac_f32_e32 v2, v14, v14
	v_fmac_f32_e32 v3, v12, v12
	v_add_f32_e32 v0, v0, v1
	v_add_f32_e32 v1, v2, v3
	v_add_f32_e32 v0, v0, v1
	v_add_f32_e32 v0, v17, v0
	v_mov_b32_e32 v1, v0
	s_nop 1
	v_permlane16_swap_b32 v1, v0
	v_cvt_pk_bf16_f32 v2, v4, v5
	v_cvt_pk_bf16_f32 v3, v6, v7
	v_cvt_pk_bf16_f32 v4, v14, v15
	v_cvt_pk_bf16_f32 v5, v12, v13
	s_waitcnt lgkmcnt(0)
	v_add_f32_e32 v0, v0, v1
	v_mov_b32_e32 v1, v0
	s_nop 1
	v_permlane32_swap_b32 v1, v0
	global_store_dwordx4 v[22:23], v[2:5], off offset:256
	s_and_saveexec_b64 s[12:13], s[10:11]
	s_cbranch_execz .LBB0_1295
	s_waitcnt lgkmcnt(0)
	v_add_f32_e32 v0, v0, v1
	v_lshl_add_u32 v1, v16, 4, s49
	ds_write_b32 v1, v0

.LBB0_1433:
	s_mov_b32 s31, s51
	v_mov_b32_e32 v212, v223
	s_mov_b32 s30, s48
	v_mov_b32_e32 v233, v222
	s_mov_b64 s[4:5], s[0:1]
	v_mul_f32_e32 v130, v125, v125
	v_mov_b64_e32 v[128:129], s[4:5]
	flat_load_dwordx2 v[206:207], v[128:129] offset:216
	flat_load_dwordx4 v[142:145], v[128:129] offset:200
	v_mul_f32_e32 v131, v127, v127
	v_fmac_f32_e32 v130, v124, v124
	v_fmac_f32_e32 v131, v126, v126
	v_add_f32_e32 v130, v130, v131
	v_mul_f32_e32 v131, v121, v121
	v_mul_f32_e32 v132, v123, v123
	v_fmac_f32_e32 v131, v120, v120
	v_fmac_f32_e32 v132, v122, v122
	v_add_f32_e32 v131, v131, v132
	v_add_f32_e32 v130, v130, v131
	v_mul_f32_e32 v131, v117, v117
	v_mul_f32_e32 v132, v119, v119
	v_fmac_f32_e32 v131, v116, v116
	v_fmac_f32_e32 v132, v118, v118
	v_and_b32_e32 v129, 64, v229
	v_add_f32_e32 v131, v131, v132
	v_xor_b32_e32 v128, 16, v229
	v_add_u32_e32 v129, 64, v129
	v_add_f32_e32 v130, v130, v131
	v_mul_f32_e32 v131, v113, v113
	v_mul_f32_e32 v132, v115, v115
	v_cmp_lt_i32_e32 vcc, v128, v129
	v_fmac_f32_e32 v131, v112, v112
	v_fmac_f32_e32 v132, v114, v114
	v_cndmask_b32_e32 v128, v229, v128, vcc
	v_add_f32_e32 v131, v131, v132
	v_lshlrev_b32_e32 v128, 2, v128
	v_add_f32_e32 v130, v130, v131
	v_mov_b32_e32 v131, v130
	s_nop 1
	v_permlane16_swap_b32 v131, v130
	v_xor_b32_e32 v132, 32, v229
	v_cmp_lt_i32_e32 vcc, v132, v129
	s_lshl_b32 s34, s31, 2
	s_add_i32 s34, s34, 0x20400
	v_cndmask_b32_e32 v129, v229, v132, vcc
	v_lshlrev_b32_e32 v129, 2, v129
	s_waitcnt lgkmcnt(0)
	v_add_f32_e32 v130, v130, v131
	v_mov_b32_e32 v131, v130
	s_nop 1
	v_permlane32_swap_b32 v131, v130
	v_cmp_eq_u32_e32 vcc, 0, v212
	s_and_saveexec_b64 s[4:5], vcc
	s_cbranch_execz .LBB0_1435
	s_lshl_b32 s35, s30, 10
	s_add_i32 s35, s34, s35
	v_lshl_add_u32 v132, v233, 4, s35
	s_waitcnt lgkmcnt(0)
	v_add_f32_e32 v130, v130, v131
	ds_write_b32 v132, v130
.LBB0_1435:
	s_or_b64 exec, exec, s[4:5]
	v_mul_f32_e32 v130, v109, v109
	s_waitcnt lgkmcnt(0)
	v_mul_f32_e32 v131, v111, v111
	v_fmac_f32_e32 v130, v108, v108
	v_fmac_f32_e32 v131, v110, v110
	v_add_f32_e32 v130, v130, v131
	v_mul_f32_e32 v131, v105, v105
	v_mul_f32_e32 v132, v107, v107
	v_fmac_f32_e32 v131, v104, v104
	v_fmac_f32_e32 v132, v106, v106
	v_add_f32_e32 v131, v131, v132
	v_add_f32_e32 v130, v130, v131
	v_mul_f32_e32 v131, v101, v101
	v_mul_f32_e32 v132, v103, v103
	v_fmac_f32_e32 v131, v100, v100
	v_fmac_f32_e32 v132, v102, v102
	v_add_f32_e32 v131, v131, v132
	v_add_f32_e32 v130, v130, v131
	v_mul_f32_e32 v131, v97, v97
	v_mul_f32_e32 v132, v99, v99
	v_fmac_f32_e32 v131, v96, v96
	v_fmac_f32_e32 v132, v98, v98
	v_add_f32_e32 v131, v131, v132
	v_add_f32_e32 v130, v130, v131
	v_mov_b32_e32 v131, v130
	s_nop 1
	v_permlane16_swap_b32 v131, v130
	s_waitcnt lgkmcnt(0)
	v_add_f32_e32 v130, v130, v131
	v_mov_b32_e32 v131, v130
	s_nop 1
	v_permlane32_swap_b32 v131, v130
	s_and_saveexec_b64 s[4:5], vcc
	s_cbranch_execz .LBB0_1437
	s_lshl_b32 s35, s30, 10
	s_add_i32 s35, s34, s35
	v_lshl_add_u32 v132, v233, 4, s35
	s_waitcnt lgkmcnt(0)
	v_add_f32_e32 v130, v130, v131
	ds_write_b32 v132, v130 offset:256
.LBB0_1437:
	s_or_b64 exec, exec, s[4:5]
	v_mul_f32_e32 v130, v93, v93
	s_waitcnt lgkmcnt(0)
	v_mul_f32_e32 v131, v95, v95
	v_fmac_f32_e32 v130, v92, v92
	v_fmac_f32_e32 v131, v94, v94
	v_add_f32_e32 v130, v130, v131
	v_mul_f32_e32 v131, v89, v89
	v_mul_f32_e32 v132, v91, v91
	v_fmac_f32_e32 v131, v88, v88
	v_fmac_f32_e32 v132, v90, v90
	v_add_f32_e32 v131, v131, v132
	v_add_f32_e32 v130, v130, v131
	v_mul_f32_e32 v131, v85, v85
	v_mul_f32_e32 v132, v87, v87
	v_fmac_f32_e32 v131, v84, v84
	v_fmac_f32_e32 v132, v86, v86
	v_add_f32_e32 v131, v131, v132
	v_add_f32_e32 v130, v130, v131
	v_mul_f32_e32 v131, v81, v81
	v_mul_f32_e32 v132, v83, v83
	v_fmac_f32_e32 v131, v80, v80
	v_fmac_f32_e32 v132, v82, v82
	v_add_f32_e32 v131, v131, v132
	v_add_f32_e32 v130, v130, v131
	v_mov_b32_e32 v131, v130
	s_nop 1
	v_permlane16_swap_b32 v131, v130
	s_waitcnt lgkmcnt(0)
	v_add_f32_e32 v130, v130, v131
	v_mov_b32_e32 v131, v130
	s_nop 1
	v_permlane32_swap_b32 v131, v130
	s_and_saveexec_b64 s[4:5], vcc
	s_cbranch_execz .LBB0_1439
	s_lshl_b32 s35, s30, 10
	s_add_i32 s35, s34, s35
	v_lshl_add_u32 v132, v233, 4, s35
	s_waitcnt lgkmcnt(0)
	v_add_f32_e32 v130, v130, v131
	ds_write_b32 v132, v130 offset:512
.LBB0_1439:
	s_or_b64 exec, exec, s[4:5]
	v_mul_f32_e32 v130, v77, v77
	s_waitcnt lgkmcnt(0)
	v_mul_f32_e32 v131, v79, v79
	v_fmac_f32_e32 v130, v76, v76
	v_fmac_f32_e32 v131, v78, v78
	v_add_f32_e32 v130, v130, v131
	v_mul_f32_e32 v131, v73, v73
	v_mul_f32_e32 v132, v75, v75
	v_fmac_f32_e32 v131, v72, v72
	v_fmac_f32_e32 v132, v74, v74
	v_add_f32_e32 v131, v131, v132
	v_add_f32_e32 v130, v130, v131
	v_mul_f32_e32 v131, v69, v69
	v_mul_f32_e32 v132, v71, v71
	v_fmac_f32_e32 v131, v68, v68
	v_fmac_f32_e32 v132, v70, v70
	v_add_f32_e32 v131, v131, v132
	v_add_f32_e32 v130, v130, v131
	v_mul_f32_e32 v131, v65, v65
	v_mul_f32_e32 v132, v67, v67
	v_fmac_f32_e32 v131, v64, v64
	v_fmac_f32_e32 v132, v66, v66
	v_add_f32_e32 v131, v131, v132
	v_add_f32_e32 v130, v130, v131
	v_mov_b32_e32 v131, v130
	s_nop 1
	v_permlane16_swap_b32 v131, v130
	s_waitcnt lgkmcnt(0)
	v_add_f32_e32 v130, v130, v131
	v_mov_b32_e32 v131, v130
	s_nop 1
	v_permlane32_swap_b32 v131, v130
	s_and_saveexec_b64 s[4:5], vcc
	s_cbranch_execz .LBB0_1441
	s_lshl_b32 s35, s30, 10
	s_add_i32 s35, s34, s35
	v_lshl_add_u32 v132, v233, 4, s35
	s_waitcnt lgkmcnt(0)
	v_add_f32_e32 v130, v130, v131
	ds_write_b32 v132, v130 offset:768
.LBB0_1441:
	s_or_b64 exec, exec, s[4:5]
	v_mul_f32_e32 v130, v61, v61
	s_waitcnt lgkmcnt(0)
	v_mul_f32_e32 v131, v63, v63
	v_fmac_f32_e32 v130, v60, v60
	v_fmac_f32_e32 v131, v62, v62
	v_add_f32_e32 v130, v130, v131
	v_mul_f32_e32 v131, v57, v57
	v_mul_f32_e32 v132, v59, v59
	v_fmac_f32_e32 v131, v56, v56
	v_fmac_f32_e32 v132, v58, v58
	v_add_f32_e32 v131, v131, v132
	v_add_f32_e32 v130, v130, v131
	v_mul_f32_e32 v131, v53, v53
	v_mul_f32_e32 v132, v55, v55
	v_fmac_f32_e32 v131, v52, v52
	v_fmac_f32_e32 v132, v54, v54
	v_add_f32_e32 v131, v131, v132
	v_add_f32_e32 v130, v130, v131
	v_mul_f32_e32 v131, v49, v49
	v_mul_f32_e32 v132, v51, v51
	v_fmac_f32_e32 v131, v48, v48
	v_fmac_f32_e32 v132, v50, v50
	v_add_f32_e32 v131, v131, v132
	v_add_f32_e32 v130, v130, v131
	v_mov_b32_e32 v131, v130
	s_nop 1
	v_permlane16_swap_b32 v131, v130
	s_waitcnt lgkmcnt(0)
	v_add_f32_e32 v130, v130, v131
	v_mov_b32_e32 v131, v130
	s_nop 1
	v_permlane32_swap_b32 v131, v130
	s_and_saveexec_b64 s[4:5], vcc
	s_cbranch_execz .LBB0_1443
	s_lshl_b32 s35, s30, 10
	s_add_i32 s35, s34, s35
	v_lshl_add_u32 v132, v233, 4, s35
	s_waitcnt lgkmcnt(0)
	v_add_f32_e32 v130, v130, v131
	ds_write_b32 v132, v130 offset:2048
.LBB0_1443:
	s_or_b64 exec, exec, s[4:5]
	v_mul_f32_e32 v130, v45, v45
	s_waitcnt lgkmcnt(0)
	v_mul_f32_e32 v131, v47, v47
	v_fmac_f32_e32 v130, v44, v44
	v_fmac_f32_e32 v131, v46, v46
	v_add_f32_e32 v130, v130, v131
	v_mul_f32_e32 v131, v41, v41
	v_mul_f32_e32 v132, v43, v43
	v_fmac_f32_e32 v131, v40, v40
	v_fmac_f32_e32 v132, v42, v42
	v_add_f32_e32 v131, v131, v132
	v_add_f32_e32 v130, v130, v131
	v_mul_f32_e32 v131, v37, v37
	v_mul_f32_e32 v132, v39, v39
	v_fmac_f32_e32 v131, v36, v36
	v_fmac_f32_e32 v132, v38, v38
	v_add_f32_e32 v131, v131, v132
	v_add_f32_e32 v130, v130, v131
	v_mul_f32_e32 v131, v33, v33
	v_mul_f32_e32 v132, v35, v35
	v_fmac_f32_e32 v131, v32, v32
	v_fmac_f32_e32 v132, v34, v34
	v_add_f32_e32 v131, v131, v132
	v_add_f32_e32 v130, v130, v131
	v_mov_b32_e32 v131, v130
	s_nop 1
	v_permlane16_swap_b32 v131, v130
	s_waitcnt lgkmcnt(0)
	v_add_f32_e32 v130, v130, v131
	v_mov_b32_e32 v131, v130
	s_nop 1
	v_permlane32_swap_b32 v131, v130
	s_and_saveexec_b64 s[4:5], vcc
	s_cbranch_execz .LBB0_1445
	s_lshl_b32 s35, s30, 10
	s_add_i32 s35, s34, s35
	v_lshl_add_u32 v132, v233, 4, s35
	s_waitcnt lgkmcnt(0)
	v_add_f32_e32 v130, v130, v131
	ds_write_b32 v132, v130 offset:2304
.LBB0_1445:
	s_or_b64 exec, exec, s[4:5]
	v_mul_f32_e32 v130, v29, v29
	s_waitcnt lgkmcnt(0)
	v_mul_f32_e32 v131, v31, v31
	v_fmac_f32_e32 v130, v28, v28
	v_fmac_f32_e32 v131, v30, v30
	v_add_f32_e32 v130, v130, v131
	v_mul_f32_e32 v131, v25, v25
	v_mul_f32_e32 v132, v27, v27
	v_fmac_f32_e32 v131, v24, v24
	v_fmac_f32_e32 v132, v26, v26
	v_add_f32_e32 v131, v131, v132
	v_add_f32_e32 v130, v130, v131
	v_mul_f32_e32 v131, v21, v21
	v_mul_f32_e32 v132, v23, v23
	v_fmac_f32_e32 v131, v20, v20
	v_fmac_f32_e32 v132, v22, v22
	v_add_f32_e32 v131, v131, v132
	v_add_f32_e32 v130, v130, v131
	v_mul_f32_e32 v131, v17, v17
	v_mul_f32_e32 v132, v19, v19
	v_fmac_f32_e32 v131, v16, v16
	v_fmac_f32_e32 v132, v18, v18
	v_add_f32_e32 v131, v131, v132
	v_add_f32_e32 v130, v130, v131
	v_mov_b32_e32 v131, v130
	s_nop 1
	v_permlane16_swap_b32 v131, v130
	s_waitcnt lgkmcnt(0)
	v_add_f32_e32 v130, v130, v131
	v_mov_b32_e32 v131, v130
	s_nop 1
	v_permlane32_swap_b32 v131, v130
	s_and_saveexec_b64 s[4:5], vcc
	s_cbranch_execz .LBB0_1447
	s_lshl_b32 s35, s30, 10
	s_add_i32 s35, s34, s35
	v_lshl_add_u32 v132, v233, 4, s35
	s_waitcnt lgkmcnt(0)
	v_add_f32_e32 v130, v130, v131
	ds_write_b32 v132, v130 offset:2560
.LBB0_1447:
	s_or_b64 exec, exec, s[4:5]
	v_mul_f32_e32 v130, v13, v13
	s_waitcnt lgkmcnt(0)
	v_mul_f32_e32 v131, v15, v15
	v_fmac_f32_e32 v130, v12, v12
	v_fmac_f32_e32 v131, v14, v14
	v_add_f32_e32 v130, v130, v131
	v_mul_f32_e32 v131, v9, v9
	v_mul_f32_e32 v132, v11, v11
	v_fmac_f32_e32 v131, v8, v8
	v_fmac_f32_e32 v132, v10, v10
	v_add_f32_e32 v131, v131, v132
	v_add_f32_e32 v130, v130, v131
	v_mul_f32_e32 v131, v5, v5
	v_mul_f32_e32 v132, v7, v7
	v_fmac_f32_e32 v131, v4, v4
	v_fmac_f32_e32 v132, v6, v6
	v_add_f32_e32 v131, v131, v132
	v_add_f32_e32 v130, v130, v131
	v_mul_f32_e32 v131, v1, v1
	v_mul_f32_e32 v132, v3, v3
	v_fmac_f32_e32 v131, v0, v0
	v_fmac_f32_e32 v132, v2, v2
	v_add_f32_e32 v131, v131, v132
	v_add_f32_e32 v130, v130, v131
	v_mov_b32_e32 v128, v130
	s_nop 1
	v_permlane16_swap_b32 v128, v130
	s_waitcnt lgkmcnt(0)
	v_add_f32_e32 v128, v130, v128
	v_mov_b32_e32 v129, v128
	s_nop 1
	v_permlane32_swap_b32 v129, v128
	s_and_saveexec_b64 s[4:5], vcc
	s_cbranch_execz .LBB0_1449
	s_lshl_b32 s35, s30, 10
	s_add_i32 s34, s34, s35
	v_lshl_add_u32 v130, v233, 4, s34
	s_waitcnt lgkmcnt(0)
	v_add_f32_e32 v128, v128, v129
	ds_write_b32 v130, v128 offset:2816
